# 8-phase GEMM main loops: arrive at the cluster-end barrier 2 MFMAs early and issue the last 2 MFMAs (priority 2) behind it, hiding the barrier hand-over under matrix work
# speedup vs baseline: 1.0100x; 1.0100x over previous
.LBB0_114:
	ds_read_b128 v[152:155], v148
	ds_read_b128 v[156:159], v148 offset:1024
	ds_read_b128 v[160:163], v148 offset:2048
	ds_read_b128 v[164:167], v148 offset:3072
	s_add_u32 s38, s36, 0xfff80080
	s_addc_u32 s39, s37, -1
	s_cmp_eq_u32 s63, 28
	s_cselect_b32 s41, s4, s39
	s_cselect_b32 s40, s5, s38
	s_cselect_b32 s39, s23, s29
	s_cselect_b32 s38, s26, s27
	v_lshl_add_u64 v[188:189], s[36:37], 0, v[138:139]
	s_add_i32 m0, s19, 0xc000
	ds_read_b128 v[168:171], v149
	ds_read_b128 v[172:175], v149 offset:1024
	ds_read_b128 v[176:179], v149 offset:2048
	ds_read_b128 v[180:183], v149 offset:3072
	ds_read_b128 v[184:187], v149 offset:4096
	ds_read_b128 v[192:195], v149 offset:5120
	ds_read_b128 v[196:199], v149 offset:6144
	ds_read_b128 v[200:203], v149 offset:7168
	global_load_lds_dwordx4 v[188:189], off
	v_lshl_add_u64 v[188:189], s[36:37], 0, v[140:141]
	s_add_i32 m0, s19, 0xe000
	s_nop 0
	global_load_lds_dwordx4 v[188:189], off
	s_waitcnt lgkmcnt(8)
	s_barrier
	s_waitcnt lgkmcnt(0)
	s_setprio 1
	s_waitcnt lgkmcnt(0)
	v_mfma_f32_16x16x32_bf16 v[126:129], v[152:155], v[168:171], v[126:129]
	v_mfma_f32_16x16x32_bf16 v[122:125], v[160:163], v[168:171], v[122:125]
	v_mfma_f32_16x16x32_bf16 v[118:121], v[152:155], v[176:179], v[118:121]
	v_mfma_f32_16x16x32_bf16 v[114:117], v[160:163], v[176:179], v[114:117]
	v_mfma_f32_16x16x32_bf16 v[102:105], v[152:155], v[184:187], v[102:105]
	v_mfma_f32_16x16x32_bf16 v[98:101], v[160:163], v[184:187], v[98:101]
	v_mfma_f32_16x16x32_bf16 v[86:89], v[152:155], v[196:199], v[86:89]
	v_mfma_f32_16x16x32_bf16 v[82:85], v[160:163], v[196:199], v[82:85]
	v_mfma_f32_16x16x32_bf16 v[126:129], v[156:159], v[172:175], v[126:129]
	v_mfma_f32_16x16x32_bf16 v[122:125], v[164:167], v[172:175], v[122:125]
	v_mfma_f32_16x16x32_bf16 v[118:121], v[156:159], v[180:183], v[118:121]
	v_mfma_f32_16x16x32_bf16 v[114:117], v[164:167], v[180:183], v[114:117]
	v_mfma_f32_16x16x32_bf16 v[102:105], v[156:159], v[192:195], v[102:105]
	v_mfma_f32_16x16x32_bf16 v[98:101], v[164:167], v[192:195], v[98:101]
	s_setprio 2
	s_barrier
	v_mfma_f32_16x16x32_bf16 v[86:89], v[156:159], v[200:203], v[86:89]
	v_mfma_f32_16x16x32_bf16 v[82:85], v[164:167], v[200:203], v[82:85]
	s_setprio 0
	s_add_i32 s64, s57, s47
	v_lshl_add_u64 v[188:189], s[38:39], 0, v[132:133]
	s_mov_b32 m0, s64
	ds_read_b128 v[204:207], v150
	ds_read_b128 v[208:211], v150 offset:1024
	ds_read_b128 v[212:215], v150 offset:2048
	ds_read_b128 v[216:219], v150 offset:3072
	global_load_lds_dwordx4 v[188:189], off
	v_lshl_add_u64 v[220:221], s[38:39], 0, v[136:137]
	s_add_i32 m0, s64, 0x2000
	s_nop 0
	global_load_lds_dwordx4 v[220:221], off
	s_barrier
	s_waitcnt lgkmcnt(0)
	s_setprio 1
	s_waitcnt lgkmcnt(0)
	v_mfma_f32_16x16x32_bf16 v[110:113], v[204:207], v[168:171], v[110:113]
	v_mfma_f32_16x16x32_bf16 v[106:109], v[212:215], v[168:171], v[106:109]
	v_mfma_f32_16x16x32_bf16 v[94:97], v[204:207], v[176:179], v[94:97]
	v_mfma_f32_16x16x32_bf16 v[90:93], v[212:215], v[176:179], v[90:93]
	v_mfma_f32_16x16x32_bf16 v[78:81], v[204:207], v[184:187], v[78:81]
	v_mfma_f32_16x16x32_bf16 v[74:77], v[212:215], v[184:187], v[74:77]
	v_mfma_f32_16x16x32_bf16 v[70:73], v[204:207], v[196:199], v[70:73]
	v_mfma_f32_16x16x32_bf16 v[66:69], v[212:215], v[196:199], v[66:69]
	v_mfma_f32_16x16x32_bf16 v[110:113], v[208:211], v[172:175], v[110:113]
	v_mfma_f32_16x16x32_bf16 v[106:109], v[216:219], v[172:175], v[106:109]
	v_mfma_f32_16x16x32_bf16 v[94:97], v[208:211], v[180:183], v[94:97]
	v_mfma_f32_16x16x32_bf16 v[90:93], v[216:219], v[180:183], v[90:93]
	v_mfma_f32_16x16x32_bf16 v[78:81], v[208:211], v[192:195], v[78:81]
	v_mfma_f32_16x16x32_bf16 v[74:77], v[216:219], v[192:195], v[74:77]
	s_setprio 2
	s_mov_b32 m0, s19
	v_lshl_add_u64 v[222:223], s[40:41], 0, v[130:131]
	s_barrier
	v_mfma_f32_16x16x32_bf16 v[70:73], v[208:211], v[200:203], v[70:73]
	v_mfma_f32_16x16x32_bf16 v[66:69], v[216:219], v[200:203], v[66:69]
	s_setprio 0
	ds_read_b128 v[168:171], v149 offset:16384
	ds_read_b128 v[172:175], v149 offset:17408
	ds_read_b128 v[176:179], v149 offset:18432
	ds_read_b128 v[180:183], v149 offset:19456
	ds_read_b128 v[184:187], v149 offset:20480
	ds_read_b128 v[192:195], v149 offset:21504
	ds_read_b128 v[196:199], v149 offset:22528
	ds_read_b128 v[200:203], v149 offset:23552
	global_load_lds_dwordx4 v[222:223], off
	v_lshl_add_u64 v[224:225], s[40:41], 0, v[134:135]
	s_mov_b32 m0, s21
	s_nop 0
	global_load_lds_dwordx4 v[224:225], off
	s_barrier
	s_waitcnt lgkmcnt(0)
	s_setprio 1
	s_waitcnt lgkmcnt(0)
	v_mfma_f32_16x16x32_bf16 v[62:65], v[152:155], v[168:171], v[62:65]
	v_mfma_f32_16x16x32_bf16 v[58:61], v[160:163], v[168:171], v[58:61]
	v_mfma_f32_16x16x32_bf16 v[54:57], v[152:155], v[176:179], v[54:57]
	v_mfma_f32_16x16x32_bf16 v[50:53], v[160:163], v[176:179], v[50:53]
	v_mfma_f32_16x16x32_bf16 v[38:41], v[152:155], v[184:187], v[38:41]
	v_mfma_f32_16x16x32_bf16 v[34:37], v[160:163], v[184:187], v[34:37]
	v_mfma_f32_16x16x32_bf16 v[22:25], v[152:155], v[196:199], v[22:25]
	v_mfma_f32_16x16x32_bf16 v[18:21], v[160:163], v[196:199], v[18:21]
	v_mfma_f32_16x16x32_bf16 v[62:65], v[156:159], v[172:175], v[62:65]
	v_mfma_f32_16x16x32_bf16 v[58:61], v[164:167], v[172:175], v[58:61]
	v_mfma_f32_16x16x32_bf16 v[54:57], v[156:159], v[180:183], v[54:57]
	v_mfma_f32_16x16x32_bf16 v[50:53], v[164:167], v[180:183], v[50:53]
	v_mfma_f32_16x16x32_bf16 v[38:41], v[156:159], v[192:195], v[38:41]
	v_mfma_f32_16x16x32_bf16 v[34:37], v[164:167], v[192:195], v[34:37]
	s_setprio 2
	s_barrier
	v_mfma_f32_16x16x32_bf16 v[22:25], v[156:159], v[200:203], v[22:25]
	v_mfma_f32_16x16x32_bf16 v[18:21], v[164:167], v[200:203], v[18:21]
	s_setprio 0
	s_add_u32 s64, s38, 0x80000
	s_addc_u32 s65, s39, 0
	s_add_i32 s66, s58, s47
	v_lshl_add_u64 v[152:153], s[64:65], 0, v[132:133]
	s_mov_b32 m0, s66
	s_nop 0
	global_load_lds_dwordx4 v[152:153], off
	v_lshl_add_u64 v[152:153], s[64:65], 0, v[136:137]
	s_add_i32 m0, s66, 0x2000
	s_nop 0
	global_load_lds_dwordx4 v[152:153], off
	s_waitcnt vmcnt(6)
	s_barrier
	s_setprio 1
	v_mfma_f32_16x16x32_bf16 v[46:49], v[204:207], v[168:171], v[46:49]
	v_mfma_f32_16x16x32_bf16 v[42:45], v[212:215], v[168:171], v[42:45]
	v_mfma_f32_16x16x32_bf16 v[30:33], v[204:207], v[176:179], v[30:33]
	v_mfma_f32_16x16x32_bf16 v[26:29], v[212:215], v[176:179], v[26:29]
	v_mfma_f32_16x16x32_bf16 v[14:17], v[204:207], v[184:187], v[14:17]
	v_mfma_f32_16x16x32_bf16 v[10:13], v[212:215], v[184:187], v[10:13]
	v_mfma_f32_16x16x32_bf16 v[6:9], v[204:207], v[196:199], v[6:9]
	v_mfma_f32_16x16x32_bf16 v[2:5], v[212:215], v[196:199], v[2:5]
	v_mfma_f32_16x16x32_bf16 v[46:49], v[208:211], v[172:175], v[46:49]
	v_mfma_f32_16x16x32_bf16 v[42:45], v[216:219], v[172:175], v[42:45]
	v_mfma_f32_16x16x32_bf16 v[30:33], v[208:211], v[180:183], v[30:33]
	v_mfma_f32_16x16x32_bf16 v[26:29], v[216:219], v[180:183], v[26:29]
	v_mfma_f32_16x16x32_bf16 v[14:17], v[208:211], v[192:195], v[14:17]
	v_mfma_f32_16x16x32_bf16 v[10:13], v[216:219], v[192:195], v[10:13]
	s_setprio 2
	s_add_i32 s64, 0, 0x18000
	v_add_u32_e32 v151, s64, v146
	s_barrier
	v_mfma_f32_16x16x32_bf16 v[6:9], v[208:211], v[200:203], v[6:9]
	v_mfma_f32_16x16x32_bf16 v[2:5], v[216:219], v[200:203], v[2:5]
	s_setprio 0
	ds_read_b128 v[152:155], v151
	ds_read_b128 v[156:159], v151 offset:1024
	ds_read_b128 v[160:163], v151 offset:2048
	ds_read_b128 v[164:167], v151 offset:3072
	s_add_u32 s40, s40, 0x80000
	s_addc_u32 s41, s41, 0
	s_mov_b32 m0, s48
	v_lshl_add_u64 v[204:205], s[40:41], 0, v[130:131]
	ds_read_b128 v[168:171], v149 offset:32768
	ds_read_b128 v[172:175], v149 offset:33792
	ds_read_b128 v[176:179], v149 offset:34816
	ds_read_b128 v[180:183], v149 offset:35840
	ds_read_b128 v[184:187], v149 offset:36864
	ds_read_b128 v[192:195], v149 offset:37888
	ds_read_b128 v[196:199], v149 offset:38912
	ds_read_b128 v[200:203], v149 offset:39936
	global_load_lds_dwordx4 v[204:205], off
	v_lshl_add_u64 v[204:205], s[40:41], 0, v[134:135]
	s_mov_b32 m0, s49
	s_nop 0
	global_load_lds_dwordx4 v[204:205], off
	s_waitcnt lgkmcnt(8)
	s_barrier
	s_waitcnt lgkmcnt(0)
	s_setprio 1
	s_waitcnt lgkmcnt(0)
	v_mfma_f32_16x16x32_bf16 v[126:129], v[152:155], v[168:171], v[126:129]
	v_mfma_f32_16x16x32_bf16 v[122:125], v[160:163], v[168:171], v[122:125]
	v_mfma_f32_16x16x32_bf16 v[118:121], v[152:155], v[176:179], v[118:121]
	v_mfma_f32_16x16x32_bf16 v[114:117], v[160:163], v[176:179], v[114:117]
	v_mfma_f32_16x16x32_bf16 v[102:105], v[152:155], v[184:187], v[102:105]
	v_mfma_f32_16x16x32_bf16 v[98:101], v[160:163], v[184:187], v[98:101]
	v_mfma_f32_16x16x32_bf16 v[86:89], v[152:155], v[196:199], v[86:89]
	v_mfma_f32_16x16x32_bf16 v[82:85], v[160:163], v[196:199], v[82:85]
	v_mfma_f32_16x16x32_bf16 v[126:129], v[156:159], v[172:175], v[126:129]
	v_mfma_f32_16x16x32_bf16 v[122:125], v[164:167], v[172:175], v[122:125]
	v_mfma_f32_16x16x32_bf16 v[118:121], v[156:159], v[180:183], v[118:121]
	v_mfma_f32_16x16x32_bf16 v[114:117], v[164:167], v[180:183], v[114:117]
	v_mfma_f32_16x16x32_bf16 v[102:105], v[156:159], v[192:195], v[102:105]
	v_mfma_f32_16x16x32_bf16 v[98:101], v[164:167], v[192:195], v[98:101]
	s_setprio 2
	s_barrier
	v_mfma_f32_16x16x32_bf16 v[86:89], v[156:159], v[200:203], v[86:89]
	v_mfma_f32_16x16x32_bf16 v[82:85], v[164:167], v[200:203], v[82:85]
	s_setprio 0
	s_add_i32 s40, 0, 0x1c000
	s_add_i32 s41, s64, s47
	v_add_u32_e32 v151, s40, v146
	v_lshl_add_u64 v[188:189], v[188:189], 0, s[10:11]
	s_mov_b32 m0, s41
	ds_read_b128 v[204:207], v151
	ds_read_b128 v[208:211], v151 offset:1024
	ds_read_b128 v[212:215], v151 offset:2048
	ds_read_b128 v[216:219], v151 offset:3072
	global_load_lds_dwordx4 v[188:189], off
	v_lshl_add_u64 v[188:189], v[220:221], 0, s[10:11]
	s_add_i32 m0, s41, 0x2000
	s_nop 0
	global_load_lds_dwordx4 v[188:189], off
	s_barrier
	s_waitcnt lgkmcnt(0)
	s_setprio 1
	s_waitcnt lgkmcnt(0)
	v_mfma_f32_16x16x32_bf16 v[110:113], v[204:207], v[168:171], v[110:113]
	v_mfma_f32_16x16x32_bf16 v[106:109], v[212:215], v[168:171], v[106:109]
	v_mfma_f32_16x16x32_bf16 v[94:97], v[204:207], v[176:179], v[94:97]
	v_mfma_f32_16x16x32_bf16 v[90:93], v[212:215], v[176:179], v[90:93]
	v_mfma_f32_16x16x32_bf16 v[78:81], v[204:207], v[184:187], v[78:81]
	v_mfma_f32_16x16x32_bf16 v[74:77], v[212:215], v[184:187], v[74:77]
	v_mfma_f32_16x16x32_bf16 v[70:73], v[204:207], v[196:199], v[70:73]
	v_mfma_f32_16x16x32_bf16 v[66:69], v[212:215], v[196:199], v[66:69]
	v_mfma_f32_16x16x32_bf16 v[110:113], v[208:211], v[172:175], v[110:113]
	v_mfma_f32_16x16x32_bf16 v[106:109], v[216:219], v[172:175], v[106:109]
	v_mfma_f32_16x16x32_bf16 v[94:97], v[208:211], v[180:183], v[94:97]
	v_mfma_f32_16x16x32_bf16 v[90:93], v[216:219], v[180:183], v[90:93]
	v_mfma_f32_16x16x32_bf16 v[78:81], v[208:211], v[192:195], v[78:81]
	v_mfma_f32_16x16x32_bf16 v[74:77], v[216:219], v[192:195], v[74:77]
	s_setprio 2
	s_mov_b32 m0, s53
	v_lshl_add_u64 v[188:189], v[222:223], 0, s[10:11]
	s_barrier
	v_mfma_f32_16x16x32_bf16 v[70:73], v[208:211], v[200:203], v[70:73]
	v_mfma_f32_16x16x32_bf16 v[66:69], v[216:219], v[200:203], v[66:69]
	s_setprio 0
	ds_read_b128 v[168:171], v149 offset:49152
	ds_read_b128 v[172:175], v149 offset:50176
	ds_read_b128 v[176:179], v149 offset:51200
	ds_read_b128 v[180:183], v149 offset:52224
	ds_read_b128 v[184:187], v149 offset:53248
	ds_read_b128 v[192:195], v149 offset:54272
	ds_read_b128 v[196:199], v149 offset:55296
	ds_read_b128 v[200:203], v149 offset:56320
	global_load_lds_dwordx4 v[188:189], off
	v_lshl_add_u64 v[188:189], v[224:225], 0, s[10:11]
	s_mov_b32 m0, s54
	s_nop 0
	global_load_lds_dwordx4 v[188:189], off
	s_barrier
	s_waitcnt lgkmcnt(0)
	s_setprio 1
	s_waitcnt lgkmcnt(0)
	v_mfma_f32_16x16x32_bf16 v[62:65], v[152:155], v[168:171], v[62:65]
	v_mfma_f32_16x16x32_bf16 v[58:61], v[160:163], v[168:171], v[58:61]
	v_mfma_f32_16x16x32_bf16 v[54:57], v[152:155], v[176:179], v[54:57]
	v_mfma_f32_16x16x32_bf16 v[50:53], v[160:163], v[176:179], v[50:53]
	v_mfma_f32_16x16x32_bf16 v[38:41], v[152:155], v[184:187], v[38:41]
	v_mfma_f32_16x16x32_bf16 v[34:37], v[160:163], v[184:187], v[34:37]
	v_mfma_f32_16x16x32_bf16 v[22:25], v[152:155], v[196:199], v[22:25]
	v_mfma_f32_16x16x32_bf16 v[18:21], v[160:163], v[196:199], v[18:21]
	v_mfma_f32_16x16x32_bf16 v[62:65], v[156:159], v[172:175], v[62:65]
	v_mfma_f32_16x16x32_bf16 v[58:61], v[164:167], v[172:175], v[58:61]
	v_mfma_f32_16x16x32_bf16 v[54:57], v[156:159], v[180:183], v[54:57]
	v_mfma_f32_16x16x32_bf16 v[50:53], v[164:167], v[180:183], v[50:53]
	v_mfma_f32_16x16x32_bf16 v[38:41], v[156:159], v[192:195], v[38:41]
	v_mfma_f32_16x16x32_bf16 v[34:37], v[164:167], v[192:195], v[34:37]
	s_setprio 2
	s_barrier
	v_mfma_f32_16x16x32_bf16 v[22:25], v[156:159], v[200:203], v[22:25]
	v_mfma_f32_16x16x32_bf16 v[18:21], v[164:167], v[200:203], v[18:21]
	s_setprio 0
	s_add_u32 s38, s38, 0x80080
	s_addc_u32 s39, s39, 0
	s_add_i32 s40, s40, s47
	v_lshl_add_u64 v[152:153], s[38:39], 0, v[132:133]
	s_mov_b32 m0, s40
	s_nop 0
	global_load_lds_dwordx4 v[152:153], off
	v_lshl_add_u64 v[152:153], s[38:39], 0, v[136:137]
	s_add_i32 m0, s40, 0x2000
	s_nop 0
	global_load_lds_dwordx4 v[152:153], off
	s_waitcnt vmcnt(6)
	s_barrier
	s_setprio 1
	v_mfma_f32_16x16x32_bf16 v[46:49], v[204:207], v[168:171], v[46:49]
	v_mfma_f32_16x16x32_bf16 v[42:45], v[212:215], v[168:171], v[42:45]
	v_mfma_f32_16x16x32_bf16 v[30:33], v[204:207], v[176:179], v[30:33]
	v_mfma_f32_16x16x32_bf16 v[26:29], v[212:215], v[176:179], v[26:29]
	v_mfma_f32_16x16x32_bf16 v[14:17], v[204:207], v[184:187], v[14:17]
	v_mfma_f32_16x16x32_bf16 v[10:13], v[212:215], v[184:187], v[10:13]
	v_mfma_f32_16x16x32_bf16 v[6:9], v[204:207], v[196:199], v[6:9]
	v_mfma_f32_16x16x32_bf16 v[2:5], v[212:215], v[196:199], v[2:5]
	v_mfma_f32_16x16x32_bf16 v[46:49], v[208:211], v[172:175], v[46:49]
	v_mfma_f32_16x16x32_bf16 v[42:45], v[216:219], v[172:175], v[42:45]
	v_mfma_f32_16x16x32_bf16 v[30:33], v[208:211], v[180:183], v[30:33]
	v_mfma_f32_16x16x32_bf16 v[26:29], v[216:219], v[180:183], v[26:29]
	v_mfma_f32_16x16x32_bf16 v[14:17], v[208:211], v[192:195], v[14:17]
	v_mfma_f32_16x16x32_bf16 v[10:13], v[216:219], v[192:195], v[10:13]
	s_setprio 2
	s_add_i32 s63, s63, 2
	s_add_u32 s36, s36, 0x100
	s_addc_u32 s37, s37, 0
	s_add_u32 s27, s27, 0x100
	s_addc_u32 s29, s29, 0
	s_cmp_gt_u32 s63, 29
	s_barrier
	v_mfma_f32_16x16x32_bf16 v[6:9], v[208:211], v[200:203], v[6:9]
	v_mfma_f32_16x16x32_bf16 v[2:5], v[216:219], v[200:203], v[2:5]
	s_setprio 0
	s_cbranch_scc0 .LBB0_114
	s_ashr_i32 s4, s18, 31
	s_lshr_b32 s4, s4, 29
	s_add_i32 s4, s18, s4
	s_lshl_b32 s5, s20, 8
	s_ashr_i32 s4, s4, 3
	s_and_b32 s5, s5, 0x3f00
	v_add_u32_e32 v152, s5, v1
	s_lshl_b32 s5, s4, 11
	s_lshl_b32 s18, s18, 8
	s_sub_i32 s5, s18, s5
	v_or_b32_e32 v154, s5, v147
	s_ashr_i32 s5, s4, 31
	s_lshl_b64 s[4:5], s[4:5], 26
	s_add_u32 s4, s51, s4
	s_addc_u32 s5, s52, s5
	v_ashrrev_i32_e32 v155, 31, v154
	v_ashrrev_i32_e32 v153, 31, v152
	v_lshl_add_u64 v[154:155], v[154:155], 1, s[4:5]
	v_lshlrev_b64 v[156:157], 12, v[152:153]
	v_lshl_add_u64 v[156:157], v[154:155], 0, v[156:157]
	v_cvt_pk_bf16_f32 v62, v62, v63
	v_cvt_pk_bf16_f32 v63, v64, v65
	v_cvt_pk_bf16_f32 v64, v58, v59
	v_add_co_u32_e32 v58, vcc, s59, v156
	v_cvt_pk_bf16_f32 v70, v70, v71
	v_cvt_pk_bf16_f32 v71, v72, v73
	v_cvt_pk_bf16_f32 v72, v66, v67
	v_lshl_add_u64 v[66:67], v[156:157], 0, s[8:9]
	v_addc_co_u32_e32 v59, vcc, 0, v157, vcc
	v_cvt_pk_bf16_f32 v46, v46, v47
	v_cvt_pk_bf16_f32 v47, v48, v49
	v_cvt_pk_bf16_f32 v48, v42, v43
	v_cvt_pk_bf16_f32 v49, v44, v45
	global_store_dwordx4 v[66:67], v[46:49], off offset:256
	v_cvt_pk_bf16_f32 v110, v110, v111
	v_cvt_pk_bf16_f32 v111, v112, v113
	v_add_co_u32_e32 v48, vcc, s60, v156
	v_cvt_pk_bf16_f32 v112, v106, v107
	v_or_b32_e32 v106, 16, v152
	v_lshl_add_u64 v[46:47], v[156:157], 0, s[12:13]
	v_addc_co_u32_e32 v49, vcc, 0, v157, vcc
	v_cvt_pk_bf16_f32 v30, v30, v31
	v_cvt_pk_bf16_f32 v31, v32, v33
	v_cvt_pk_bf16_f32 v32, v26, v27
	v_cvt_pk_bf16_f32 v33, v28, v29
	v_ashrrev_i32_e32 v107, 31, v106
	v_cvt_pk_bf16_f32 v94, v94, v95
	v_cvt_pk_bf16_f32 v95, v96, v97
	v_cvt_pk_bf16_f32 v96, v90, v91
	v_or_b32_e32 v90, 32, v152
	global_store_dwordx4 v[46:47], v[30:33], off offset:256
	v_cvt_pk_bf16_f32 v113, v108, v109
	v_lshlrev_b64 v[106:107], 12, v[106:107]
	v_add_co_u32_e32 v32, vcc, s61, v156
	v_ashrrev_i32_e32 v91, 31, v90
	v_cvt_pk_bf16_f32 v78, v78, v79
	v_cvt_pk_bf16_f32 v79, v80, v81
	v_cvt_pk_bf16_f32 v80, v74, v75
	v_or_b32_e32 v74, 48, v152
	v_lshl_add_u64 v[30:31], v[156:157], 0, s[14:15]
	v_addc_co_u32_e32 v33, vcc, 0, v157, vcc
	v_cvt_pk_bf16_f32 v14, v14, v15
	v_cvt_pk_bf16_f32 v15, v16, v17
	v_cvt_pk_bf16_f32 v16, v10, v11
	v_cvt_pk_bf16_f32 v17, v12, v13
	global_store_dwordx4 v[156:157], v[110:113], off offset:256
	v_cvt_pk_bf16_f32 v97, v92, v93
	v_lshlrev_b64 v[90:91], 12, v[90:91]
	v_lshl_add_u64 v[110:111], v[154:155], 0, v[106:107]
	v_ashrrev_i32_e32 v75, 31, v74
	global_store_dwordx4 v[30:31], v[14:17], off offset:256
	global_store_dwordx4 v[110:111], v[94:97], off offset:256
	v_cvt_pk_bf16_f32 v81, v76, v77
	v_add_co_u32_e32 v16, vcc, s62, v156
	v_lshl_add_u64 v[94:95], v[154:155], 0, v[90:91]
	v_lshlrev_b64 v[74:75], 12, v[74:75]
	v_addc_co_u32_e32 v17, vcc, 0, v157, vcc
	v_cvt_pk_bf16_f32 v126, v126, v127
	v_cvt_pk_bf16_f32 v127, v128, v129
	v_cvt_pk_bf16_f32 v128, v122, v123
	v_cvt_pk_bf16_f32 v129, v124, v125
	v_cvt_pk_bf16_f32 v106, v118, v119
	v_cvt_pk_bf16_f32 v107, v120, v121
	v_cvt_pk_bf16_f32 v108, v114, v115
	v_cvt_pk_bf16_f32 v109, v116, v117
	v_cvt_pk_bf16_f32 v90, v102, v103
	v_cvt_pk_bf16_f32 v91, v104, v105
	v_cvt_pk_bf16_f32 v92, v98, v99
	v_cvt_pk_bf16_f32 v93, v100, v101
	global_store_dwordx4 v[94:95], v[78:81], off offset:256
	v_cvt_pk_bf16_f32 v76, v82, v83
	v_cvt_pk_bf16_f32 v77, v84, v85
	v_lshl_add_u64 v[78:79], v[154:155], 0, v[74:75]
	v_cvt_pk_bf16_f32 v74, v86, v87
	v_cvt_pk_bf16_f32 v75, v88, v89
	v_cvt_pk_bf16_f32 v73, v68, v69
	v_cvt_pk_bf16_f32 v65, v60, v61
	v_cvt_pk_bf16_f32 v42, v54, v55
	v_cvt_pk_bf16_f32 v43, v56, v57
	v_cvt_pk_bf16_f32 v44, v50, v51
	v_cvt_pk_bf16_f32 v45, v52, v53
	v_cvt_pk_bf16_f32 v26, v38, v39
	v_cvt_pk_bf16_f32 v27, v40, v41
	v_cvt_pk_bf16_f32 v28, v34, v35
	v_cvt_pk_bf16_f32 v29, v36, v37
	v_lshl_add_u64 v[14:15], v[156:157], 0, s[16:17]
	v_cvt_pk_bf16_f32 v10, v22, v23
	v_cvt_pk_bf16_f32 v11, v24, v25
	v_cvt_pk_bf16_f32 v12, v18, v19
	v_cvt_pk_bf16_f32 v13, v20, v21
	v_cvt_pk_bf16_f32 v6, v6, v7
	v_cvt_pk_bf16_f32 v7, v8, v9
	v_cvt_pk_bf16_f32 v8, v2, v3
	v_cvt_pk_bf16_f32 v9, v4, v5
	s_and_b64 vcc, exec, s[6:7]
	s_mov_b32 s18, s28
	s_mov_b32 s20, s22
	s_mov_b64 s[38:39], s[34:35]
	s_mov_b64 s[36:37], s[30:31]
	global_store_dwordx4 v[156:157], v[126:129], off
	global_store_dwordx4 v[110:111], v[106:109], off
	global_store_dwordx4 v[94:95], v[90:93], off
	global_store_dwordx4 v[78:79], v[74:77], off
	global_store_dwordx4 v[78:79], v[70:73], off offset:256
	global_store_dwordx4 v[58:59], v[62:65], off
	global_store_dwordx4 v[48:49], v[42:45], off
	global_store_dwordx4 v[32:33], v[26:29], off
	global_store_dwordx4 v[16:17], v[10:13], off
	global_store_dwordx4 v[14:15], v[6:9], off offset:256
	s_cbranch_vccz .LBB0_107
	s_waitcnt vmcnt(0)
	s_cmpk_gt_u32 s3, 0xff
	s_cbranch_scc1 .LBB0_118
	s_barrier

.LBB0_320:
	ds_read_b128 v[152:155], v149
	ds_read_b128 v[156:159], v149 offset:1024
	ds_read_b128 v[160:163], v149 offset:2048
	ds_read_b128 v[164:167], v149 offset:3072
	s_add_u32 s38, s36, 0xfff80080
	s_addc_u32 s39, s37, -1
	s_cmp_eq_u32 s27, 28
	s_cselect_b32 s41, s4, s39
	s_cselect_b32 s40, s5, s38
	s_cselect_b32 s39, s9, s26
	s_cselect_b32 s38, s21, s23
	v_lshl_add_u64 v[188:189], s[36:37], 0, v[140:141]
	s_add_i32 m0, s35, 0xc000
	ds_read_b128 v[168:171], v150
	ds_read_b128 v[172:175], v150 offset:1024
	ds_read_b128 v[176:179], v150 offset:2048
	ds_read_b128 v[180:183], v150 offset:3072
	ds_read_b128 v[184:187], v150 offset:4096
	ds_read_b128 v[192:195], v150 offset:5120
	ds_read_b128 v[196:199], v150 offset:6144
	ds_read_b128 v[200:203], v150 offset:7168
	global_load_lds_dwordx4 v[188:189], off
	v_lshl_add_u64 v[188:189], s[36:37], 0, v[142:143]
	s_add_i32 m0, s35, 0xe000
	s_nop 0
	global_load_lds_dwordx4 v[188:189], off
	s_waitcnt lgkmcnt(8)
	s_barrier
	s_waitcnt lgkmcnt(0)
	s_setprio 1
	s_waitcnt lgkmcnt(0)
	v_mfma_f32_16x16x32_bf16 v[126:129], v[152:155], v[168:171], v[126:129]
	v_mfma_f32_16x16x32_bf16 v[122:125], v[160:163], v[168:171], v[122:125]
	v_mfma_f32_16x16x32_bf16 v[110:113], v[152:155], v[176:179], v[110:113]
	v_mfma_f32_16x16x32_bf16 v[106:109], v[160:163], v[176:179], v[106:109]
	v_mfma_f32_16x16x32_bf16 v[94:97], v[152:155], v[184:187], v[94:97]
	v_mfma_f32_16x16x32_bf16 v[90:93], v[160:163], v[184:187], v[90:93]
	v_mfma_f32_16x16x32_bf16 v[78:81], v[152:155], v[196:199], v[78:81]
	v_mfma_f32_16x16x32_bf16 v[74:77], v[160:163], v[196:199], v[74:77]
	v_mfma_f32_16x16x32_bf16 v[126:129], v[156:159], v[172:175], v[126:129]
	v_mfma_f32_16x16x32_bf16 v[122:125], v[164:167], v[172:175], v[122:125]
	v_mfma_f32_16x16x32_bf16 v[110:113], v[156:159], v[180:183], v[110:113]
	v_mfma_f32_16x16x32_bf16 v[106:109], v[164:167], v[180:183], v[106:109]
	v_mfma_f32_16x16x32_bf16 v[94:97], v[156:159], v[192:195], v[94:97]
	v_mfma_f32_16x16x32_bf16 v[90:93], v[164:167], v[192:195], v[90:93]
	s_setprio 2
	s_barrier
	v_mfma_f32_16x16x32_bf16 v[78:81], v[156:159], v[200:203], v[78:81]
	v_mfma_f32_16x16x32_bf16 v[74:77], v[164:167], v[200:203], v[74:77]
	s_setprio 0
	s_add_i32 s58, s56, s46
	v_lshl_add_u64 v[188:189], s[38:39], 0, v[132:133]
	s_mov_b32 m0, s58
	ds_read_b128 v[204:207], v151
	ds_read_b128 v[208:211], v151 offset:1024
	ds_read_b128 v[212:215], v151 offset:2048
	ds_read_b128 v[216:219], v151 offset:3072
	global_load_lds_dwordx4 v[188:189], off
	v_lshl_add_u64 v[220:221], s[38:39], 0, v[136:137]
	s_add_i32 m0, s58, 0x2000
	s_nop 0
	global_load_lds_dwordx4 v[220:221], off
	s_barrier
	s_waitcnt lgkmcnt(0)
	s_setprio 1
	s_waitcnt lgkmcnt(0)
	v_mfma_f32_16x16x32_bf16 v[118:121], v[204:207], v[168:171], v[118:121]
	v_mfma_f32_16x16x32_bf16 v[114:117], v[212:215], v[168:171], v[114:117]
	v_mfma_f32_16x16x32_bf16 v[102:105], v[204:207], v[176:179], v[102:105]
	v_mfma_f32_16x16x32_bf16 v[98:101], v[212:215], v[176:179], v[98:101]
	v_mfma_f32_16x16x32_bf16 v[86:89], v[204:207], v[184:187], v[86:89]
	v_mfma_f32_16x16x32_bf16 v[82:85], v[212:215], v[184:187], v[82:85]
	v_mfma_f32_16x16x32_bf16 v[70:73], v[204:207], v[196:199], v[70:73]
	v_mfma_f32_16x16x32_bf16 v[66:69], v[212:215], v[196:199], v[66:69]
	v_mfma_f32_16x16x32_bf16 v[118:121], v[208:211], v[172:175], v[118:121]
	v_mfma_f32_16x16x32_bf16 v[114:117], v[216:219], v[172:175], v[114:117]
	v_mfma_f32_16x16x32_bf16 v[102:105], v[208:211], v[180:183], v[102:105]
	v_mfma_f32_16x16x32_bf16 v[98:101], v[216:219], v[180:183], v[98:101]
	v_mfma_f32_16x16x32_bf16 v[86:89], v[208:211], v[192:195], v[86:89]
	v_mfma_f32_16x16x32_bf16 v[82:85], v[216:219], v[192:195], v[82:85]
	s_setprio 2
	s_mov_b32 m0, s35
	v_lshl_add_u64 v[222:223], s[40:41], 0, v[130:131]
	s_barrier
	v_mfma_f32_16x16x32_bf16 v[70:73], v[208:211], v[200:203], v[70:73]
	v_mfma_f32_16x16x32_bf16 v[66:69], v[216:219], v[200:203], v[66:69]
	s_setprio 0
	ds_read_b128 v[168:171], v150 offset:16384
	ds_read_b128 v[172:175], v150 offset:17408
	ds_read_b128 v[176:179], v150 offset:18432
	ds_read_b128 v[180:183], v150 offset:19456
	ds_read_b128 v[184:187], v150 offset:20480
	ds_read_b128 v[192:195], v150 offset:21504
	ds_read_b128 v[196:199], v150 offset:22528
	ds_read_b128 v[200:203], v150 offset:23552
	global_load_lds_dwordx4 v[222:223], off
	v_lshl_add_u64 v[224:225], s[40:41], 0, v[134:135]
	s_mov_b32 m0, s47
	s_nop 0
	global_load_lds_dwordx4 v[224:225], off
	s_barrier
	s_waitcnt lgkmcnt(0)
	s_setprio 1
	s_waitcnt lgkmcnt(0)
	v_mfma_f32_16x16x32_bf16 v[62:65], v[152:155], v[168:171], v[62:65]
	v_mfma_f32_16x16x32_bf16 v[58:61], v[160:163], v[168:171], v[58:61]
	v_mfma_f32_16x16x32_bf16 v[46:49], v[152:155], v[176:179], v[46:49]
	v_mfma_f32_16x16x32_bf16 v[42:45], v[160:163], v[176:179], v[42:45]
	v_mfma_f32_16x16x32_bf16 v[30:33], v[152:155], v[184:187], v[30:33]
	v_mfma_f32_16x16x32_bf16 v[26:29], v[160:163], v[184:187], v[26:29]
	v_mfma_f32_16x16x32_bf16 v[14:17], v[152:155], v[196:199], v[14:17]
	v_mfma_f32_16x16x32_bf16 v[10:13], v[160:163], v[196:199], v[10:13]
	v_mfma_f32_16x16x32_bf16 v[62:65], v[156:159], v[172:175], v[62:65]
	v_mfma_f32_16x16x32_bf16 v[58:61], v[164:167], v[172:175], v[58:61]
	v_mfma_f32_16x16x32_bf16 v[46:49], v[156:159], v[180:183], v[46:49]
	v_mfma_f32_16x16x32_bf16 v[42:45], v[164:167], v[180:183], v[42:45]
	v_mfma_f32_16x16x32_bf16 v[30:33], v[156:159], v[192:195], v[30:33]
	v_mfma_f32_16x16x32_bf16 v[26:29], v[164:167], v[192:195], v[26:29]
	s_setprio 2
	s_barrier
	v_mfma_f32_16x16x32_bf16 v[14:17], v[156:159], v[200:203], v[14:17]
	v_mfma_f32_16x16x32_bf16 v[10:13], v[164:167], v[200:203], v[10:13]
	s_setprio 0
	s_add_u32 s58, s38, 0x80000
	s_addc_u32 s59, s39, 0
	s_add_i32 s60, s57, s46
	v_lshl_add_u64 v[152:153], s[58:59], 0, v[132:133]
	s_mov_b32 m0, s60
	s_nop 0
	global_load_lds_dwordx4 v[152:153], off
	v_lshl_add_u64 v[152:153], s[58:59], 0, v[136:137]
	s_add_i32 m0, s60, 0x2000
	s_nop 0
	global_load_lds_dwordx4 v[152:153], off
	s_waitcnt vmcnt(6)
	s_barrier
	s_setprio 1
	v_mfma_f32_16x16x32_bf16 v[54:57], v[204:207], v[168:171], v[54:57]
	v_mfma_f32_16x16x32_bf16 v[50:53], v[212:215], v[168:171], v[50:53]
	v_mfma_f32_16x16x32_bf16 v[38:41], v[204:207], v[176:179], v[38:41]
	v_mfma_f32_16x16x32_bf16 v[34:37], v[212:215], v[176:179], v[34:37]
	v_mfma_f32_16x16x32_bf16 v[22:25], v[204:207], v[184:187], v[22:25]
	v_mfma_f32_16x16x32_bf16 v[18:21], v[212:215], v[184:187], v[18:21]
	v_mfma_f32_16x16x32_bf16 v[6:9], v[204:207], v[196:199], v[6:9]
	v_mfma_f32_16x16x32_bf16 v[2:5], v[212:215], v[196:199], v[2:5]
	v_mfma_f32_16x16x32_bf16 v[54:57], v[208:211], v[172:175], v[54:57]
	v_mfma_f32_16x16x32_bf16 v[50:53], v[216:219], v[172:175], v[50:53]
	v_mfma_f32_16x16x32_bf16 v[38:41], v[208:211], v[180:183], v[38:41]
	v_mfma_f32_16x16x32_bf16 v[34:37], v[216:219], v[180:183], v[34:37]
	v_mfma_f32_16x16x32_bf16 v[22:25], v[208:211], v[192:195], v[22:25]
	v_mfma_f32_16x16x32_bf16 v[18:21], v[216:219], v[192:195], v[18:21]
	s_setprio 2
	s_add_i32 s58, 0, 0x18000
	v_add_u32_e32 v164, s58, v148
	s_barrier
	v_mfma_f32_16x16x32_bf16 v[6:9], v[208:211], v[200:203], v[6:9]
	v_mfma_f32_16x16x32_bf16 v[2:5], v[216:219], v[200:203], v[2:5]
	s_setprio 0
	ds_read_b128 v[152:155], v164
	ds_read_b128 v[156:159], v164 offset:1024
	ds_read_b128 v[160:163], v164 offset:2048
	ds_read_b128 v[164:167], v164 offset:3072
	s_add_u32 s40, s40, 0x80000
	s_addc_u32 s41, s41, 0
	s_mov_b32 m0, s48
	v_lshl_add_u64 v[204:205], s[40:41], 0, v[130:131]
	ds_read_b128 v[168:171], v150 offset:32768
	ds_read_b128 v[172:175], v150 offset:33792
	ds_read_b128 v[176:179], v150 offset:34816
	ds_read_b128 v[180:183], v150 offset:35840
	ds_read_b128 v[184:187], v150 offset:36864
	ds_read_b128 v[192:195], v150 offset:37888
	ds_read_b128 v[196:199], v150 offset:38912
	ds_read_b128 v[200:203], v150 offset:39936
	global_load_lds_dwordx4 v[204:205], off
	v_lshl_add_u64 v[204:205], s[40:41], 0, v[134:135]
	s_mov_b32 m0, s49
	s_nop 0
	global_load_lds_dwordx4 v[204:205], off
	s_waitcnt lgkmcnt(8)
	s_barrier
	s_waitcnt lgkmcnt(0)
	s_setprio 1
	s_waitcnt lgkmcnt(0)
	v_mfma_f32_16x16x32_bf16 v[126:129], v[152:155], v[168:171], v[126:129]
	v_mfma_f32_16x16x32_bf16 v[122:125], v[160:163], v[168:171], v[122:125]
	v_mfma_f32_16x16x32_bf16 v[110:113], v[152:155], v[176:179], v[110:113]
	v_mfma_f32_16x16x32_bf16 v[106:109], v[160:163], v[176:179], v[106:109]
	v_mfma_f32_16x16x32_bf16 v[94:97], v[152:155], v[184:187], v[94:97]
	v_mfma_f32_16x16x32_bf16 v[90:93], v[160:163], v[184:187], v[90:93]
	v_mfma_f32_16x16x32_bf16 v[78:81], v[152:155], v[196:199], v[78:81]
	v_mfma_f32_16x16x32_bf16 v[74:77], v[160:163], v[196:199], v[74:77]
	v_mfma_f32_16x16x32_bf16 v[126:129], v[156:159], v[172:175], v[126:129]
	v_mfma_f32_16x16x32_bf16 v[122:125], v[164:167], v[172:175], v[122:125]
	v_mfma_f32_16x16x32_bf16 v[110:113], v[156:159], v[180:183], v[110:113]
	v_mfma_f32_16x16x32_bf16 v[106:109], v[164:167], v[180:183], v[106:109]
	v_mfma_f32_16x16x32_bf16 v[94:97], v[156:159], v[192:195], v[94:97]
	v_mfma_f32_16x16x32_bf16 v[90:93], v[164:167], v[192:195], v[90:93]
	s_setprio 2
	s_barrier
	v_mfma_f32_16x16x32_bf16 v[78:81], v[156:159], v[200:203], v[78:81]
	v_mfma_f32_16x16x32_bf16 v[74:77], v[164:167], v[200:203], v[74:77]
	s_setprio 0
	s_add_i32 s40, 0, 0x1c000
	s_add_i32 s41, s58, s46
	v_add_u32_e32 v191, s40, v148
	v_lshl_add_u64 v[188:189], v[188:189], 0, s[10:11]
	s_mov_b32 m0, s41
	ds_read_b128 v[204:207], v191
	ds_read_b128 v[208:211], v191 offset:1024
	ds_read_b128 v[212:215], v191 offset:2048
	ds_read_b128 v[216:219], v191 offset:3072
	global_load_lds_dwordx4 v[188:189], off
	v_lshl_add_u64 v[188:189], v[220:221], 0, s[10:11]
	s_add_i32 m0, s41, 0x2000
	s_nop 0
	global_load_lds_dwordx4 v[188:189], off
	s_barrier
	s_waitcnt lgkmcnt(0)
	s_setprio 1
	s_waitcnt lgkmcnt(0)
	v_mfma_f32_16x16x32_bf16 v[118:121], v[204:207], v[168:171], v[118:121]
	v_mfma_f32_16x16x32_bf16 v[114:117], v[212:215], v[168:171], v[114:117]
	v_mfma_f32_16x16x32_bf16 v[102:105], v[204:207], v[176:179], v[102:105]
	v_mfma_f32_16x16x32_bf16 v[98:101], v[212:215], v[176:179], v[98:101]
	v_mfma_f32_16x16x32_bf16 v[86:89], v[204:207], v[184:187], v[86:89]
	v_mfma_f32_16x16x32_bf16 v[82:85], v[212:215], v[184:187], v[82:85]
	v_mfma_f32_16x16x32_bf16 v[70:73], v[204:207], v[196:199], v[70:73]
	v_mfma_f32_16x16x32_bf16 v[66:69], v[212:215], v[196:199], v[66:69]
	v_mfma_f32_16x16x32_bf16 v[118:121], v[208:211], v[172:175], v[118:121]
	v_mfma_f32_16x16x32_bf16 v[114:117], v[216:219], v[172:175], v[114:117]
	v_mfma_f32_16x16x32_bf16 v[102:105], v[208:211], v[180:183], v[102:105]
	v_mfma_f32_16x16x32_bf16 v[98:101], v[216:219], v[180:183], v[98:101]
	v_mfma_f32_16x16x32_bf16 v[86:89], v[208:211], v[192:195], v[86:89]
	v_mfma_f32_16x16x32_bf16 v[82:85], v[216:219], v[192:195], v[82:85]
	s_setprio 2
	s_mov_b32 m0, s52
	v_lshl_add_u64 v[188:189], v[222:223], 0, s[10:11]
	s_barrier
	v_mfma_f32_16x16x32_bf16 v[70:73], v[208:211], v[200:203], v[70:73]
	v_mfma_f32_16x16x32_bf16 v[66:69], v[216:219], v[200:203], v[66:69]
	s_setprio 0
	ds_read_b128 v[168:171], v150 offset:49152
	ds_read_b128 v[172:175], v150 offset:50176
	ds_read_b128 v[176:179], v150 offset:51200
	ds_read_b128 v[180:183], v150 offset:52224
	ds_read_b128 v[184:187], v150 offset:53248
	ds_read_b128 v[192:195], v150 offset:54272
	ds_read_b128 v[196:199], v150 offset:55296
	ds_read_b128 v[200:203], v150 offset:56320
	global_load_lds_dwordx4 v[188:189], off
	v_lshl_add_u64 v[188:189], v[224:225], 0, s[10:11]
	s_mov_b32 m0, s53
	s_nop 0
	global_load_lds_dwordx4 v[188:189], off
	s_barrier
	s_waitcnt lgkmcnt(0)
	s_setprio 1
	s_waitcnt lgkmcnt(0)
	v_mfma_f32_16x16x32_bf16 v[62:65], v[152:155], v[168:171], v[62:65]
	v_mfma_f32_16x16x32_bf16 v[58:61], v[160:163], v[168:171], v[58:61]
	v_mfma_f32_16x16x32_bf16 v[46:49], v[152:155], v[176:179], v[46:49]
	v_mfma_f32_16x16x32_bf16 v[42:45], v[160:163], v[176:179], v[42:45]
	v_mfma_f32_16x16x32_bf16 v[30:33], v[152:155], v[184:187], v[30:33]
	v_mfma_f32_16x16x32_bf16 v[26:29], v[160:163], v[184:187], v[26:29]
	v_mfma_f32_16x16x32_bf16 v[14:17], v[152:155], v[196:199], v[14:17]
	v_mfma_f32_16x16x32_bf16 v[10:13], v[160:163], v[196:199], v[10:13]
	v_mfma_f32_16x16x32_bf16 v[62:65], v[156:159], v[172:175], v[62:65]
	v_mfma_f32_16x16x32_bf16 v[58:61], v[164:167], v[172:175], v[58:61]
	v_mfma_f32_16x16x32_bf16 v[46:49], v[156:159], v[180:183], v[46:49]
	v_mfma_f32_16x16x32_bf16 v[42:45], v[164:167], v[180:183], v[42:45]
	v_mfma_f32_16x16x32_bf16 v[30:33], v[156:159], v[192:195], v[30:33]
	v_mfma_f32_16x16x32_bf16 v[26:29], v[164:167], v[192:195], v[26:29]
	s_setprio 2
	s_barrier
	v_mfma_f32_16x16x32_bf16 v[14:17], v[156:159], v[200:203], v[14:17]
	v_mfma_f32_16x16x32_bf16 v[10:13], v[164:167], v[200:203], v[10:13]
	s_setprio 0
	s_add_u32 s38, s38, 0x80080
	s_addc_u32 s39, s39, 0
	s_add_i32 s40, s40, s46
	v_lshl_add_u64 v[152:153], s[38:39], 0, v[132:133]
	s_mov_b32 m0, s40
	s_nop 0
	global_load_lds_dwordx4 v[152:153], off
	v_lshl_add_u64 v[152:153], s[38:39], 0, v[136:137]
	s_add_i32 m0, s40, 0x2000
	s_nop 0
	global_load_lds_dwordx4 v[152:153], off
	s_waitcnt vmcnt(6)
	s_barrier
	s_setprio 1
	v_mfma_f32_16x16x32_bf16 v[54:57], v[204:207], v[168:171], v[54:57]
	v_mfma_f32_16x16x32_bf16 v[50:53], v[212:215], v[168:171], v[50:53]
	v_mfma_f32_16x16x32_bf16 v[38:41], v[204:207], v[176:179], v[38:41]
	v_mfma_f32_16x16x32_bf16 v[34:37], v[212:215], v[176:179], v[34:37]
	v_mfma_f32_16x16x32_bf16 v[22:25], v[204:207], v[184:187], v[22:25]
	v_mfma_f32_16x16x32_bf16 v[18:21], v[212:215], v[184:187], v[18:21]
	v_mfma_f32_16x16x32_bf16 v[6:9], v[204:207], v[196:199], v[6:9]
	v_mfma_f32_16x16x32_bf16 v[2:5], v[212:215], v[196:199], v[2:5]
	v_mfma_f32_16x16x32_bf16 v[54:57], v[208:211], v[172:175], v[54:57]
	v_mfma_f32_16x16x32_bf16 v[50:53], v[216:219], v[172:175], v[50:53]
	v_mfma_f32_16x16x32_bf16 v[38:41], v[208:211], v[180:183], v[38:41]
	v_mfma_f32_16x16x32_bf16 v[34:37], v[216:219], v[180:183], v[34:37]
	v_mfma_f32_16x16x32_bf16 v[22:25], v[208:211], v[192:195], v[22:25]
	v_mfma_f32_16x16x32_bf16 v[18:21], v[216:219], v[192:195], v[18:21]
	s_setprio 2
	s_add_i32 s27, s27, 2
	s_add_u32 s36, s36, 0x100
	s_addc_u32 s37, s37, 0
	s_add_u32 s23, s23, 0x100
	s_addc_u32 s26, s26, 0
	s_cmp_gt_u32 s27, 29
	s_barrier
	v_mfma_f32_16x16x32_bf16 v[6:9], v[208:211], v[200:203], v[6:9]
	v_mfma_f32_16x16x32_bf16 v[2:5], v[216:219], v[200:203], v[2:5]
	s_setprio 0
	s_cbranch_scc0 .LBB0_320
	s_cmp_lt_i32 s8, 2
	s_mov_b64 s[4:5], -1
	s_cbranch_scc1 .LBB0_325
	s_cmp_eq_u32 s8, 2
	v_mov_b32_e32 v158, v125
	v_mov_b32_e32 v157, v124
	v_mov_b32_e32 v155, v123
	v_mov_b32_e32 v153, v122
	v_mov_b32_e32 v159, v129
	v_mov_b32_e32 v156, v128
	v_mov_b32_e32 v154, v127
	v_mov_b32_e32 v152, v126
	s_cbranch_scc0 .LBB0_324
	v_mul_f32_e32 v158, 0xbfb8aa3b, v129
	v_mul_f32_e32 v152, 0xbfb8aa3b, v126
	v_mul_f32_e32 v153, 0xbfb8aa3b, v122
	v_mul_f32_e32 v154, 0xbfb8aa3b, v127
	v_mul_f32_e32 v155, 0xbfb8aa3b, v123
	v_mul_f32_e32 v156, 0xbfb8aa3b, v128
	v_mul_f32_e32 v157, 0xbfb8aa3b, v124
	v_exp_f32_e32 v158, v158
	v_mul_f32_e32 v159, 0xbfb8aa3b, v125
	v_exp_f32_e32 v152, v152
	v_exp_f32_e32 v153, v153
	v_exp_f32_e32 v154, v154
	v_exp_f32_e32 v155, v155
	v_exp_f32_e32 v156, v156
	v_exp_f32_e32 v157, v157
	v_exp_f32_e32 v160, v159
	v_add_f32_e32 v158, 1.0, v158
	v_add_f32_e32 v152, 1.0, v152
	v_add_f32_e32 v153, 1.0, v153
	v_add_f32_e32 v154, 1.0, v154
	v_add_f32_e32 v155, 1.0, v155
	v_add_f32_e32 v156, 1.0, v156
	v_add_f32_e32 v157, 1.0, v157
	v_rcp_f32_e32 v159, v158
	v_add_f32_e32 v158, 1.0, v160
	v_rcp_f32_e32 v152, v152
	v_rcp_f32_e32 v153, v153
	v_rcp_f32_e32 v154, v154
	v_rcp_f32_e32 v155, v155
	v_rcp_f32_e32 v156, v156
	v_rcp_f32_e32 v157, v157
	v_rcp_f32_e32 v158, v158

.LBB0_850:
	ds_read_b128 v[154:157], v150
	ds_read_b128 v[158:161], v150 offset:1024
	ds_read_b128 v[162:165], v150 offset:2048
	ds_read_b128 v[166:169], v150 offset:3072
	s_add_u32 s44, s42, 0xfff80080
	s_addc_u32 s45, s43, -1
	s_cmp_eq_u32 s62, 28
	s_cselect_b32 s47, s4, s45
	s_cselect_b32 s46, s5, s44
	s_cselect_b32 s45, s26, s31
	s_cselect_b32 s44, s27, s29
	v_lshl_add_u64 v[146:147], s[42:43], 0, v[138:139]
	s_add_i32 m0, s39, 0xc000
	ds_read_b128 v[170:173], v151
	ds_read_b128 v[174:177], v151 offset:1024
	ds_read_b128 v[178:181], v151 offset:2048
	ds_read_b128 v[182:185], v151 offset:3072
	ds_read_b128 v[186:189], v151 offset:4096
	ds_read_b128 v[192:195], v151 offset:5120
	ds_read_b128 v[196:199], v151 offset:6144
	ds_read_b128 v[200:203], v151 offset:7168
	global_load_lds_dwordx4 v[146:147], off
	v_lshl_add_u64 v[146:147], s[42:43], 0, v[140:141]
	s_add_i32 m0, s39, 0xe000
	s_nop 0
	global_load_lds_dwordx4 v[146:147], off
	s_waitcnt lgkmcnt(8)
	s_barrier
	s_waitcnt lgkmcnt(0)
	s_setprio 1
	s_waitcnt lgkmcnt(0)
	v_mfma_f32_16x16x32_bf16 v[126:129], v[154:157], v[170:173], v[126:129]
	v_mfma_f32_16x16x32_bf16 v[122:125], v[162:165], v[170:173], v[122:125]
	v_mfma_f32_16x16x32_bf16 v[110:113], v[154:157], v[178:181], v[110:113]
	v_mfma_f32_16x16x32_bf16 v[106:109], v[162:165], v[178:181], v[106:109]
	v_mfma_f32_16x16x32_bf16 v[94:97], v[154:157], v[186:189], v[94:97]
	v_mfma_f32_16x16x32_bf16 v[90:93], v[162:165], v[186:189], v[90:93]
	v_mfma_f32_16x16x32_bf16 v[78:81], v[154:157], v[196:199], v[78:81]
	v_mfma_f32_16x16x32_bf16 v[74:77], v[162:165], v[196:199], v[74:77]
	v_mfma_f32_16x16x32_bf16 v[126:129], v[158:161], v[174:177], v[126:129]
	v_mfma_f32_16x16x32_bf16 v[122:125], v[166:169], v[174:177], v[122:125]
	v_mfma_f32_16x16x32_bf16 v[110:113], v[158:161], v[182:185], v[110:113]
	v_mfma_f32_16x16x32_bf16 v[106:109], v[166:169], v[182:185], v[106:109]
	v_mfma_f32_16x16x32_bf16 v[94:97], v[158:161], v[192:195], v[94:97]
	v_mfma_f32_16x16x32_bf16 v[90:93], v[166:169], v[192:195], v[90:93]
	s_setprio 2
	s_barrier
	v_mfma_f32_16x16x32_bf16 v[78:81], v[158:161], v[200:203], v[78:81]
	v_mfma_f32_16x16x32_bf16 v[74:77], v[166:169], v[200:203], v[74:77]
	s_setprio 0
	s_add_i32 s63, s60, s52
	v_lshl_add_u64 v[146:147], s[44:45], 0, v[132:133]
	s_mov_b32 m0, s63
	ds_read_b128 v[204:207], v152
	ds_read_b128 v[208:211], v152 offset:1024
	ds_read_b128 v[212:215], v152 offset:2048
	ds_read_b128 v[216:219], v152 offset:3072
	global_load_lds_dwordx4 v[146:147], off
	v_lshl_add_u64 v[220:221], s[44:45], 0, v[136:137]
	s_add_i32 m0, s63, 0x2000
	s_nop 0
	global_load_lds_dwordx4 v[220:221], off
	s_barrier
	s_waitcnt lgkmcnt(0)
	s_setprio 1
	s_waitcnt lgkmcnt(0)
	v_mfma_f32_16x16x32_bf16 v[118:121], v[204:207], v[170:173], v[118:121]
	v_mfma_f32_16x16x32_bf16 v[114:117], v[212:215], v[170:173], v[114:117]
	v_mfma_f32_16x16x32_bf16 v[102:105], v[204:207], v[178:181], v[102:105]
	v_mfma_f32_16x16x32_bf16 v[98:101], v[212:215], v[178:181], v[98:101]
	v_mfma_f32_16x16x32_bf16 v[86:89], v[204:207], v[186:189], v[86:89]
	v_mfma_f32_16x16x32_bf16 v[82:85], v[212:215], v[186:189], v[82:85]
	v_mfma_f32_16x16x32_bf16 v[70:73], v[204:207], v[196:199], v[70:73]
	v_mfma_f32_16x16x32_bf16 v[66:69], v[212:215], v[196:199], v[66:69]
	v_mfma_f32_16x16x32_bf16 v[118:121], v[208:211], v[174:177], v[118:121]
	v_mfma_f32_16x16x32_bf16 v[114:117], v[216:219], v[174:177], v[114:117]
	v_mfma_f32_16x16x32_bf16 v[102:105], v[208:211], v[182:185], v[102:105]
	v_mfma_f32_16x16x32_bf16 v[98:101], v[216:219], v[182:185], v[98:101]
	v_mfma_f32_16x16x32_bf16 v[86:89], v[208:211], v[192:195], v[86:89]
	v_mfma_f32_16x16x32_bf16 v[82:85], v[216:219], v[192:195], v[82:85]
	s_setprio 2
	s_mov_b32 m0, s39
	v_lshl_add_u64 v[222:223], s[46:47], 0, v[130:131]
	s_barrier
	v_mfma_f32_16x16x32_bf16 v[70:73], v[208:211], v[200:203], v[70:73]
	v_mfma_f32_16x16x32_bf16 v[66:69], v[216:219], v[200:203], v[66:69]
	s_setprio 0
	ds_read_b128 v[170:173], v151 offset:16384
	ds_read_b128 v[174:177], v151 offset:17408
	ds_read_b128 v[178:181], v151 offset:18432
	ds_read_b128 v[182:185], v151 offset:19456
	ds_read_b128 v[186:189], v151 offset:20480
	ds_read_b128 v[192:195], v151 offset:21504
	ds_read_b128 v[196:199], v151 offset:22528
	ds_read_b128 v[200:203], v151 offset:23552
	global_load_lds_dwordx4 v[222:223], off
	v_lshl_add_u64 v[224:225], s[46:47], 0, v[134:135]
	s_mov_b32 m0, s41
	s_nop 0
	global_load_lds_dwordx4 v[224:225], off
	s_barrier
	s_waitcnt lgkmcnt(0)
	s_setprio 1
	s_waitcnt lgkmcnt(0)
	v_mfma_f32_16x16x32_bf16 v[62:65], v[154:157], v[170:173], v[62:65]
	v_mfma_f32_16x16x32_bf16 v[58:61], v[162:165], v[170:173], v[58:61]
	v_mfma_f32_16x16x32_bf16 v[46:49], v[154:157], v[178:181], v[46:49]
	v_mfma_f32_16x16x32_bf16 v[42:45], v[162:165], v[178:181], v[42:45]
	v_mfma_f32_16x16x32_bf16 v[30:33], v[154:157], v[186:189], v[30:33]
	v_mfma_f32_16x16x32_bf16 v[26:29], v[162:165], v[186:189], v[26:29]
	v_mfma_f32_16x16x32_bf16 v[14:17], v[154:157], v[196:199], v[14:17]
	v_mfma_f32_16x16x32_bf16 v[10:13], v[162:165], v[196:199], v[10:13]
	v_mfma_f32_16x16x32_bf16 v[62:65], v[158:161], v[174:177], v[62:65]
	v_mfma_f32_16x16x32_bf16 v[58:61], v[166:169], v[174:177], v[58:61]
	v_mfma_f32_16x16x32_bf16 v[46:49], v[158:161], v[182:185], v[46:49]
	v_mfma_f32_16x16x32_bf16 v[42:45], v[166:169], v[182:185], v[42:45]
	v_mfma_f32_16x16x32_bf16 v[30:33], v[158:161], v[192:195], v[30:33]
	v_mfma_f32_16x16x32_bf16 v[26:29], v[166:169], v[192:195], v[26:29]
	s_setprio 2
	s_barrier
	v_mfma_f32_16x16x32_bf16 v[14:17], v[158:161], v[200:203], v[14:17]
	v_mfma_f32_16x16x32_bf16 v[10:13], v[166:169], v[200:203], v[10:13]
	s_setprio 0
	s_add_u32 s64, s44, 0x80000
	s_addc_u32 s65, s45, 0
	s_add_i32 s63, s61, s52
	v_lshl_add_u64 v[154:155], s[64:65], 0, v[132:133]
	s_mov_b32 m0, s63
	s_nop 0
	global_load_lds_dwordx4 v[154:155], off
	v_lshl_add_u64 v[154:155], s[64:65], 0, v[136:137]
	s_add_i32 m0, s63, 0x2000
	s_nop 0
	global_load_lds_dwordx4 v[154:155], off
	s_waitcnt vmcnt(6)
	s_barrier
	s_setprio 1
	v_mfma_f32_16x16x32_bf16 v[54:57], v[204:207], v[170:173], v[54:57]
	v_mfma_f32_16x16x32_bf16 v[50:53], v[212:215], v[170:173], v[50:53]
	v_mfma_f32_16x16x32_bf16 v[38:41], v[204:207], v[178:181], v[38:41]
	v_mfma_f32_16x16x32_bf16 v[34:37], v[212:215], v[178:181], v[34:37]
	v_mfma_f32_16x16x32_bf16 v[22:25], v[204:207], v[186:189], v[22:25]
	v_mfma_f32_16x16x32_bf16 v[18:21], v[212:215], v[186:189], v[18:21]
	v_mfma_f32_16x16x32_bf16 v[6:9], v[204:207], v[196:199], v[6:9]
	v_mfma_f32_16x16x32_bf16 v[2:5], v[212:215], v[196:199], v[2:5]
	v_mfma_f32_16x16x32_bf16 v[54:57], v[208:211], v[174:177], v[54:57]
	v_mfma_f32_16x16x32_bf16 v[50:53], v[216:219], v[174:177], v[50:53]
	v_mfma_f32_16x16x32_bf16 v[38:41], v[208:211], v[182:185], v[38:41]
	v_mfma_f32_16x16x32_bf16 v[34:37], v[216:219], v[182:185], v[34:37]
	v_mfma_f32_16x16x32_bf16 v[22:25], v[208:211], v[192:195], v[22:25]
	v_mfma_f32_16x16x32_bf16 v[18:21], v[216:219], v[192:195], v[18:21]
	s_setprio 2
	s_add_i32 s63, 0, 0x18000
	v_add_u32_e32 v153, s63, v148
	s_barrier
	v_mfma_f32_16x16x32_bf16 v[6:9], v[208:211], v[200:203], v[6:9]
	v_mfma_f32_16x16x32_bf16 v[2:5], v[216:219], v[200:203], v[2:5]
	s_setprio 0
	ds_read_b128 v[154:157], v153
	ds_read_b128 v[158:161], v153 offset:1024
	ds_read_b128 v[162:165], v153 offset:2048
	ds_read_b128 v[166:169], v153 offset:3072
	s_add_u32 s46, s46, 0x80000
	s_addc_u32 s47, s47, 0
	s_mov_b32 m0, s53
	v_lshl_add_u64 v[204:205], s[46:47], 0, v[130:131]
	ds_read_b128 v[170:173], v151 offset:32768
	ds_read_b128 v[174:177], v151 offset:33792
	ds_read_b128 v[178:181], v151 offset:34816
	ds_read_b128 v[182:185], v151 offset:35840
	ds_read_b128 v[186:189], v151 offset:36864
	ds_read_b128 v[192:195], v151 offset:37888
	ds_read_b128 v[196:199], v151 offset:38912
	ds_read_b128 v[200:203], v151 offset:39936
	global_load_lds_dwordx4 v[204:205], off
	v_lshl_add_u64 v[204:205], s[46:47], 0, v[134:135]
	s_mov_b32 m0, s54
	s_nop 0
	global_load_lds_dwordx4 v[204:205], off
	s_waitcnt lgkmcnt(8)
	s_barrier
	s_waitcnt lgkmcnt(0)
	s_setprio 1
	s_waitcnt lgkmcnt(0)
	v_mfma_f32_16x16x32_bf16 v[126:129], v[154:157], v[170:173], v[126:129]
	v_mfma_f32_16x16x32_bf16 v[122:125], v[162:165], v[170:173], v[122:125]
	v_mfma_f32_16x16x32_bf16 v[110:113], v[154:157], v[178:181], v[110:113]
	v_mfma_f32_16x16x32_bf16 v[106:109], v[162:165], v[178:181], v[106:109]
	v_mfma_f32_16x16x32_bf16 v[94:97], v[154:157], v[186:189], v[94:97]
	v_mfma_f32_16x16x32_bf16 v[90:93], v[162:165], v[186:189], v[90:93]
	v_mfma_f32_16x16x32_bf16 v[78:81], v[154:157], v[196:199], v[78:81]
	v_mfma_f32_16x16x32_bf16 v[74:77], v[162:165], v[196:199], v[74:77]
	v_mfma_f32_16x16x32_bf16 v[126:129], v[158:161], v[174:177], v[126:129]
	v_mfma_f32_16x16x32_bf16 v[122:125], v[166:169], v[174:177], v[122:125]
	v_mfma_f32_16x16x32_bf16 v[110:113], v[158:161], v[182:185], v[110:113]
	v_mfma_f32_16x16x32_bf16 v[106:109], v[166:169], v[182:185], v[106:109]
	v_mfma_f32_16x16x32_bf16 v[94:97], v[158:161], v[192:195], v[94:97]
	v_mfma_f32_16x16x32_bf16 v[90:93], v[166:169], v[192:195], v[90:93]
	s_setprio 2
	s_barrier
	v_mfma_f32_16x16x32_bf16 v[78:81], v[158:161], v[200:203], v[78:81]
	v_mfma_f32_16x16x32_bf16 v[74:77], v[166:169], v[200:203], v[74:77]
	s_setprio 0
	s_add_i32 s46, 0, 0x1c000
	s_add_i32 s47, s63, s52
	v_add_u32_e32 v153, s46, v148
	v_lshl_add_u64 v[146:147], v[146:147], 0, s[12:13]
	s_mov_b32 m0, s47
	ds_read_b128 v[204:207], v153
	ds_read_b128 v[208:211], v153 offset:1024
	ds_read_b128 v[212:215], v153 offset:2048
	ds_read_b128 v[216:219], v153 offset:3072
	global_load_lds_dwordx4 v[146:147], off
	v_lshl_add_u64 v[146:147], v[220:221], 0, s[12:13]
	s_add_i32 m0, s47, 0x2000
	s_nop 0
	global_load_lds_dwordx4 v[146:147], off
	s_barrier
	s_waitcnt lgkmcnt(0)
	s_setprio 1
	s_waitcnt lgkmcnt(0)
	v_mfma_f32_16x16x32_bf16 v[118:121], v[204:207], v[170:173], v[118:121]
	v_mfma_f32_16x16x32_bf16 v[114:117], v[212:215], v[170:173], v[114:117]
	v_mfma_f32_16x16x32_bf16 v[102:105], v[204:207], v[178:181], v[102:105]
	v_mfma_f32_16x16x32_bf16 v[98:101], v[212:215], v[178:181], v[98:101]
	v_mfma_f32_16x16x32_bf16 v[86:89], v[204:207], v[186:189], v[86:89]
	v_mfma_f32_16x16x32_bf16 v[82:85], v[212:215], v[186:189], v[82:85]
	v_mfma_f32_16x16x32_bf16 v[70:73], v[204:207], v[196:199], v[70:73]
	v_mfma_f32_16x16x32_bf16 v[66:69], v[212:215], v[196:199], v[66:69]
	v_mfma_f32_16x16x32_bf16 v[118:121], v[208:211], v[174:177], v[118:121]
	v_mfma_f32_16x16x32_bf16 v[114:117], v[216:219], v[174:177], v[114:117]
	v_mfma_f32_16x16x32_bf16 v[102:105], v[208:211], v[182:185], v[102:105]
	v_mfma_f32_16x16x32_bf16 v[98:101], v[216:219], v[182:185], v[98:101]
	v_mfma_f32_16x16x32_bf16 v[86:89], v[208:211], v[192:195], v[86:89]
	v_mfma_f32_16x16x32_bf16 v[82:85], v[216:219], v[192:195], v[82:85]
	s_setprio 2
	s_mov_b32 m0, s56
	v_lshl_add_u64 v[146:147], v[222:223], 0, s[12:13]
	s_barrier
	v_mfma_f32_16x16x32_bf16 v[70:73], v[208:211], v[200:203], v[70:73]
	v_mfma_f32_16x16x32_bf16 v[66:69], v[216:219], v[200:203], v[66:69]
	s_setprio 0
	ds_read_b128 v[170:173], v151 offset:49152
	ds_read_b128 v[174:177], v151 offset:50176
	ds_read_b128 v[178:181], v151 offset:51200
	ds_read_b128 v[182:185], v151 offset:52224
	ds_read_b128 v[186:189], v151 offset:53248
	ds_read_b128 v[192:195], v151 offset:54272
	ds_read_b128 v[196:199], v151 offset:55296
	ds_read_b128 v[200:203], v151 offset:56320
	global_load_lds_dwordx4 v[146:147], off
	v_lshl_add_u64 v[146:147], v[224:225], 0, s[12:13]
	s_mov_b32 m0, s57
	s_nop 0
	global_load_lds_dwordx4 v[146:147], off
	s_barrier
	s_waitcnt lgkmcnt(0)
	s_setprio 1
	s_waitcnt lgkmcnt(0)
	v_mfma_f32_16x16x32_bf16 v[62:65], v[154:157], v[170:173], v[62:65]
	v_mfma_f32_16x16x32_bf16 v[58:61], v[162:165], v[170:173], v[58:61]
	v_mfma_f32_16x16x32_bf16 v[46:49], v[154:157], v[178:181], v[46:49]
	v_mfma_f32_16x16x32_bf16 v[42:45], v[162:165], v[178:181], v[42:45]
	v_mfma_f32_16x16x32_bf16 v[30:33], v[154:157], v[186:189], v[30:33]
	v_mfma_f32_16x16x32_bf16 v[26:29], v[162:165], v[186:189], v[26:29]
	v_mfma_f32_16x16x32_bf16 v[14:17], v[154:157], v[196:199], v[14:17]
	v_mfma_f32_16x16x32_bf16 v[10:13], v[162:165], v[196:199], v[10:13]
	v_mfma_f32_16x16x32_bf16 v[62:65], v[158:161], v[174:177], v[62:65]
	v_mfma_f32_16x16x32_bf16 v[58:61], v[166:169], v[174:177], v[58:61]
	v_mfma_f32_16x16x32_bf16 v[46:49], v[158:161], v[182:185], v[46:49]
	v_mfma_f32_16x16x32_bf16 v[42:45], v[166:169], v[182:185], v[42:45]
	v_mfma_f32_16x16x32_bf16 v[30:33], v[158:161], v[192:195], v[30:33]
	v_mfma_f32_16x16x32_bf16 v[26:29], v[166:169], v[192:195], v[26:29]
	s_setprio 2
	s_barrier
	v_mfma_f32_16x16x32_bf16 v[14:17], v[158:161], v[200:203], v[14:17]
	v_mfma_f32_16x16x32_bf16 v[10:13], v[166:169], v[200:203], v[10:13]
	s_setprio 0
	s_add_u32 s44, s44, 0x80080
	s_addc_u32 s45, s45, 0
	s_add_i32 s46, s46, s52
	v_lshl_add_u64 v[146:147], s[44:45], 0, v[132:133]
	s_mov_b32 m0, s46
	s_nop 0
	global_load_lds_dwordx4 v[146:147], off
	v_lshl_add_u64 v[146:147], s[44:45], 0, v[136:137]
	s_add_i32 m0, s46, 0x2000
	s_nop 0
	global_load_lds_dwordx4 v[146:147], off
	s_waitcnt vmcnt(6)
	s_barrier
	s_setprio 1
	v_mfma_f32_16x16x32_bf16 v[54:57], v[204:207], v[170:173], v[54:57]
	v_mfma_f32_16x16x32_bf16 v[50:53], v[212:215], v[170:173], v[50:53]
	v_mfma_f32_16x16x32_bf16 v[38:41], v[204:207], v[178:181], v[38:41]
	v_mfma_f32_16x16x32_bf16 v[34:37], v[212:215], v[178:181], v[34:37]
	v_mfma_f32_16x16x32_bf16 v[22:25], v[204:207], v[186:189], v[22:25]
	v_mfma_f32_16x16x32_bf16 v[18:21], v[212:215], v[186:189], v[18:21]
	v_mfma_f32_16x16x32_bf16 v[6:9], v[204:207], v[196:199], v[6:9]
	v_mfma_f32_16x16x32_bf16 v[2:5], v[212:215], v[196:199], v[2:5]
	v_mfma_f32_16x16x32_bf16 v[54:57], v[208:211], v[174:177], v[54:57]
	v_mfma_f32_16x16x32_bf16 v[50:53], v[216:219], v[174:177], v[50:53]
	v_mfma_f32_16x16x32_bf16 v[38:41], v[208:211], v[182:185], v[38:41]
	v_mfma_f32_16x16x32_bf16 v[34:37], v[216:219], v[182:185], v[34:37]
	v_mfma_f32_16x16x32_bf16 v[22:25], v[208:211], v[192:195], v[22:25]
	v_mfma_f32_16x16x32_bf16 v[18:21], v[216:219], v[192:195], v[18:21]
	s_setprio 2
	s_add_i32 s62, s62, 2
	s_add_u32 s42, s42, 0x100
	s_addc_u32 s43, s43, 0
	s_add_u32 s29, s29, 0x100
	s_addc_u32 s31, s31, 0
	s_cmp_gt_u32 s62, 29
	s_barrier
	v_mfma_f32_16x16x32_bf16 v[6:9], v[208:211], v[200:203], v[6:9]
	v_mfma_f32_16x16x32_bf16 v[2:5], v[216:219], v[200:203], v[2:5]
	s_setprio 0
	s_cbranch_scc0 .LBB0_850
	s_lshl_b32 s4, s40, 8
	s_and_b32 s4, s4, 0x3f00
	v_add_u32_e32 v162, s4, v1
	s_ashr_i32 s4, s38, 31
	s_lshr_b32 s4, s4, 29
	s_add_i32 s4, s38, s4
	s_and_b32 s4, s4, 0xfffff8
	s_sub_i32 s4, s38, s4
	v_lshl_or_b32 v164, s4, 8, v149
	v_ashrrev_i32_e32 v163, 31, v162
	v_ashrrev_i32_e32 v165, 31, v164
	v_lshlrev_b32_e32 v146, 13, v162
	v_lshl_add_u32 v146, v164, 2, v146
	v_lshlrev_b32_e32 v147, 12, v162
	v_lshl_add_u32 v147, v164, 1, v147
	s_add_u32 s64, s8, 0x0
	s_addc_u32 s65, s9, 0
	global_load_dwordx4 v[176:179], v146, s[64:65]
	global_load_dwordx4 v[180:183], v146, s[64:65] offset:16
	s_add_u32 s64, s8, 0x200
	s_addc_u32 s65, s9, 0
	global_load_dwordx4 v[184:187], v146, s[64:65]
	global_load_dwordx4 v[192:195], v146, s[64:65] offset:16
	s_add_u32 s64, s8, 0x20000
	s_addc_u32 s65, s9, 0
	global_load_dwordx4 v[196:199], v146, s[64:65]
	global_load_dwordx4 v[200:203], v146, s[64:65] offset:16
	s_add_u32 s64, s8, 0x20200
	s_addc_u32 s65, s9, 0
	global_load_dwordx4 v[204:207], v146, s[64:65]
	global_load_dwordx4 v[208:211], v146, s[64:65] offset:16
	s_add_u32 s64, s8, 0x40000
	s_addc_u32 s65, s9, 0
	global_load_dwordx4 v[212:215], v146, s[64:65]
	global_load_dwordx4 v[216:219], v146, s[64:65] offset:16
	s_add_u32 s64, s8, 0x40200
	s_addc_u32 s65, s9, 0
	global_load_dwordx4 v[220:223], v146, s[64:65]
	global_load_dwordx4 v[224:227], v146, s[64:65] offset:16
	s_add_u32 s64, s8, 0x60000
	s_addc_u32 s65, s9, 0
	global_load_dwordx4 v[228:231], v146, s[64:65]
	global_load_dwordx4 v[232:235], v146, s[64:65] offset:16
	s_add_u32 s64, s8, 0x60200
	s_addc_u32 s65, s9, 0
	global_load_dwordx4 v[236:239], v146, s[64:65]
	global_load_dwordx4 v[240:243], v146, s[64:65] offset:16
	s_waitcnt vmcnt(14)
	v_pk_fma_f32 v[176:177], v[176:177], s[14:15], v[126:127] op_sel_hi:[1,0,1]
	v_pk_fma_f32 v[178:179], v[178:179], s[14:15], v[128:129] op_sel_hi:[1,0,1]
	v_pk_fma_f32 v[180:181], v[180:181], s[14:15], v[122:123] op_sel_hi:[1,0,1]
	v_pk_fma_f32 v[182:183], v[182:183], s[14:15], v[124:125] op_sel_hi:[1,0,1]
	v_cvt_pk_bf16_f32 v176, v176, v177
	v_cvt_pk_bf16_f32 v177, v178, v179
	v_cvt_pk_bf16_f32 v178, v180, v181
	v_cvt_pk_bf16_f32 v179, v182, v183
	s_add_u32 s66, s10, 0x0
	s_addc_u32 s67, s11, 0
	global_store_dwordx4 v147, v[176:179], s[66:67]
	s_waitcnt vmcnt(13)
	v_pk_fma_f32 v[184:185], v[184:185], s[14:15], v[118:119] op_sel_hi:[1,0,1]
	v_pk_fma_f32 v[186:187], v[186:187], s[14:15], v[120:121] op_sel_hi:[1,0,1]
	v_pk_fma_f32 v[192:193], v[192:193], s[14:15], v[114:115] op_sel_hi:[1,0,1]
	v_pk_fma_f32 v[194:195], v[194:195], s[14:15], v[116:117] op_sel_hi:[1,0,1]
	v_cvt_pk_bf16_f32 v184, v184, v185
	v_cvt_pk_bf16_f32 v185, v186, v187
	v_cvt_pk_bf16_f32 v186, v192, v193
	v_cvt_pk_bf16_f32 v187, v194, v195
	s_add_u32 s66, s10, 0x100
	s_addc_u32 s67, s11, 0
	global_store_dwordx4 v147, v[184:187], s[66:67]
	s_waitcnt vmcnt(12)
	v_pk_fma_f32 v[196:197], v[196:197], s[14:15], v[110:111] op_sel_hi:[1,0,1]
	v_pk_fma_f32 v[198:199], v[198:199], s[14:15], v[112:113] op_sel_hi:[1,0,1]
	v_pk_fma_f32 v[200:201], v[200:201], s[14:15], v[106:107] op_sel_hi:[1,0,1]
	v_pk_fma_f32 v[202:203], v[202:203], s[14:15], v[108:109] op_sel_hi:[1,0,1]
	v_cvt_pk_bf16_f32 v196, v196, v197
	v_cvt_pk_bf16_f32 v197, v198, v199
	v_cvt_pk_bf16_f32 v198, v200, v201
	v_cvt_pk_bf16_f32 v199, v202, v203
	s_add_u32 s66, s10, 0x10000
	s_addc_u32 s67, s11, 0
	global_store_dwordx4 v147, v[196:199], s[66:67]
	s_waitcnt vmcnt(11)
	v_pk_fma_f32 v[204:205], v[204:205], s[14:15], v[102:103] op_sel_hi:[1,0,1]
	v_pk_fma_f32 v[206:207], v[206:207], s[14:15], v[104:105] op_sel_hi:[1,0,1]
	v_pk_fma_f32 v[208:209], v[208:209], s[14:15], v[98:99] op_sel_hi:[1,0,1]
	v_pk_fma_f32 v[210:211], v[210:211], s[14:15], v[100:101] op_sel_hi:[1,0,1]
	v_cvt_pk_bf16_f32 v204, v204, v205
	v_cvt_pk_bf16_f32 v205, v206, v207
	v_cvt_pk_bf16_f32 v206, v208, v209
	v_cvt_pk_bf16_f32 v207, v210, v211
	s_add_u32 s66, s10, 0x10100
	s_addc_u32 s67, s11, 0
	global_store_dwordx4 v147, v[204:207], s[66:67]
	s_waitcnt vmcnt(10)
	v_pk_fma_f32 v[212:213], v[212:213], s[14:15], v[94:95] op_sel_hi:[1,0,1]
	v_pk_fma_f32 v[214:215], v[214:215], s[14:15], v[96:97] op_sel_hi:[1,0,1]
	v_pk_fma_f32 v[216:217], v[216:217], s[14:15], v[90:91] op_sel_hi:[1,0,1]
	v_pk_fma_f32 v[218:219], v[218:219], s[14:15], v[92:93] op_sel_hi:[1,0,1]
	v_cvt_pk_bf16_f32 v212, v212, v213
	v_cvt_pk_bf16_f32 v213, v214, v215
	v_cvt_pk_bf16_f32 v214, v216, v217
	v_cvt_pk_bf16_f32 v215, v218, v219
	s_add_u32 s66, s10, 0x20000
	s_addc_u32 s67, s11, 0
	global_store_dwordx4 v147, v[212:215], s[66:67]
	s_waitcnt vmcnt(9)
	v_pk_fma_f32 v[220:221], v[220:221], s[14:15], v[86:87] op_sel_hi:[1,0,1]
	v_pk_fma_f32 v[222:223], v[222:223], s[14:15], v[88:89] op_sel_hi:[1,0,1]
	v_pk_fma_f32 v[224:225], v[224:225], s[14:15], v[82:83] op_sel_hi:[1,0,1]
	v_pk_fma_f32 v[226:227], v[226:227], s[14:15], v[84:85] op_sel_hi:[1,0,1]
	v_cvt_pk_bf16_f32 v220, v220, v221
	v_cvt_pk_bf16_f32 v221, v222, v223
	v_cvt_pk_bf16_f32 v222, v224, v225
	v_cvt_pk_bf16_f32 v223, v226, v227
	s_add_u32 s66, s10, 0x20100
	s_addc_u32 s67, s11, 0
	global_store_dwordx4 v147, v[220:223], s[66:67]
	s_waitcnt vmcnt(8)
	v_pk_fma_f32 v[228:229], v[228:229], s[14:15], v[78:79] op_sel_hi:[1,0,1]
	v_pk_fma_f32 v[230:231], v[230:231], s[14:15], v[80:81] op_sel_hi:[1,0,1]
	v_pk_fma_f32 v[232:233], v[232:233], s[14:15], v[74:75] op_sel_hi:[1,0,1]
	v_pk_fma_f32 v[234:235], v[234:235], s[14:15], v[76:77] op_sel_hi:[1,0,1]
	v_cvt_pk_bf16_f32 v228, v228, v229
	v_cvt_pk_bf16_f32 v229, v230, v231
	v_cvt_pk_bf16_f32 v230, v232, v233
	v_cvt_pk_bf16_f32 v231, v234, v235
	s_add_u32 s66, s10, 0x30000
	s_addc_u32 s67, s11, 0
	global_store_dwordx4 v147, v[228:231], s[66:67]
	s_waitcnt vmcnt(7)
	v_pk_fma_f32 v[236:237], v[236:237], s[14:15], v[70:71] op_sel_hi:[1,0,1]
	v_pk_fma_f32 v[238:239], v[238:239], s[14:15], v[72:73] op_sel_hi:[1,0,1]
	v_pk_fma_f32 v[240:241], v[240:241], s[14:15], v[66:67] op_sel_hi:[1,0,1]
	v_pk_fma_f32 v[242:243], v[242:243], s[14:15], v[68:69] op_sel_hi:[1,0,1]
	v_cvt_pk_bf16_f32 v236, v236, v237
	v_cvt_pk_bf16_f32 v237, v238, v239
	v_cvt_pk_bf16_f32 v238, v240, v241
	v_cvt_pk_bf16_f32 v239, v242, v243
	s_add_u32 s66, s10, 0x30100
	s_addc_u32 s67, s11, 0
	global_store_dwordx4 v147, v[236:239], s[66:67]
	s_add_u32 s64, s8, 0x100000
	s_addc_u32 s65, s9, 0
	global_load_dwordx4 v[176:179], v146, s[64:65]
	global_load_dwordx4 v[180:183], v146, s[64:65] offset:16
	s_add_u32 s64, s8, 0x100200
	s_addc_u32 s65, s9, 0
	global_load_dwordx4 v[184:187], v146, s[64:65]
	global_load_dwordx4 v[192:195], v146, s[64:65] offset:16
	s_add_u32 s64, s8, 0x120000
	s_addc_u32 s65, s9, 0
	global_load_dwordx4 v[196:199], v146, s[64:65]
	global_load_dwordx4 v[200:203], v146, s[64:65] offset:16
	s_add_u32 s64, s8, 0x120200
	s_addc_u32 s65, s9, 0
	global_load_dwordx4 v[204:207], v146, s[64:65]
	global_load_dwordx4 v[208:211], v146, s[64:65] offset:16
	s_add_u32 s64, s8, 0x140000
	s_addc_u32 s65, s9, 0
	global_load_dwordx4 v[212:215], v146, s[64:65]
	global_load_dwordx4 v[216:219], v146, s[64:65] offset:16
	s_add_u32 s64, s8, 0x140200
	s_addc_u32 s65, s9, 0
	global_load_dwordx4 v[220:223], v146, s[64:65]
	global_load_dwordx4 v[224:227], v146, s[64:65] offset:16
	s_add_u32 s64, s8, 0x160000
	s_addc_u32 s65, s9, 0
	global_load_dwordx4 v[228:231], v146, s[64:65]
	global_load_dwordx4 v[232:235], v146, s[64:65] offset:16
	s_add_u32 s64, s8, 0x160200
	s_addc_u32 s65, s9, 0
	global_load_dwordx4 v[236:239], v146, s[64:65]
	global_load_dwordx4 v[240:243], v146, s[64:65] offset:16
	s_waitcnt vmcnt(14)
	v_pk_fma_f32 v[176:177], v[176:177], s[14:15], v[62:63] op_sel_hi:[1,0,1]
	v_pk_fma_f32 v[178:179], v[178:179], s[14:15], v[64:65] op_sel_hi:[1,0,1]
	v_pk_fma_f32 v[180:181], v[180:181], s[14:15], v[58:59] op_sel_hi:[1,0,1]
	v_pk_fma_f32 v[182:183], v[182:183], s[14:15], v[60:61] op_sel_hi:[1,0,1]
	v_cvt_pk_bf16_f32 v176, v176, v177
	v_cvt_pk_bf16_f32 v177, v178, v179
	v_cvt_pk_bf16_f32 v178, v180, v181
	v_cvt_pk_bf16_f32 v179, v182, v183
	s_add_u32 s66, s10, 0x80000
	s_addc_u32 s67, s11, 0
	global_store_dwordx4 v147, v[176:179], s[66:67]
	s_waitcnt vmcnt(13)
	v_pk_fma_f32 v[184:185], v[184:185], s[14:15], v[54:55] op_sel_hi:[1,0,1]
	v_pk_fma_f32 v[186:187], v[186:187], s[14:15], v[56:57] op_sel_hi:[1,0,1]
	v_pk_fma_f32 v[192:193], v[192:193], s[14:15], v[50:51] op_sel_hi:[1,0,1]
	v_pk_fma_f32 v[194:195], v[194:195], s[14:15], v[52:53] op_sel_hi:[1,0,1]
	v_cvt_pk_bf16_f32 v184, v184, v185
	v_cvt_pk_bf16_f32 v185, v186, v187
	v_cvt_pk_bf16_f32 v186, v192, v193
	v_cvt_pk_bf16_f32 v187, v194, v195
	s_add_u32 s66, s10, 0x80100
	s_addc_u32 s67, s11, 0
	global_store_dwordx4 v147, v[184:187], s[66:67]
	s_waitcnt vmcnt(12)
	v_pk_fma_f32 v[196:197], v[196:197], s[14:15], v[46:47] op_sel_hi:[1,0,1]
	v_pk_fma_f32 v[198:199], v[198:199], s[14:15], v[48:49] op_sel_hi:[1,0,1]
	v_pk_fma_f32 v[200:201], v[200:201], s[14:15], v[42:43] op_sel_hi:[1,0,1]
	v_pk_fma_f32 v[202:203], v[202:203], s[14:15], v[44:45] op_sel_hi:[1,0,1]
	v_cvt_pk_bf16_f32 v196, v196, v197
	v_cvt_pk_bf16_f32 v197, v198, v199
	v_cvt_pk_bf16_f32 v198, v200, v201
	v_cvt_pk_bf16_f32 v199, v202, v203
	s_add_u32 s66, s10, 0x90000
	s_addc_u32 s67, s11, 0
	global_store_dwordx4 v147, v[196:199], s[66:67]
	s_waitcnt vmcnt(11)
	v_pk_fma_f32 v[204:205], v[204:205], s[14:15], v[38:39] op_sel_hi:[1,0,1]
	v_pk_fma_f32 v[206:207], v[206:207], s[14:15], v[40:41] op_sel_hi:[1,0,1]
	v_pk_fma_f32 v[208:209], v[208:209], s[14:15], v[34:35] op_sel_hi:[1,0,1]
	v_pk_fma_f32 v[210:211], v[210:211], s[14:15], v[36:37] op_sel_hi:[1,0,1]
	v_cvt_pk_bf16_f32 v204, v204, v205
	v_cvt_pk_bf16_f32 v205, v206, v207
	v_cvt_pk_bf16_f32 v206, v208, v209
	v_cvt_pk_bf16_f32 v207, v210, v211
	s_add_u32 s66, s10, 0x90100
	s_addc_u32 s67, s11, 0
	global_store_dwordx4 v147, v[204:207], s[66:67]
	s_waitcnt vmcnt(10)
	v_pk_fma_f32 v[212:213], v[212:213], s[14:15], v[30:31] op_sel_hi:[1,0,1]
	v_pk_fma_f32 v[214:215], v[214:215], s[14:15], v[32:33] op_sel_hi:[1,0,1]
	v_pk_fma_f32 v[216:217], v[216:217], s[14:15], v[26:27] op_sel_hi:[1,0,1]
	v_pk_fma_f32 v[218:219], v[218:219], s[14:15], v[28:29] op_sel_hi:[1,0,1]
	v_cvt_pk_bf16_f32 v212, v212, v213
	v_cvt_pk_bf16_f32 v213, v214, v215
	v_cvt_pk_bf16_f32 v214, v216, v217
	v_cvt_pk_bf16_f32 v215, v218, v219
	s_add_u32 s66, s10, 0xa0000
	s_addc_u32 s67, s11, 0
	global_store_dwordx4 v147, v[212:215], s[66:67]
	s_waitcnt vmcnt(9)
	v_pk_fma_f32 v[220:221], v[220:221], s[14:15], v[22:23] op_sel_hi:[1,0,1]
	v_pk_fma_f32 v[222:223], v[222:223], s[14:15], v[24:25] op_sel_hi:[1,0,1]
	v_pk_fma_f32 v[224:225], v[224:225], s[14:15], v[18:19] op_sel_hi:[1,0,1]
	v_pk_fma_f32 v[226:227], v[226:227], s[14:15], v[20:21] op_sel_hi:[1,0,1]
	v_cvt_pk_bf16_f32 v220, v220, v221
	v_cvt_pk_bf16_f32 v221, v222, v223
	v_cvt_pk_bf16_f32 v222, v224, v225
	v_cvt_pk_bf16_f32 v223, v226, v227
	s_add_u32 s66, s10, 0xa0100
	s_addc_u32 s67, s11, 0
	global_store_dwordx4 v147, v[220:223], s[66:67]
	s_waitcnt vmcnt(8)
	v_pk_fma_f32 v[228:229], v[228:229], s[14:15], v[14:15] op_sel_hi:[1,0,1]
	v_pk_fma_f32 v[230:231], v[230:231], s[14:15], v[16:17] op_sel_hi:[1,0,1]
	v_pk_fma_f32 v[232:233], v[232:233], s[14:15], v[10:11] op_sel_hi:[1,0,1]
	v_pk_fma_f32 v[234:235], v[234:235], s[14:15], v[12:13] op_sel_hi:[1,0,1]
	v_cvt_pk_bf16_f32 v228, v228, v229
	v_cvt_pk_bf16_f32 v229, v230, v231
	v_cvt_pk_bf16_f32 v230, v232, v233
	v_cvt_pk_bf16_f32 v231, v234, v235
	s_add_u32 s66, s10, 0xb0000
	s_addc_u32 s67, s11, 0
	global_store_dwordx4 v147, v[228:231], s[66:67]
	s_waitcnt vmcnt(7)
	v_pk_fma_f32 v[236:237], v[236:237], s[14:15], v[6:7] op_sel_hi:[1,0,1]
	v_pk_fma_f32 v[238:239], v[238:239], s[14:15], v[8:9] op_sel_hi:[1,0,1]
	v_pk_fma_f32 v[240:241], v[240:241], s[14:15], v[2:3] op_sel_hi:[1,0,1]
	v_pk_fma_f32 v[242:243], v[242:243], s[14:15], v[4:5] op_sel_hi:[1,0,1]
	v_cvt_pk_bf16_f32 v236, v236, v237
	v_cvt_pk_bf16_f32 v237, v238, v239
	v_cvt_pk_bf16_f32 v238, v240, v241
	v_cvt_pk_bf16_f32 v239, v242, v243
	s_add_u32 s66, s10, 0xb0100
	s_addc_u32 s67, s11, 0
	global_store_dwordx4 v147, v[236:239], s[66:67]
	s_and_b64 vcc, exec, s[6:7]
	s_mov_b32 s40, s28
	s_mov_b32 s38, s30
	s_mov_b64 s[44:45], s[36:37]
	s_mov_b64 s[42:43], s[34:35]
	s_cbranch_vccz .LBB0_843
	s_waitcnt vmcnt(0)
	s_cmpk_gt_u32 s3, 0xff
	s_cbranch_scc1 .LBB0_854
	s_barrier

.LBB0_1019:
	s_add_u32 s44, s68, 0xfff80080
	s_addc_u32 s45, s69, -1
	s_add_i32 s48, 0, 0x10000
	v_add_u32_e32 v144, s48, v141
	ds_read_b128 v[158:161], v144
	ds_read_b128 v[162:165], v144 offset:1024
	ds_read_b128 v[166:169], v144 offset:2048
	ds_read_b128 v[170:173], v144 offset:3072
	s_cmp_eq_u32 s47, 28
	s_cselect_b32 s95, s11, s45
	s_cselect_b32 s94, s43, s44
	s_cselect_b32 s45, s13, s7
	s_cselect_b32 s44, s46, s6
	v_lshl_add_u64 v[144:145], s[68:69], 0, v[136:137]
	s_add_i32 m0, s23, 0xc000
	ds_read_b128 v[174:177], v143
	ds_read_b128 v[178:181], v143 offset:1024
	ds_read_b128 v[182:185], v143 offset:2048
	ds_read_b128 v[186:189], v143 offset:3072
	ds_read_b128 v[206:209], v143 offset:4096
	ds_read_b128 v[210:213], v143 offset:5120
	ds_read_b128 v[214:217], v143 offset:6144
	ds_read_b128 v[218:221], v143 offset:7168
	global_load_lds_dwordx4 v[144:145], off
	v_lshl_add_u64 v[144:145], s[68:69], 0, v[138:139]
	s_add_i32 m0, s23, 0xe000
	s_nop 0
	global_load_lds_dwordx4 v[144:145], off
	s_waitcnt lgkmcnt(8)
	s_barrier
	s_waitcnt lgkmcnt(0)
	s_setprio 1
	s_waitcnt lgkmcnt(0)
	v_mfma_f32_16x16x32_bf16 v[126:129], v[158:161], v[174:177], v[126:129]
	v_mfma_f32_16x16x32_bf16 v[122:125], v[166:169], v[174:177], v[122:125]
	v_mfma_f32_16x16x32_bf16 v[118:121], v[158:161], v[182:185], v[118:121]
	v_mfma_f32_16x16x32_bf16 v[114:117], v[166:169], v[182:185], v[114:117]
	v_mfma_f32_16x16x32_bf16 v[102:105], v[158:161], v[206:209], v[102:105]
	v_mfma_f32_16x16x32_bf16 v[98:101], v[166:169], v[206:209], v[98:101]
	v_mfma_f32_16x16x32_bf16 v[86:89], v[158:161], v[214:217], v[86:89]
	v_mfma_f32_16x16x32_bf16 v[82:85], v[166:169], v[214:217], v[82:85]
	v_mfma_f32_16x16x32_bf16 v[126:129], v[162:165], v[178:181], v[126:129]
	v_mfma_f32_16x16x32_bf16 v[122:125], v[170:173], v[178:181], v[122:125]
	v_mfma_f32_16x16x32_bf16 v[118:121], v[162:165], v[186:189], v[118:121]
	v_mfma_f32_16x16x32_bf16 v[114:117], v[170:173], v[186:189], v[114:117]
	v_mfma_f32_16x16x32_bf16 v[102:105], v[162:165], v[210:213], v[102:105]
	v_mfma_f32_16x16x32_bf16 v[98:101], v[170:173], v[210:213], v[98:101]
	s_setprio 2
	s_barrier
	v_mfma_f32_16x16x32_bf16 v[86:89], v[162:165], v[218:221], v[86:89]
	v_mfma_f32_16x16x32_bf16 v[82:85], v[170:173], v[218:221], v[82:85]
	s_setprio 0
	s_add_i32 s50, 0, 0x14000
	v_add_u32_e32 v144, s50, v141
	s_add_i32 s48, s48, s22
	ds_read_b128 v[222:225], v144
	ds_read_b128 v[226:229], v144 offset:1024
	ds_read_b128 v[230:233], v144 offset:2048
	ds_read_b128 v[234:237], v144 offset:3072
	v_lshl_add_u64 v[144:145], s[44:45], 0, v[0:1]
	s_mov_b32 m0, s48
	v_lshl_add_u64 v[238:239], s[44:45], 0, v[130:131]
	global_load_lds_dwordx4 v[144:145], off
	s_add_i32 m0, s48, 0x2000
	s_nop 0
	global_load_lds_dwordx4 v[238:239], off
	s_barrier
	s_waitcnt lgkmcnt(0)
	s_setprio 1
	s_waitcnt lgkmcnt(0)
	v_mfma_f32_16x16x32_bf16 v[110:113], v[222:225], v[174:177], v[110:113]
	v_mfma_f32_16x16x32_bf16 v[106:109], v[230:233], v[174:177], v[106:109]
	v_mfma_f32_16x16x32_bf16 v[94:97], v[222:225], v[182:185], v[94:97]
	v_mfma_f32_16x16x32_bf16 v[90:93], v[230:233], v[182:185], v[90:93]
	v_mfma_f32_16x16x32_bf16 v[78:81], v[222:225], v[206:209], v[78:81]
	v_mfma_f32_16x16x32_bf16 v[74:77], v[230:233], v[206:209], v[74:77]
	v_mfma_f32_16x16x32_bf16 v[70:73], v[222:225], v[214:217], v[70:73]
	v_mfma_f32_16x16x32_bf16 v[66:69], v[230:233], v[214:217], v[66:69]
	v_mfma_f32_16x16x32_bf16 v[110:113], v[226:229], v[178:181], v[110:113]
	v_mfma_f32_16x16x32_bf16 v[106:109], v[234:237], v[178:181], v[106:109]
	v_mfma_f32_16x16x32_bf16 v[94:97], v[226:229], v[186:189], v[94:97]
	v_mfma_f32_16x16x32_bf16 v[90:93], v[234:237], v[186:189], v[90:93]
	v_mfma_f32_16x16x32_bf16 v[78:81], v[226:229], v[210:213], v[78:81]
	v_mfma_f32_16x16x32_bf16 v[74:77], v[234:237], v[210:213], v[74:77]
	s_setprio 2
	s_mov_b32 m0, s23
	v_lshl_add_u64 v[240:241], s[94:95], 0, v[134:135]
	s_barrier
	v_mfma_f32_16x16x32_bf16 v[70:73], v[226:229], v[218:221], v[70:73]
	v_mfma_f32_16x16x32_bf16 v[66:69], v[234:237], v[218:221], v[66:69]
	s_setprio 0
	ds_read_b128 v[174:177], v143 offset:16384
	ds_read_b128 v[178:181], v143 offset:17408
	ds_read_b128 v[182:185], v143 offset:18432
	ds_read_b128 v[186:189], v143 offset:19456
	ds_read_b128 v[206:209], v143 offset:20480
	ds_read_b128 v[210:213], v143 offset:21504
	ds_read_b128 v[214:217], v143 offset:22528
	ds_read_b128 v[218:221], v143 offset:23552
	global_load_lds_dwordx4 v[240:241], off
	v_lshl_add_u64 v[242:243], s[94:95], 0, v[132:133]
	s_mov_b32 m0, s26
	s_nop 0
	global_load_lds_dwordx4 v[242:243], off
	s_barrier
	s_waitcnt lgkmcnt(0)
	s_setprio 1
	s_waitcnt lgkmcnt(0)
	v_mfma_f32_16x16x32_bf16 v[62:65], v[158:161], v[174:177], v[62:65]
	v_mfma_f32_16x16x32_bf16 v[58:61], v[166:169], v[174:177], v[58:61]
	v_mfma_f32_16x16x32_bf16 v[54:57], v[158:161], v[182:185], v[54:57]
	v_mfma_f32_16x16x32_bf16 v[50:53], v[166:169], v[182:185], v[50:53]
	v_mfma_f32_16x16x32_bf16 v[38:41], v[158:161], v[206:209], v[38:41]
	v_mfma_f32_16x16x32_bf16 v[34:37], v[166:169], v[206:209], v[34:37]
	v_mfma_f32_16x16x32_bf16 v[22:25], v[158:161], v[214:217], v[22:25]
	v_mfma_f32_16x16x32_bf16 v[18:21], v[166:169], v[214:217], v[18:21]
	v_mfma_f32_16x16x32_bf16 v[62:65], v[162:165], v[178:181], v[62:65]
	v_mfma_f32_16x16x32_bf16 v[58:61], v[170:173], v[178:181], v[58:61]
	v_mfma_f32_16x16x32_bf16 v[54:57], v[162:165], v[186:189], v[54:57]
	v_mfma_f32_16x16x32_bf16 v[50:53], v[170:173], v[186:189], v[50:53]
	v_mfma_f32_16x16x32_bf16 v[38:41], v[162:165], v[210:213], v[38:41]
	v_mfma_f32_16x16x32_bf16 v[34:37], v[170:173], v[210:213], v[34:37]
	s_setprio 2
	s_barrier
	v_mfma_f32_16x16x32_bf16 v[22:25], v[162:165], v[218:221], v[22:25]
	v_mfma_f32_16x16x32_bf16 v[18:21], v[170:173], v[218:221], v[18:21]
	s_setprio 0
	s_add_u32 s48, s44, 0x80000
	s_addc_u32 s49, s45, 0
	s_add_i32 s50, s50, s22
	v_lshl_add_u64 v[158:159], s[48:49], 0, v[0:1]
	s_mov_b32 m0, s50
	s_nop 0
	global_load_lds_dwordx4 v[158:159], off
	v_lshl_add_u64 v[158:159], s[48:49], 0, v[130:131]
	s_add_i32 m0, s50, 0x2000
	s_nop 0
	global_load_lds_dwordx4 v[158:159], off
	s_waitcnt vmcnt(6)
	s_barrier
	s_setprio 1
	v_mfma_f32_16x16x32_bf16 v[46:49], v[222:225], v[174:177], v[46:49]
	v_mfma_f32_16x16x32_bf16 v[42:45], v[230:233], v[174:177], v[42:45]
	v_mfma_f32_16x16x32_bf16 v[30:33], v[222:225], v[182:185], v[30:33]
	v_mfma_f32_16x16x32_bf16 v[26:29], v[230:233], v[182:185], v[26:29]
	v_mfma_f32_16x16x32_bf16 v[14:17], v[222:225], v[206:209], v[14:17]
	v_mfma_f32_16x16x32_bf16 v[10:13], v[230:233], v[206:209], v[10:13]
	v_mfma_f32_16x16x32_bf16 v[6:9], v[222:225], v[214:217], v[6:9]
	v_mfma_f32_16x16x32_bf16 v[2:5], v[230:233], v[214:217], v[2:5]
	v_mfma_f32_16x16x32_bf16 v[46:49], v[226:229], v[178:181], v[46:49]
	v_mfma_f32_16x16x32_bf16 v[42:45], v[234:237], v[178:181], v[42:45]
	v_mfma_f32_16x16x32_bf16 v[30:33], v[226:229], v[186:189], v[30:33]
	v_mfma_f32_16x16x32_bf16 v[26:29], v[234:237], v[186:189], v[26:29]
	v_mfma_f32_16x16x32_bf16 v[14:17], v[226:229], v[210:213], v[14:17]
	v_mfma_f32_16x16x32_bf16 v[10:13], v[234:237], v[210:213], v[10:13]
	s_setprio 2
	s_add_i32 s50, 0, 0x18000
	v_add_u32_e32 v170, s50, v141
	s_barrier
	v_mfma_f32_16x16x32_bf16 v[6:9], v[226:229], v[218:221], v[6:9]
	v_mfma_f32_16x16x32_bf16 v[2:5], v[234:237], v[218:221], v[2:5]
	s_setprio 0
	ds_read_b128 v[158:161], v170
	ds_read_b128 v[162:165], v170 offset:1024
	ds_read_b128 v[166:169], v170 offset:2048
	ds_read_b128 v[170:173], v170 offset:3072
	s_add_u32 s48, s94, 0x80000
	s_addc_u32 s49, s95, 0
	s_mov_b32 m0, s27
	v_lshl_add_u64 v[222:223], s[48:49], 0, v[134:135]
	ds_read_b128 v[174:177], v143 offset:32768
	ds_read_b128 v[178:181], v143 offset:33792
	ds_read_b128 v[182:185], v143 offset:34816
	ds_read_b128 v[186:189], v143 offset:35840
	ds_read_b128 v[206:209], v143 offset:36864
	ds_read_b128 v[210:213], v143 offset:37888
	ds_read_b128 v[214:217], v143 offset:38912
	ds_read_b128 v[218:221], v143 offset:39936
	global_load_lds_dwordx4 v[222:223], off
	v_lshl_add_u64 v[222:223], s[48:49], 0, v[132:133]
	s_mov_b32 m0, s28
	s_nop 0
	global_load_lds_dwordx4 v[222:223], off
	s_waitcnt lgkmcnt(8)
	s_barrier
	s_waitcnt lgkmcnt(0)
	s_setprio 1
	s_waitcnt lgkmcnt(0)
	v_mfma_f32_16x16x32_bf16 v[126:129], v[158:161], v[174:177], v[126:129]
	v_mfma_f32_16x16x32_bf16 v[122:125], v[166:169], v[174:177], v[122:125]
	v_mfma_f32_16x16x32_bf16 v[118:121], v[158:161], v[182:185], v[118:121]
	v_mfma_f32_16x16x32_bf16 v[114:117], v[166:169], v[182:185], v[114:117]
	v_mfma_f32_16x16x32_bf16 v[102:105], v[158:161], v[206:209], v[102:105]
	v_mfma_f32_16x16x32_bf16 v[98:101], v[166:169], v[206:209], v[98:101]
	v_mfma_f32_16x16x32_bf16 v[86:89], v[158:161], v[214:217], v[86:89]
	v_mfma_f32_16x16x32_bf16 v[82:85], v[166:169], v[214:217], v[82:85]
	v_mfma_f32_16x16x32_bf16 v[126:129], v[162:165], v[178:181], v[126:129]
	v_mfma_f32_16x16x32_bf16 v[122:125], v[170:173], v[178:181], v[122:125]
	v_mfma_f32_16x16x32_bf16 v[118:121], v[162:165], v[186:189], v[118:121]
	v_mfma_f32_16x16x32_bf16 v[114:117], v[170:173], v[186:189], v[114:117]
	v_mfma_f32_16x16x32_bf16 v[102:105], v[162:165], v[210:213], v[102:105]
	v_mfma_f32_16x16x32_bf16 v[98:101], v[170:173], v[210:213], v[98:101]
	s_setprio 2
	s_barrier
	v_mfma_f32_16x16x32_bf16 v[86:89], v[162:165], v[218:221], v[86:89]
	v_mfma_f32_16x16x32_bf16 v[82:85], v[170:173], v[218:221], v[82:85]
	s_setprio 0
	s_add_i32 s48, 0, 0x1c000
	s_add_i32 s49, s50, s22
	v_add_u32_e32 v205, s48, v141
	v_lshl_add_u64 v[144:145], v[144:145], 0, s[62:63]
	s_mov_b32 m0, s49
	ds_read_b128 v[222:225], v205
	ds_read_b128 v[226:229], v205 offset:1024
	ds_read_b128 v[230:233], v205 offset:2048
	ds_read_b128 v[234:237], v205 offset:3072
	global_load_lds_dwordx4 v[144:145], off
	v_lshl_add_u64 v[144:145], v[238:239], 0, s[62:63]
	s_add_i32 m0, s49, 0x2000
	s_nop 0
	global_load_lds_dwordx4 v[144:145], off
	s_barrier
	s_waitcnt lgkmcnt(0)
	s_setprio 1
	s_waitcnt lgkmcnt(0)
	v_mfma_f32_16x16x32_bf16 v[110:113], v[222:225], v[174:177], v[110:113]
	v_mfma_f32_16x16x32_bf16 v[106:109], v[230:233], v[174:177], v[106:109]
	v_mfma_f32_16x16x32_bf16 v[94:97], v[222:225], v[182:185], v[94:97]
	v_mfma_f32_16x16x32_bf16 v[90:93], v[230:233], v[182:185], v[90:93]
	v_mfma_f32_16x16x32_bf16 v[78:81], v[222:225], v[206:209], v[78:81]
	v_mfma_f32_16x16x32_bf16 v[74:77], v[230:233], v[206:209], v[74:77]
	v_mfma_f32_16x16x32_bf16 v[70:73], v[222:225], v[214:217], v[70:73]
	v_mfma_f32_16x16x32_bf16 v[66:69], v[230:233], v[214:217], v[66:69]
	v_mfma_f32_16x16x32_bf16 v[110:113], v[226:229], v[178:181], v[110:113]
	v_mfma_f32_16x16x32_bf16 v[106:109], v[234:237], v[178:181], v[106:109]
	v_mfma_f32_16x16x32_bf16 v[94:97], v[226:229], v[186:189], v[94:97]
	v_mfma_f32_16x16x32_bf16 v[90:93], v[234:237], v[186:189], v[90:93]
	v_mfma_f32_16x16x32_bf16 v[78:81], v[226:229], v[210:213], v[78:81]
	v_mfma_f32_16x16x32_bf16 v[74:77], v[234:237], v[210:213], v[74:77]
	s_setprio 2
	s_mov_b32 m0, s36
	v_lshl_add_u64 v[144:145], v[240:241], 0, s[62:63]
	s_barrier
	v_mfma_f32_16x16x32_bf16 v[70:73], v[226:229], v[218:221], v[70:73]
	v_mfma_f32_16x16x32_bf16 v[66:69], v[234:237], v[218:221], v[66:69]
	s_setprio 0
	ds_read_b128 v[174:177], v143 offset:49152
	ds_read_b128 v[178:181], v143 offset:50176
	ds_read_b128 v[182:185], v143 offset:51200
	ds_read_b128 v[186:189], v143 offset:52224
	ds_read_b128 v[206:209], v143 offset:53248
	ds_read_b128 v[210:213], v143 offset:54272
	ds_read_b128 v[214:217], v143 offset:55296
	ds_read_b128 v[218:221], v143 offset:56320
	global_load_lds_dwordx4 v[144:145], off
	v_lshl_add_u64 v[144:145], v[242:243], 0, s[62:63]
	s_mov_b32 m0, s37
	s_nop 0
	global_load_lds_dwordx4 v[144:145], off
	s_barrier
	s_waitcnt lgkmcnt(0)
	s_setprio 1
	s_waitcnt lgkmcnt(0)
	v_mfma_f32_16x16x32_bf16 v[62:65], v[158:161], v[174:177], v[62:65]
	v_mfma_f32_16x16x32_bf16 v[58:61], v[166:169], v[174:177], v[58:61]
	v_mfma_f32_16x16x32_bf16 v[54:57], v[158:161], v[182:185], v[54:57]
	v_mfma_f32_16x16x32_bf16 v[50:53], v[166:169], v[182:185], v[50:53]
	v_mfma_f32_16x16x32_bf16 v[38:41], v[158:161], v[206:209], v[38:41]
	v_mfma_f32_16x16x32_bf16 v[34:37], v[166:169], v[206:209], v[34:37]
	v_mfma_f32_16x16x32_bf16 v[22:25], v[158:161], v[214:217], v[22:25]
	v_mfma_f32_16x16x32_bf16 v[18:21], v[166:169], v[214:217], v[18:21]
	v_mfma_f32_16x16x32_bf16 v[62:65], v[162:165], v[178:181], v[62:65]
	v_mfma_f32_16x16x32_bf16 v[58:61], v[170:173], v[178:181], v[58:61]
	v_mfma_f32_16x16x32_bf16 v[54:57], v[162:165], v[186:189], v[54:57]
	v_mfma_f32_16x16x32_bf16 v[50:53], v[170:173], v[186:189], v[50:53]
	v_mfma_f32_16x16x32_bf16 v[38:41], v[162:165], v[210:213], v[38:41]
	v_mfma_f32_16x16x32_bf16 v[34:37], v[170:173], v[210:213], v[34:37]
	s_setprio 2
	s_barrier
	v_mfma_f32_16x16x32_bf16 v[22:25], v[162:165], v[218:221], v[22:25]
	v_mfma_f32_16x16x32_bf16 v[18:21], v[170:173], v[218:221], v[18:21]
	s_setprio 0
	s_add_u32 s44, s44, 0x80080
	s_addc_u32 s45, s45, 0
	s_add_i32 s48, s48, s22
	v_lshl_add_u64 v[144:145], s[44:45], 0, v[0:1]
	s_mov_b32 m0, s48
	s_nop 0
	global_load_lds_dwordx4 v[144:145], off
	v_lshl_add_u64 v[144:145], s[44:45], 0, v[130:131]
	s_add_i32 m0, s48, 0x2000
	s_nop 0
	global_load_lds_dwordx4 v[144:145], off
	s_waitcnt vmcnt(6)
	s_barrier
	s_setprio 1
	v_mfma_f32_16x16x32_bf16 v[46:49], v[222:225], v[174:177], v[46:49]
	v_mfma_f32_16x16x32_bf16 v[42:45], v[230:233], v[174:177], v[42:45]
	v_mfma_f32_16x16x32_bf16 v[30:33], v[222:225], v[182:185], v[30:33]
	v_mfma_f32_16x16x32_bf16 v[26:29], v[230:233], v[182:185], v[26:29]
	v_mfma_f32_16x16x32_bf16 v[14:17], v[222:225], v[206:209], v[14:17]
	v_mfma_f32_16x16x32_bf16 v[10:13], v[230:233], v[206:209], v[10:13]
	v_mfma_f32_16x16x32_bf16 v[6:9], v[222:225], v[214:217], v[6:9]
	v_mfma_f32_16x16x32_bf16 v[2:5], v[230:233], v[214:217], v[2:5]
	v_mfma_f32_16x16x32_bf16 v[46:49], v[226:229], v[178:181], v[46:49]
	v_mfma_f32_16x16x32_bf16 v[42:45], v[234:237], v[178:181], v[42:45]
	v_mfma_f32_16x16x32_bf16 v[30:33], v[226:229], v[186:189], v[30:33]
	v_mfma_f32_16x16x32_bf16 v[26:29], v[234:237], v[186:189], v[26:29]
	v_mfma_f32_16x16x32_bf16 v[14:17], v[226:229], v[210:213], v[14:17]
	v_mfma_f32_16x16x32_bf16 v[10:13], v[234:237], v[210:213], v[10:13]
	s_setprio 2
	s_add_i32 s47, s47, 2
	s_add_u32 s68, s68, 0x100
	s_addc_u32 s69, s69, 0
	s_add_u32 s6, s6, 0x100
	s_addc_u32 s7, s7, 0
	s_cmp_gt_u32 s47, 29
	s_barrier
	v_mfma_f32_16x16x32_bf16 v[6:9], v[226:229], v[218:221], v[6:9]
	v_mfma_f32_16x16x32_bf16 v[2:5], v[234:237], v[218:221], v[2:5]
	s_setprio 0
	s_cbranch_scc0 .LBB0_1019
	s_lshl_b32 s6, s42, 8
	s_and_b32 s6, s6, 0x3f00
	v_add_u32_e32 v160, s6, v140
	s_mul_hi_i32 s6, s41, 0x2aaaaaab
	s_lshr_b32 s7, s6, 31
	s_lshr_b32 s6, s6, 2
	s_add_i32 s6, s6, s7
	s_mul_i32 s6, s6, 24
	s_sub_i32 s6, s41, s6
	v_lshl_or_b32 v144, s6, 8, v142
	v_ashrrev_i32_e32 v145, 31, v144
	v_lshl_add_u64 v[144:145], v[144:145], 1, s[84:85]
	v_cvt_pk_bf16_f32 v70, v70, v71
	v_cvt_pk_bf16_f32 v71, v72, v73
	v_cvt_pk_bf16_f32 v72, v66, v67
	v_add_u32_e32 v66, 0x80, v160
	v_mad_i64_i32 v[158:159], s[6:7], v160, s34, v[144:145]
	v_cvt_pk_bf16_f32 v110, v110, v111
	v_cvt_pk_bf16_f32 v111, v112, v113
	v_cvt_pk_bf16_f32 v112, v106, v107
	v_cvt_pk_bf16_f32 v113, v108, v109
	v_or_b32_e32 v106, 16, v160
	v_mad_i64_i32 v[66:67], s[6:7], v66, s34, v[144:145]
	v_cvt_pk_bf16_f32 v46, v46, v47
	v_cvt_pk_bf16_f32 v47, v48, v49
	v_cvt_pk_bf16_f32 v48, v42, v43
	v_cvt_pk_bf16_f32 v49, v44, v45
	v_add_u32_e32 v42, 0x90, v160
	global_store_dwordx4 v[158:159], v[110:113], off offset:256
	v_cvt_pk_bf16_f32 v94, v94, v95
	v_cvt_pk_bf16_f32 v95, v96, v97
	v_mad_i64_i32 v[110:111], s[6:7], v106, s34, v[144:145]
	v_cvt_pk_bf16_f32 v96, v90, v91
	v_cvt_pk_bf16_f32 v97, v92, v93
	v_or_b32_e32 v90, 32, v160
	global_store_dwordx4 v[66:67], v[46:49], off offset:256
	v_cvt_pk_bf16_f32 v30, v30, v31
	v_cvt_pk_bf16_f32 v31, v32, v33
	v_mad_i64_i32 v[46:47], s[6:7], v42, s34, v[144:145]
	v_cvt_pk_bf16_f32 v32, v26, v27
	v_cvt_pk_bf16_f32 v33, v28, v29
	v_add_u32_e32 v26, 0xa0, v160
	global_store_dwordx4 v[110:111], v[94:97], off offset:256
	v_cvt_pk_bf16_f32 v78, v78, v79
	v_cvt_pk_bf16_f32 v79, v80, v81
	v_mad_i64_i32 v[94:95], s[6:7], v90, s34, v[144:145]
	v_cvt_pk_bf16_f32 v80, v74, v75
	v_cvt_pk_bf16_f32 v81, v76, v77
	v_or_b32_e32 v74, 48, v160
	global_store_dwordx4 v[46:47], v[30:33], off offset:256
	v_cvt_pk_bf16_f32 v14, v14, v15
	v_cvt_pk_bf16_f32 v15, v16, v17
	v_mad_i64_i32 v[30:31], s[6:7], v26, s34, v[144:145]
	v_cvt_pk_bf16_f32 v16, v10, v11
	v_cvt_pk_bf16_f32 v17, v12, v13
	v_add_u32_e32 v10, 0xb0, v160
	global_store_dwordx4 v[94:95], v[78:81], off offset:256
	global_store_dwordx4 v[30:31], v[14:17], off offset:256
	v_cvt_pk_bf16_f32 v126, v126, v127
	v_mad_i64_i32 v[78:79], s[6:7], v74, s34, v[144:145]
	v_mad_i64_i32 v[14:15], s[6:7], v10, s34, v[144:145]
	v_cvt_pk_bf16_f32 v127, v128, v129
	v_cvt_pk_bf16_f32 v128, v122, v123
	v_cvt_pk_bf16_f32 v129, v124, v125
	v_cvt_pk_bf16_f32 v106, v118, v119
	v_cvt_pk_bf16_f32 v107, v120, v121
	v_cvt_pk_bf16_f32 v108, v114, v115
	v_cvt_pk_bf16_f32 v109, v116, v117
	v_cvt_pk_bf16_f32 v90, v102, v103
	v_cvt_pk_bf16_f32 v91, v104, v105
	v_cvt_pk_bf16_f32 v92, v98, v99
	v_cvt_pk_bf16_f32 v93, v100, v101
	v_cvt_pk_bf16_f32 v74, v86, v87
	v_cvt_pk_bf16_f32 v75, v88, v89
	v_cvt_pk_bf16_f32 v76, v82, v83
	v_cvt_pk_bf16_f32 v77, v84, v85
	v_cvt_pk_bf16_f32 v73, v68, v69
	v_cvt_pk_bf16_f32 v62, v62, v63
	v_cvt_pk_bf16_f32 v63, v64, v65
	v_cvt_pk_bf16_f32 v64, v58, v59
	v_cvt_pk_bf16_f32 v65, v60, v61
	v_cvt_pk_bf16_f32 v42, v54, v55
	v_cvt_pk_bf16_f32 v43, v56, v57
	v_cvt_pk_bf16_f32 v44, v50, v51
	v_cvt_pk_bf16_f32 v45, v52, v53
	v_cvt_pk_bf16_f32 v26, v38, v39
	v_cvt_pk_bf16_f32 v27, v40, v41
	v_cvt_pk_bf16_f32 v28, v34, v35
	v_cvt_pk_bf16_f32 v29, v36, v37
	v_cvt_pk_bf16_f32 v10, v22, v23
	v_cvt_pk_bf16_f32 v11, v24, v25
	v_cvt_pk_bf16_f32 v12, v18, v19
	v_cvt_pk_bf16_f32 v13, v20, v21
	v_cvt_pk_bf16_f32 v6, v6, v7
	v_cvt_pk_bf16_f32 v7, v8, v9
	v_cvt_pk_bf16_f32 v8, v2, v3
	v_cvt_pk_bf16_f32 v9, v4, v5
	s_and_b64 vcc, exec, s[8:9]
	s_mov_b32 s41, s12
	s_mov_b32 s42, s10
	s_mov_b64 s[94:95], s[64:65]
	s_mov_b64 s[6:7], s[14:15]
	global_store_dwordx4 v[158:159], v[126:129], off
	global_store_dwordx4 v[110:111], v[106:109], off
	global_store_dwordx4 v[94:95], v[90:93], off
	global_store_dwordx4 v[78:79], v[74:77], off
	global_store_dwordx4 v[78:79], v[70:73], off offset:256
	global_store_dwordx4 v[66:67], v[62:65], off
	global_store_dwordx4 v[46:47], v[42:45], off
	global_store_dwordx4 v[30:31], v[26:29], off
	global_store_dwordx4 v[14:15], v[10:13], off
	global_store_dwordx4 v[14:15], v[6:9], off offset:256
	s_cbranch_vccz .LBB0_1016
	s_waitcnt vmcnt(0)
	s_cmpk_gt_u32 s5, 0xff
	s_cbranch_scc1 .LBB0_1023
	s_barrier

.LBB0_1256:
	s_add_u32 s44, s64, 0xfff80080
	s_addc_u32 s45, s65, -1
	s_add_i32 s48, 0, 0x10000
	v_add_u32_e32 v102, s48, v187
	ds_read_b128 v[90:93], v102
	ds_read_b128 v[94:97], v102 offset:1024
	ds_read_b128 v[98:101], v102 offset:2048
	ds_read_b128 v[102:105], v102 offset:3072
	s_cmp_eq_u32 s47, 28
	s_cselect_b32 s69, s4, s45
	s_cselect_b32 s68, s5, s44
	s_cselect_b32 s45, s6, s19
	s_cselect_b32 s44, s7, s18
	v_lshl_add_u64 v[184:185], s[64:65], 0, v[164:165]
	s_add_i32 m0, s27, 0xc000
	ds_read_b128 v[168:171], v189
	ds_read_b128 v[172:175], v189 offset:1024
	ds_read_b128 v[176:179], v189 offset:2048
	ds_read_b128 v[180:183], v189 offset:3072
	ds_read_b128 v[206:209], v189 offset:4096
	ds_read_b128 v[210:213], v189 offset:5120
	ds_read_b128 v[214:217], v189 offset:6144
	ds_read_b128 v[218:221], v189 offset:7168
	global_load_lds_dwordx4 v[184:185], off
	v_lshl_add_u64 v[184:185], s[64:65], 0, v[166:167]
	s_add_i32 m0, s27, 0xe000
	s_nop 0
	global_load_lds_dwordx4 v[184:185], off
	s_waitcnt lgkmcnt(8)
	s_barrier
	s_waitcnt lgkmcnt(0)
	s_setprio 1
	s_waitcnt lgkmcnt(0)
	v_mfma_f32_16x16x32_bf16 v[142:145], v[90:93], v[168:171], v[142:145]
	v_mfma_f32_16x16x32_bf16 v[138:141], v[98:101], v[168:171], v[138:141]
	v_mfma_f32_16x16x32_bf16 v[134:137], v[90:93], v[176:179], v[134:137]
	v_mfma_f32_16x16x32_bf16 v[130:133], v[98:101], v[176:179], v[130:133]
	v_mfma_f32_16x16x32_bf16 v[126:129], v[90:93], v[206:209], v[126:129]
	v_mfma_f32_16x16x32_bf16 v[122:125], v[98:101], v[206:209], v[122:125]
	v_mfma_f32_16x16x32_bf16 v[118:121], v[90:93], v[214:217], v[118:121]
	v_mfma_f32_16x16x32_bf16 v[114:117], v[98:101], v[214:217], v[114:117]
	v_mfma_f32_16x16x32_bf16 v[142:145], v[94:97], v[172:175], v[142:145]
	v_mfma_f32_16x16x32_bf16 v[138:141], v[102:105], v[172:175], v[138:141]
	v_mfma_f32_16x16x32_bf16 v[134:137], v[94:97], v[180:183], v[134:137]
	v_mfma_f32_16x16x32_bf16 v[130:133], v[102:105], v[180:183], v[130:133]
	v_mfma_f32_16x16x32_bf16 v[126:129], v[94:97], v[210:213], v[126:129]
	v_mfma_f32_16x16x32_bf16 v[122:125], v[102:105], v[210:213], v[122:125]
	s_setprio 2
	s_barrier
	v_mfma_f32_16x16x32_bf16 v[118:121], v[94:97], v[218:221], v[118:121]
	v_mfma_f32_16x16x32_bf16 v[114:117], v[102:105], v[218:221], v[114:117]
	s_setprio 0
	s_add_i32 s50, 0, 0x14000
	v_add_u32_e32 v184, s50, v187
	s_add_i32 s48, s48, s22
	ds_read_b128 v[222:225], v184
	ds_read_b128 v[226:229], v184 offset:1024
	ds_read_b128 v[230:233], v184 offset:2048
	ds_read_b128 v[234:237], v184 offset:3072
	v_lshl_add_u64 v[184:185], s[44:45], 0, v[0:1]
	s_mov_b32 m0, s48
	v_lshl_add_u64 v[238:239], s[44:45], 0, v[158:159]
	global_load_lds_dwordx4 v[184:185], off
	s_add_i32 m0, s48, 0x2000
	s_nop 0
	global_load_lds_dwordx4 v[238:239], off
	s_barrier
	s_waitcnt lgkmcnt(0)
	s_setprio 1
	s_waitcnt lgkmcnt(0)
	v_mfma_f32_16x16x32_bf16 v[62:65], v[222:225], v[168:171], v[62:65]
	v_mfma_f32_16x16x32_bf16 v[58:61], v[230:233], v[168:171], v[58:61]
	v_mfma_f32_16x16x32_bf16 v[54:57], v[222:225], v[176:179], v[54:57]
	v_mfma_f32_16x16x32_bf16 v[50:53], v[230:233], v[176:179], v[50:53]
	v_mfma_f32_16x16x32_bf16 v[46:49], v[222:225], v[206:209], v[46:49]
	v_mfma_f32_16x16x32_bf16 v[42:45], v[230:233], v[206:209], v[42:45]
	v_mfma_f32_16x16x32_bf16 v[38:41], v[222:225], v[214:217], v[38:41]
	v_mfma_f32_16x16x32_bf16 v[34:37], v[230:233], v[214:217], v[34:37]
	v_mfma_f32_16x16x32_bf16 v[62:65], v[226:229], v[172:175], v[62:65]
	v_mfma_f32_16x16x32_bf16 v[58:61], v[234:237], v[172:175], v[58:61]
	v_mfma_f32_16x16x32_bf16 v[54:57], v[226:229], v[180:183], v[54:57]
	v_mfma_f32_16x16x32_bf16 v[50:53], v[234:237], v[180:183], v[50:53]
	v_mfma_f32_16x16x32_bf16 v[46:49], v[226:229], v[210:213], v[46:49]
	v_mfma_f32_16x16x32_bf16 v[42:45], v[234:237], v[210:213], v[42:45]
	s_setprio 2
	s_mov_b32 m0, s27
	v_lshl_add_u64 v[240:241], s[68:69], 0, v[162:163]
	s_barrier
	v_mfma_f32_16x16x32_bf16 v[38:41], v[226:229], v[218:221], v[38:41]
	v_mfma_f32_16x16x32_bf16 v[34:37], v[234:237], v[218:221], v[34:37]
	s_setprio 0
	ds_read_b128 v[168:171], v189 offset:16384
	ds_read_b128 v[172:175], v189 offset:17408
	ds_read_b128 v[176:179], v189 offset:18432
	ds_read_b128 v[180:183], v189 offset:19456
	ds_read_b128 v[206:209], v189 offset:20480
	ds_read_b128 v[210:213], v189 offset:21504
	ds_read_b128 v[214:217], v189 offset:22528
	ds_read_b128 v[218:221], v189 offset:23552
	global_load_lds_dwordx4 v[240:241], off
	v_lshl_add_u64 v[242:243], s[68:69], 0, v[160:161]
	s_mov_b32 m0, s28
	s_nop 0
	global_load_lds_dwordx4 v[242:243], off
	s_barrier
	s_waitcnt lgkmcnt(0)
	s_setprio 1
	s_waitcnt lgkmcnt(0)
	v_mfma_f32_16x16x32_bf16 v[110:113], v[90:93], v[168:171], v[110:113]
	v_mfma_f32_16x16x32_bf16 v[106:109], v[98:101], v[168:171], v[106:109]
	v_mfma_f32_16x16x32_bf16 v[86:89], v[90:93], v[176:179], v[86:89]
	v_mfma_f32_16x16x32_bf16 v[82:85], v[98:101], v[176:179], v[82:85]
	v_mfma_f32_16x16x32_bf16 v[78:81], v[90:93], v[206:209], v[78:81]
	v_mfma_f32_16x16x32_bf16 v[74:77], v[98:101], v[206:209], v[74:77]
	v_mfma_f32_16x16x32_bf16 v[70:73], v[90:93], v[214:217], v[70:73]
	v_mfma_f32_16x16x32_bf16 v[66:69], v[98:101], v[214:217], v[66:69]
	v_mfma_f32_16x16x32_bf16 v[110:113], v[94:97], v[172:175], v[110:113]
	v_mfma_f32_16x16x32_bf16 v[106:109], v[102:105], v[172:175], v[106:109]
	v_mfma_f32_16x16x32_bf16 v[86:89], v[94:97], v[180:183], v[86:89]
	v_mfma_f32_16x16x32_bf16 v[82:85], v[102:105], v[180:183], v[82:85]
	v_mfma_f32_16x16x32_bf16 v[78:81], v[94:97], v[210:213], v[78:81]
	v_mfma_f32_16x16x32_bf16 v[74:77], v[102:105], v[210:213], v[74:77]
	s_setprio 2
	s_barrier
	v_mfma_f32_16x16x32_bf16 v[70:73], v[94:97], v[218:221], v[70:73]
	v_mfma_f32_16x16x32_bf16 v[66:69], v[102:105], v[218:221], v[66:69]
	s_setprio 0
	s_add_u32 s48, s44, 0x80000
	s_addc_u32 s49, s45, 0
	s_add_i32 s50, s50, s22
	v_lshl_add_u64 v[90:91], s[48:49], 0, v[0:1]
	s_mov_b32 m0, s50
	s_nop 0
	global_load_lds_dwordx4 v[90:91], off
	v_lshl_add_u64 v[90:91], s[48:49], 0, v[158:159]
	s_add_i32 m0, s50, 0x2000
	s_nop 0
	global_load_lds_dwordx4 v[90:91], off
	s_waitcnt vmcnt(6)
	s_barrier
	s_setprio 1
	v_mfma_f32_16x16x32_bf16 v[30:33], v[222:225], v[168:171], v[30:33]
	v_mfma_f32_16x16x32_bf16 v[26:29], v[230:233], v[168:171], v[26:29]
	v_mfma_f32_16x16x32_bf16 v[22:25], v[222:225], v[176:179], v[22:25]
	v_mfma_f32_16x16x32_bf16 v[18:21], v[230:233], v[176:179], v[18:21]
	v_mfma_f32_16x16x32_bf16 v[14:17], v[222:225], v[206:209], v[14:17]
	v_mfma_f32_16x16x32_bf16 v[10:13], v[230:233], v[206:209], v[10:13]
	v_mfma_f32_16x16x32_bf16 v[6:9], v[222:225], v[214:217], v[6:9]
	v_mfma_f32_16x16x32_bf16 v[2:5], v[230:233], v[214:217], v[2:5]
	v_mfma_f32_16x16x32_bf16 v[30:33], v[226:229], v[172:175], v[30:33]
	v_mfma_f32_16x16x32_bf16 v[26:29], v[234:237], v[172:175], v[26:29]
	v_mfma_f32_16x16x32_bf16 v[22:25], v[226:229], v[180:183], v[22:25]
	v_mfma_f32_16x16x32_bf16 v[18:21], v[234:237], v[180:183], v[18:21]
	v_mfma_f32_16x16x32_bf16 v[14:17], v[226:229], v[210:213], v[14:17]
	v_mfma_f32_16x16x32_bf16 v[10:13], v[234:237], v[210:213], v[10:13]
	s_setprio 2
	s_add_i32 s50, 0, 0x18000
	v_add_u32_e32 v102, s50, v187
	s_barrier
	v_mfma_f32_16x16x32_bf16 v[6:9], v[226:229], v[218:221], v[6:9]
	v_mfma_f32_16x16x32_bf16 v[2:5], v[234:237], v[218:221], v[2:5]
	s_setprio 0
	ds_read_b128 v[90:93], v102
	ds_read_b128 v[94:97], v102 offset:1024
	ds_read_b128 v[98:101], v102 offset:2048
	ds_read_b128 v[102:105], v102 offset:3072
	s_add_u32 s48, s68, 0x80000
	s_addc_u32 s49, s69, 0
	s_mov_b32 m0, s36
	v_lshl_add_u64 v[222:223], s[48:49], 0, v[162:163]
	ds_read_b128 v[168:171], v189 offset:32768
	ds_read_b128 v[172:175], v189 offset:33792
	ds_read_b128 v[176:179], v189 offset:34816
	ds_read_b128 v[180:183], v189 offset:35840
	ds_read_b128 v[206:209], v189 offset:36864
	ds_read_b128 v[210:213], v189 offset:37888
	ds_read_b128 v[214:217], v189 offset:38912
	ds_read_b128 v[218:221], v189 offset:39936
	global_load_lds_dwordx4 v[222:223], off
	v_lshl_add_u64 v[222:223], s[48:49], 0, v[160:161]
	s_mov_b32 m0, s37
	s_nop 0
	global_load_lds_dwordx4 v[222:223], off
	s_waitcnt lgkmcnt(8)
	s_barrier
	s_waitcnt lgkmcnt(0)
	s_setprio 1
	s_waitcnt lgkmcnt(0)
	v_mfma_f32_16x16x32_bf16 v[142:145], v[90:93], v[168:171], v[142:145]
	v_mfma_f32_16x16x32_bf16 v[138:141], v[98:101], v[168:171], v[138:141]
	v_mfma_f32_16x16x32_bf16 v[134:137], v[90:93], v[176:179], v[134:137]
	v_mfma_f32_16x16x32_bf16 v[130:133], v[98:101], v[176:179], v[130:133]
	v_mfma_f32_16x16x32_bf16 v[126:129], v[90:93], v[206:209], v[126:129]
	v_mfma_f32_16x16x32_bf16 v[122:125], v[98:101], v[206:209], v[122:125]
	v_mfma_f32_16x16x32_bf16 v[118:121], v[90:93], v[214:217], v[118:121]
	v_mfma_f32_16x16x32_bf16 v[114:117], v[98:101], v[214:217], v[114:117]
	v_mfma_f32_16x16x32_bf16 v[142:145], v[94:97], v[172:175], v[142:145]
	v_mfma_f32_16x16x32_bf16 v[138:141], v[102:105], v[172:175], v[138:141]
	v_mfma_f32_16x16x32_bf16 v[134:137], v[94:97], v[180:183], v[134:137]
	v_mfma_f32_16x16x32_bf16 v[130:133], v[102:105], v[180:183], v[130:133]
	v_mfma_f32_16x16x32_bf16 v[126:129], v[94:97], v[210:213], v[126:129]
	v_mfma_f32_16x16x32_bf16 v[122:125], v[102:105], v[210:213], v[122:125]
	s_setprio 2
	s_barrier
	v_mfma_f32_16x16x32_bf16 v[118:121], v[94:97], v[218:221], v[118:121]
	v_mfma_f32_16x16x32_bf16 v[114:117], v[102:105], v[218:221], v[114:117]
	s_setprio 0
	s_add_i32 s48, 0, 0x1c000
	s_add_i32 s49, s50, s22
	v_add_u32_e32 v205, s48, v187
	v_lshl_add_u64 v[184:185], v[184:185], 0, s[62:63]
	s_mov_b32 m0, s49
	ds_read_b128 v[222:225], v205
	ds_read_b128 v[226:229], v205 offset:1024
	ds_read_b128 v[230:233], v205 offset:2048
	ds_read_b128 v[234:237], v205 offset:3072
	global_load_lds_dwordx4 v[184:185], off
	v_lshl_add_u64 v[184:185], v[238:239], 0, s[62:63]
	s_add_i32 m0, s49, 0x2000
	s_nop 0
	global_load_lds_dwordx4 v[184:185], off
	s_barrier
	s_waitcnt lgkmcnt(0)
	s_setprio 1
	s_waitcnt lgkmcnt(0)
	v_mfma_f32_16x16x32_bf16 v[62:65], v[222:225], v[168:171], v[62:65]
	v_mfma_f32_16x16x32_bf16 v[58:61], v[230:233], v[168:171], v[58:61]
	v_mfma_f32_16x16x32_bf16 v[54:57], v[222:225], v[176:179], v[54:57]
	v_mfma_f32_16x16x32_bf16 v[50:53], v[230:233], v[176:179], v[50:53]
	v_mfma_f32_16x16x32_bf16 v[46:49], v[222:225], v[206:209], v[46:49]
	v_mfma_f32_16x16x32_bf16 v[42:45], v[230:233], v[206:209], v[42:45]
	v_mfma_f32_16x16x32_bf16 v[38:41], v[222:225], v[214:217], v[38:41]
	v_mfma_f32_16x16x32_bf16 v[34:37], v[230:233], v[214:217], v[34:37]
	v_mfma_f32_16x16x32_bf16 v[62:65], v[226:229], v[172:175], v[62:65]
	v_mfma_f32_16x16x32_bf16 v[58:61], v[234:237], v[172:175], v[58:61]
	v_mfma_f32_16x16x32_bf16 v[54:57], v[226:229], v[180:183], v[54:57]
	v_mfma_f32_16x16x32_bf16 v[50:53], v[234:237], v[180:183], v[50:53]
	v_mfma_f32_16x16x32_bf16 v[46:49], v[226:229], v[210:213], v[46:49]
	v_mfma_f32_16x16x32_bf16 v[42:45], v[234:237], v[210:213], v[42:45]
	s_setprio 2
	s_mov_b32 m0, s40
	v_lshl_add_u64 v[184:185], v[240:241], 0, s[62:63]
	s_barrier
	v_mfma_f32_16x16x32_bf16 v[38:41], v[226:229], v[218:221], v[38:41]
	v_mfma_f32_16x16x32_bf16 v[34:37], v[234:237], v[218:221], v[34:37]
	s_setprio 0
	ds_read_b128 v[168:171], v189 offset:49152
	ds_read_b128 v[172:175], v189 offset:50176
	ds_read_b128 v[176:179], v189 offset:51200
	ds_read_b128 v[180:183], v189 offset:52224
	ds_read_b128 v[206:209], v189 offset:53248
	ds_read_b128 v[210:213], v189 offset:54272
	ds_read_b128 v[214:217], v189 offset:55296
	ds_read_b128 v[218:221], v189 offset:56320
	global_load_lds_dwordx4 v[184:185], off
	v_lshl_add_u64 v[184:185], v[242:243], 0, s[62:63]
	s_mov_b32 m0, s41
	s_nop 0
	global_load_lds_dwordx4 v[184:185], off
	s_barrier
	s_waitcnt lgkmcnt(0)
	s_setprio 1
	s_waitcnt lgkmcnt(0)
	v_mfma_f32_16x16x32_bf16 v[110:113], v[90:93], v[168:171], v[110:113]
	v_mfma_f32_16x16x32_bf16 v[106:109], v[98:101], v[168:171], v[106:109]
	v_mfma_f32_16x16x32_bf16 v[86:89], v[90:93], v[176:179], v[86:89]
	v_mfma_f32_16x16x32_bf16 v[82:85], v[98:101], v[176:179], v[82:85]
	v_mfma_f32_16x16x32_bf16 v[78:81], v[90:93], v[206:209], v[78:81]
	v_mfma_f32_16x16x32_bf16 v[74:77], v[98:101], v[206:209], v[74:77]
	v_mfma_f32_16x16x32_bf16 v[70:73], v[90:93], v[214:217], v[70:73]
	v_mfma_f32_16x16x32_bf16 v[66:69], v[98:101], v[214:217], v[66:69]
	v_mfma_f32_16x16x32_bf16 v[110:113], v[94:97], v[172:175], v[110:113]
	v_mfma_f32_16x16x32_bf16 v[106:109], v[102:105], v[172:175], v[106:109]
	v_mfma_f32_16x16x32_bf16 v[86:89], v[94:97], v[180:183], v[86:89]
	v_mfma_f32_16x16x32_bf16 v[82:85], v[102:105], v[180:183], v[82:85]
	v_mfma_f32_16x16x32_bf16 v[78:81], v[94:97], v[210:213], v[78:81]
	v_mfma_f32_16x16x32_bf16 v[74:77], v[102:105], v[210:213], v[74:77]
	s_setprio 2
	s_barrier
	v_mfma_f32_16x16x32_bf16 v[70:73], v[94:97], v[218:221], v[70:73]
	v_mfma_f32_16x16x32_bf16 v[66:69], v[102:105], v[218:221], v[66:69]
	s_setprio 0
	s_add_u32 s44, s44, 0x80080
	s_addc_u32 s45, s45, 0
	s_add_i32 s48, s48, s22
	v_lshl_add_u64 v[90:91], s[44:45], 0, v[0:1]
	s_mov_b32 m0, s48
	s_nop 0
	global_load_lds_dwordx4 v[90:91], off
	v_lshl_add_u64 v[90:91], s[44:45], 0, v[158:159]
	s_add_i32 m0, s48, 0x2000
	s_nop 0
	global_load_lds_dwordx4 v[90:91], off
	s_waitcnt vmcnt(6)
	s_barrier
	s_setprio 1
	v_mfma_f32_16x16x32_bf16 v[30:33], v[222:225], v[168:171], v[30:33]
	v_mfma_f32_16x16x32_bf16 v[26:29], v[230:233], v[168:171], v[26:29]
	v_mfma_f32_16x16x32_bf16 v[22:25], v[222:225], v[176:179], v[22:25]
	v_mfma_f32_16x16x32_bf16 v[18:21], v[230:233], v[176:179], v[18:21]
	v_mfma_f32_16x16x32_bf16 v[14:17], v[222:225], v[206:209], v[14:17]
	v_mfma_f32_16x16x32_bf16 v[10:13], v[230:233], v[206:209], v[10:13]
	v_mfma_f32_16x16x32_bf16 v[6:9], v[222:225], v[214:217], v[6:9]
	v_mfma_f32_16x16x32_bf16 v[2:5], v[230:233], v[214:217], v[2:5]
	v_mfma_f32_16x16x32_bf16 v[30:33], v[226:229], v[172:175], v[30:33]
	v_mfma_f32_16x16x32_bf16 v[26:29], v[234:237], v[172:175], v[26:29]
	v_mfma_f32_16x16x32_bf16 v[22:25], v[226:229], v[180:183], v[22:25]
	v_mfma_f32_16x16x32_bf16 v[18:21], v[234:237], v[180:183], v[18:21]
	v_mfma_f32_16x16x32_bf16 v[14:17], v[226:229], v[210:213], v[14:17]
	v_mfma_f32_16x16x32_bf16 v[10:13], v[234:237], v[210:213], v[10:13]
	s_setprio 2
	s_add_i32 s47, s47, 2
	s_add_u32 s64, s64, 0x100
	s_addc_u32 s65, s65, 0
	s_add_u32 s18, s18, 0x100
	s_addc_u32 s19, s19, 0
	s_cmp_gt_u32 s47, 29
	s_barrier
	v_mfma_f32_16x16x32_bf16 v[6:9], v[226:229], v[218:221], v[6:9]
	v_mfma_f32_16x16x32_bf16 v[2:5], v[234:237], v[218:221], v[2:5]
	s_setprio 0
	s_cbranch_scc0 .LBB0_1256
	s_lshl_b32 s4, s46, 8
	s_and_b32 s4, s4, 0x3f00
	v_add_u32_e32 v178, s4, v186
	s_ashr_i32 s4, s43, 31
	s_lshr_b32 s4, s4, 29
	s_add_i32 s4, s43, s4
	s_and_b32 s4, s4, 0xfffff8
	s_sub_i32 s4, s43, s4
	v_lshl_or_b32 v172, s4, 8, v188
	v_ashrrev_i32_e32 v173, 31, v172
	v_ashrrev_i32_e32 v179, 31, v178
	v_lshlrev_b32_e32 v170, 12, v178
	v_lshl_add_u32 v170, v172, 1, v170
	v_lshlrev_b32_e32 v171, 3, v178
	v_lshlrev_b32_e32 v174, 2, v172
	global_load_dwordx4 v[98:101], v174, s[12:13]
	global_load_dwordx4 v[90:93], v174, s[12:13] offset:16
	global_load_dwordx4 v[102:105], v174, s[14:15]
	global_load_dwordx4 v[94:97], v174, s[14:15] offset:16
	s_add_u32 s48, s82, 0x0
	s_addc_u32 s49, s83, 0
	global_load_dwordx4 v[220:223], v170, s[48:49]
	s_add_u32 s50, s10, 0x0
	s_addc_u32 s51, s11, 0
	global_load_dwordx2 v[176:177], v171, s[50:51]
	s_add_u32 s48, s82, 0x10000
	s_addc_u32 s49, s83, 0
	global_load_dwordx4 v[224:227], v170, s[48:49]
	s_add_u32 s50, s10, 0x80
	s_addc_u32 s51, s11, 0
	global_load_dwordx2 v[180:181], v171, s[50:51]
	s_add_u32 s48, s82, 0x20000
	s_addc_u32 s49, s83, 0
	global_load_dwordx4 v[228:231], v170, s[48:49]
	s_add_u32 s50, s10, 0x100
	s_addc_u32 s51, s11, 0
	global_load_dwordx2 v[182:183], v171, s[50:51]
	s_add_u32 s48, s82, 0x30000
	s_addc_u32 s49, s83, 0
	global_load_dwordx4 v[232:235], v170, s[48:49]
	s_add_u32 s50, s10, 0x180
	s_addc_u32 s51, s11, 0
	global_load_dwordx2 v[184:185], v171, s[50:51]
	s_add_u32 s48, s82, 0x80000
	s_addc_u32 s49, s83, 0
	global_load_dwordx4 v[236:239], v170, s[48:49]
	s_add_u32 s50, s10, 0x400
	s_addc_u32 s51, s11, 0
	global_load_dwordx2 v[168:169], v171, s[50:51]
	s_add_u32 s48, s82, 0x90000
	s_addc_u32 s49, s83, 0
	global_load_dwordx4 v[240:243], v170, s[48:49]
	s_add_u32 s50, s10, 0x480
	s_addc_u32 s51, s11, 0
	global_load_dwordx2 v[252:253], v171, s[50:51]
	s_add_u32 s48, s82, 0xa0000
	s_addc_u32 s49, s83, 0
	global_load_dwordx4 v[244:247], v170, s[48:49]
	s_add_u32 s50, s10, 0x500
	s_addc_u32 s51, s11, 0
	global_load_dwordx2 v[214:215], v171, s[50:51]
	s_add_u32 s48, s82, 0xb0000
	s_addc_u32 s49, s83, 0
	global_load_dwordx4 v[248:251], v170, s[48:49]
	s_add_u32 s50, s10, 0x580
	s_addc_u32 s51, s11, 0
	global_load_dwordx2 v[216:217], v171, s[50:51]
	s_waitcnt vmcnt(14)
	v_lshlrev_b32_e32 v206, 16, v220
	v_and_b32_e32 v207, 0xffff0000, v220
	v_lshlrev_b32_e32 v208, 16, v221
	v_and_b32_e32 v209, 0xffff0000, v221
	v_lshlrev_b32_e32 v210, 16, v222
	v_and_b32_e32 v211, 0xffff0000, v222
	v_lshlrev_b32_e32 v212, 16, v223
	v_and_b32_e32 v213, 0xffff0000, v223
	v_sub_f32_e32 v206, v206, v176
	v_sub_f32_e32 v207, v207, v176
	v_sub_f32_e32 v208, v208, v176
	v_sub_f32_e32 v209, v209, v176
	v_sub_f32_e32 v210, v210, v176
	v_sub_f32_e32 v211, v211, v176
	v_sub_f32_e32 v212, v212, v176
	v_sub_f32_e32 v213, v213, v176
	v_pk_mul_f32 v[206:207], v[176:177], v[206:207] op_sel:[1,0]
	v_pk_mul_f32 v[208:209], v[176:177], v[208:209] op_sel:[1,0]
	v_pk_mul_f32 v[210:211], v[176:177], v[210:211] op_sel:[1,0]
	v_pk_mul_f32 v[212:213], v[176:177], v[212:213] op_sel:[1,0]
	v_pk_fma_f32 v[206:207], v[98:99], v[206:207], v[102:103]
	v_pk_fma_f32 v[208:209], v[100:101], v[208:209], v[104:105]
	v_pk_fma_f32 v[210:211], v[90:91], v[210:211], v[94:95]
	v_pk_fma_f32 v[212:213], v[92:93], v[212:213], v[96:97]
	v_pk_fma_f32 v[206:207], v[206:207], s[66:67], v[142:143] op_sel_hi:[1,0,1]
	v_pk_fma_f32 v[208:209], v[208:209], s[66:67], v[144:145] op_sel_hi:[1,0,1]
	v_pk_fma_f32 v[210:211], v[210:211], s[66:67], v[138:139] op_sel_hi:[1,0,1]
	v_pk_fma_f32 v[212:213], v[212:213], s[66:67], v[140:141] op_sel_hi:[1,0,1]
	v_cvt_pk_bf16_f32 v220, v206, v207
	v_cvt_pk_bf16_f32 v221, v208, v209
	v_cvt_pk_bf16_f32 v222, v210, v211
	v_cvt_pk_bf16_f32 v223, v212, v213
	s_add_u32 s48, s82, 0x0
	s_addc_u32 s49, s83, 0
	global_store_dwordx4 v170, v[220:223], s[48:49]
	s_waitcnt vmcnt(13)
	v_lshlrev_b32_e32 v206, 16, v224
	v_and_b32_e32 v207, 0xffff0000, v224
	v_lshlrev_b32_e32 v208, 16, v225
	v_and_b32_e32 v209, 0xffff0000, v225
	v_lshlrev_b32_e32 v210, 16, v226
	v_and_b32_e32 v211, 0xffff0000, v226
	v_lshlrev_b32_e32 v212, 16, v227
	v_and_b32_e32 v213, 0xffff0000, v227
	v_sub_f32_e32 v206, v206, v180
	v_sub_f32_e32 v207, v207, v180
	v_sub_f32_e32 v208, v208, v180
	v_sub_f32_e32 v209, v209, v180
	v_sub_f32_e32 v210, v210, v180
	v_sub_f32_e32 v211, v211, v180
	v_sub_f32_e32 v212, v212, v180
	v_sub_f32_e32 v213, v213, v180
	v_pk_mul_f32 v[206:207], v[180:181], v[206:207] op_sel:[1,0]
	v_pk_mul_f32 v[208:209], v[180:181], v[208:209] op_sel:[1,0]
	v_pk_mul_f32 v[210:211], v[180:181], v[210:211] op_sel:[1,0]
	v_pk_mul_f32 v[212:213], v[180:181], v[212:213] op_sel:[1,0]
	v_pk_fma_f32 v[206:207], v[98:99], v[206:207], v[102:103]
	v_pk_fma_f32 v[208:209], v[100:101], v[208:209], v[104:105]
	v_pk_fma_f32 v[210:211], v[90:91], v[210:211], v[94:95]
	v_pk_fma_f32 v[212:213], v[92:93], v[212:213], v[96:97]
	v_pk_fma_f32 v[206:207], v[206:207], s[66:67], v[134:135] op_sel_hi:[1,0,1]
	v_pk_fma_f32 v[208:209], v[208:209], s[66:67], v[136:137] op_sel_hi:[1,0,1]
	v_pk_fma_f32 v[210:211], v[210:211], s[66:67], v[130:131] op_sel_hi:[1,0,1]
	v_pk_fma_f32 v[212:213], v[212:213], s[66:67], v[132:133] op_sel_hi:[1,0,1]
	v_cvt_pk_bf16_f32 v224, v206, v207
	v_cvt_pk_bf16_f32 v225, v208, v209
	v_cvt_pk_bf16_f32 v226, v210, v211
	v_cvt_pk_bf16_f32 v227, v212, v213
	s_add_u32 s48, s82, 0x10000
	s_addc_u32 s49, s83, 0
	global_store_dwordx4 v170, v[224:227], s[48:49]
	s_waitcnt vmcnt(12)
	v_lshlrev_b32_e32 v206, 16, v228
	v_and_b32_e32 v207, 0xffff0000, v228
	v_lshlrev_b32_e32 v208, 16, v229
	v_and_b32_e32 v209, 0xffff0000, v229
	v_lshlrev_b32_e32 v210, 16, v230
	v_and_b32_e32 v211, 0xffff0000, v230
	v_lshlrev_b32_e32 v212, 16, v231
	v_and_b32_e32 v213, 0xffff0000, v231
	v_sub_f32_e32 v206, v206, v182
	v_sub_f32_e32 v207, v207, v182
	v_sub_f32_e32 v208, v208, v182
	v_sub_f32_e32 v209, v209, v182
	v_sub_f32_e32 v210, v210, v182
	v_sub_f32_e32 v211, v211, v182
	v_sub_f32_e32 v212, v212, v182
	v_sub_f32_e32 v213, v213, v182
	v_pk_mul_f32 v[206:207], v[182:183], v[206:207] op_sel:[1,0]
	v_pk_mul_f32 v[208:209], v[182:183], v[208:209] op_sel:[1,0]
	v_pk_mul_f32 v[210:211], v[182:183], v[210:211] op_sel:[1,0]
	v_pk_mul_f32 v[212:213], v[182:183], v[212:213] op_sel:[1,0]
	v_pk_fma_f32 v[206:207], v[98:99], v[206:207], v[102:103]
	v_pk_fma_f32 v[208:209], v[100:101], v[208:209], v[104:105]
	v_pk_fma_f32 v[210:211], v[90:91], v[210:211], v[94:95]
	v_pk_fma_f32 v[212:213], v[92:93], v[212:213], v[96:97]
	v_pk_fma_f32 v[206:207], v[206:207], s[66:67], v[126:127] op_sel_hi:[1,0,1]
	v_pk_fma_f32 v[208:209], v[208:209], s[66:67], v[128:129] op_sel_hi:[1,0,1]
	v_pk_fma_f32 v[210:211], v[210:211], s[66:67], v[122:123] op_sel_hi:[1,0,1]
	v_pk_fma_f32 v[212:213], v[212:213], s[66:67], v[124:125] op_sel_hi:[1,0,1]
	v_cvt_pk_bf16_f32 v228, v206, v207
	v_cvt_pk_bf16_f32 v229, v208, v209
	v_cvt_pk_bf16_f32 v230, v210, v211
	v_cvt_pk_bf16_f32 v231, v212, v213
	s_add_u32 s48, s82, 0x20000
	s_addc_u32 s49, s83, 0
	global_store_dwordx4 v170, v[228:231], s[48:49]
	s_waitcnt vmcnt(11)
	v_lshlrev_b32_e32 v206, 16, v232
	v_and_b32_e32 v207, 0xffff0000, v232
	v_lshlrev_b32_e32 v208, 16, v233
	v_and_b32_e32 v209, 0xffff0000, v233
	v_lshlrev_b32_e32 v210, 16, v234
	v_and_b32_e32 v211, 0xffff0000, v234
	v_lshlrev_b32_e32 v212, 16, v235
	v_and_b32_e32 v213, 0xffff0000, v235
	v_sub_f32_e32 v206, v206, v184
	v_sub_f32_e32 v207, v207, v184
	v_sub_f32_e32 v208, v208, v184
	v_sub_f32_e32 v209, v209, v184
	v_sub_f32_e32 v210, v210, v184
	v_sub_f32_e32 v211, v211, v184
	v_sub_f32_e32 v212, v212, v184
	v_sub_f32_e32 v213, v213, v184
	v_pk_mul_f32 v[206:207], v[184:185], v[206:207] op_sel:[1,0]
	v_pk_mul_f32 v[208:209], v[184:185], v[208:209] op_sel:[1,0]
	v_pk_mul_f32 v[210:211], v[184:185], v[210:211] op_sel:[1,0]
	v_pk_mul_f32 v[212:213], v[184:185], v[212:213] op_sel:[1,0]
	v_pk_fma_f32 v[206:207], v[98:99], v[206:207], v[102:103]
	v_pk_fma_f32 v[208:209], v[100:101], v[208:209], v[104:105]
	v_pk_fma_f32 v[210:211], v[90:91], v[210:211], v[94:95]
	v_pk_fma_f32 v[212:213], v[92:93], v[212:213], v[96:97]
	v_pk_fma_f32 v[206:207], v[206:207], s[66:67], v[118:119] op_sel_hi:[1,0,1]
	v_pk_fma_f32 v[208:209], v[208:209], s[66:67], v[120:121] op_sel_hi:[1,0,1]
	v_pk_fma_f32 v[210:211], v[210:211], s[66:67], v[114:115] op_sel_hi:[1,0,1]
	v_pk_fma_f32 v[212:213], v[212:213], s[66:67], v[116:117] op_sel_hi:[1,0,1]
	v_cvt_pk_bf16_f32 v232, v206, v207
	v_cvt_pk_bf16_f32 v233, v208, v209
	v_cvt_pk_bf16_f32 v234, v210, v211
	v_cvt_pk_bf16_f32 v235, v212, v213
	s_add_u32 s48, s82, 0x30000
	s_addc_u32 s49, s83, 0
	global_store_dwordx4 v170, v[232:235], s[48:49]
	s_waitcnt vmcnt(10)
	v_lshlrev_b32_e32 v206, 16, v236
	v_and_b32_e32 v207, 0xffff0000, v236
	v_lshlrev_b32_e32 v208, 16, v237
	v_and_b32_e32 v209, 0xffff0000, v237
	v_lshlrev_b32_e32 v210, 16, v238
	v_and_b32_e32 v211, 0xffff0000, v238
	v_lshlrev_b32_e32 v212, 16, v239
	v_and_b32_e32 v213, 0xffff0000, v239
	v_sub_f32_e32 v206, v206, v168
	v_sub_f32_e32 v207, v207, v168
	v_sub_f32_e32 v208, v208, v168
	v_sub_f32_e32 v209, v209, v168
	v_sub_f32_e32 v210, v210, v168
	v_sub_f32_e32 v211, v211, v168
	v_sub_f32_e32 v212, v212, v168
	v_sub_f32_e32 v213, v213, v168
	v_pk_mul_f32 v[206:207], v[168:169], v[206:207] op_sel:[1,0]
	v_pk_mul_f32 v[208:209], v[168:169], v[208:209] op_sel:[1,0]
	v_pk_mul_f32 v[210:211], v[168:169], v[210:211] op_sel:[1,0]
	v_pk_mul_f32 v[212:213], v[168:169], v[212:213] op_sel:[1,0]
	v_pk_fma_f32 v[206:207], v[98:99], v[206:207], v[102:103]
	v_pk_fma_f32 v[208:209], v[100:101], v[208:209], v[104:105]
	v_pk_fma_f32 v[210:211], v[90:91], v[210:211], v[94:95]
	v_pk_fma_f32 v[212:213], v[92:93], v[212:213], v[96:97]
	v_pk_fma_f32 v[206:207], v[206:207], s[66:67], v[110:111] op_sel_hi:[1,0,1]
	v_pk_fma_f32 v[208:209], v[208:209], s[66:67], v[112:113] op_sel_hi:[1,0,1]
	v_pk_fma_f32 v[210:211], v[210:211], s[66:67], v[106:107] op_sel_hi:[1,0,1]
	v_pk_fma_f32 v[212:213], v[212:213], s[66:67], v[108:109] op_sel_hi:[1,0,1]
	v_cvt_pk_bf16_f32 v236, v206, v207
	v_cvt_pk_bf16_f32 v237, v208, v209
	v_cvt_pk_bf16_f32 v238, v210, v211
	v_cvt_pk_bf16_f32 v239, v212, v213
	s_add_u32 s48, s82, 0x80000
	s_addc_u32 s49, s83, 0
	global_store_dwordx4 v170, v[236:239], s[48:49]
	s_waitcnt vmcnt(9)
	v_lshlrev_b32_e32 v206, 16, v240
	v_and_b32_e32 v207, 0xffff0000, v240
	v_lshlrev_b32_e32 v208, 16, v241
	v_and_b32_e32 v209, 0xffff0000, v241
	v_lshlrev_b32_e32 v210, 16, v242
	v_and_b32_e32 v211, 0xffff0000, v242
	v_lshlrev_b32_e32 v212, 16, v243
	v_and_b32_e32 v213, 0xffff0000, v243
	v_sub_f32_e32 v206, v206, v252
	v_sub_f32_e32 v207, v207, v252
	v_sub_f32_e32 v208, v208, v252
	v_sub_f32_e32 v209, v209, v252
	v_sub_f32_e32 v210, v210, v252
	v_sub_f32_e32 v211, v211, v252
	v_sub_f32_e32 v212, v212, v252
	v_sub_f32_e32 v213, v213, v252
	v_pk_mul_f32 v[206:207], v[252:253], v[206:207] op_sel:[1,0]
	v_pk_mul_f32 v[208:209], v[252:253], v[208:209] op_sel:[1,0]
	v_pk_mul_f32 v[210:211], v[252:253], v[210:211] op_sel:[1,0]
	v_pk_mul_f32 v[212:213], v[252:253], v[212:213] op_sel:[1,0]
	v_pk_fma_f32 v[206:207], v[98:99], v[206:207], v[102:103]
	v_pk_fma_f32 v[208:209], v[100:101], v[208:209], v[104:105]
	v_pk_fma_f32 v[210:211], v[90:91], v[210:211], v[94:95]
	v_pk_fma_f32 v[212:213], v[92:93], v[212:213], v[96:97]
	v_pk_fma_f32 v[206:207], v[206:207], s[66:67], v[86:87] op_sel_hi:[1,0,1]
	v_pk_fma_f32 v[208:209], v[208:209], s[66:67], v[88:89] op_sel_hi:[1,0,1]
	v_pk_fma_f32 v[210:211], v[210:211], s[66:67], v[82:83] op_sel_hi:[1,0,1]
	v_pk_fma_f32 v[212:213], v[212:213], s[66:67], v[84:85] op_sel_hi:[1,0,1]
	v_cvt_pk_bf16_f32 v240, v206, v207
	v_cvt_pk_bf16_f32 v241, v208, v209
	v_cvt_pk_bf16_f32 v242, v210, v211
	v_cvt_pk_bf16_f32 v243, v212, v213
	s_add_u32 s48, s82, 0x90000
	s_addc_u32 s49, s83, 0
	global_store_dwordx4 v170, v[240:243], s[48:49]
	s_waitcnt vmcnt(8)
	v_lshlrev_b32_e32 v206, 16, v244
	v_and_b32_e32 v207, 0xffff0000, v244
	v_lshlrev_b32_e32 v208, 16, v245
	v_and_b32_e32 v209, 0xffff0000, v245
	v_lshlrev_b32_e32 v210, 16, v246
	v_and_b32_e32 v211, 0xffff0000, v246
	v_lshlrev_b32_e32 v212, 16, v247
	v_and_b32_e32 v213, 0xffff0000, v247
	v_sub_f32_e32 v206, v206, v214
	v_sub_f32_e32 v207, v207, v214
	v_sub_f32_e32 v208, v208, v214
	v_sub_f32_e32 v209, v209, v214
	v_sub_f32_e32 v210, v210, v214
	v_sub_f32_e32 v211, v211, v214
	v_sub_f32_e32 v212, v212, v214
	v_sub_f32_e32 v213, v213, v214
	v_pk_mul_f32 v[206:207], v[214:215], v[206:207] op_sel:[1,0]
	v_pk_mul_f32 v[208:209], v[214:215], v[208:209] op_sel:[1,0]
	v_pk_mul_f32 v[210:211], v[214:215], v[210:211] op_sel:[1,0]
	v_pk_mul_f32 v[212:213], v[214:215], v[212:213] op_sel:[1,0]
	v_pk_fma_f32 v[206:207], v[98:99], v[206:207], v[102:103]
	v_pk_fma_f32 v[208:209], v[100:101], v[208:209], v[104:105]
	v_pk_fma_f32 v[210:211], v[90:91], v[210:211], v[94:95]
	v_pk_fma_f32 v[212:213], v[92:93], v[212:213], v[96:97]
	v_pk_fma_f32 v[206:207], v[206:207], s[66:67], v[78:79] op_sel_hi:[1,0,1]
	v_pk_fma_f32 v[208:209], v[208:209], s[66:67], v[80:81] op_sel_hi:[1,0,1]
	v_pk_fma_f32 v[210:211], v[210:211], s[66:67], v[74:75] op_sel_hi:[1,0,1]
	v_pk_fma_f32 v[212:213], v[212:213], s[66:67], v[76:77] op_sel_hi:[1,0,1]
	v_cvt_pk_bf16_f32 v244, v206, v207
	v_cvt_pk_bf16_f32 v245, v208, v209
	v_cvt_pk_bf16_f32 v246, v210, v211
	v_cvt_pk_bf16_f32 v247, v212, v213
	s_add_u32 s48, s82, 0xa0000
	s_addc_u32 s49, s83, 0
	global_store_dwordx4 v170, v[244:247], s[48:49]
	s_waitcnt vmcnt(7)
	v_lshlrev_b32_e32 v206, 16, v248
	v_and_b32_e32 v207, 0xffff0000, v248
	v_lshlrev_b32_e32 v208, 16, v249
	v_and_b32_e32 v209, 0xffff0000, v249
	v_lshlrev_b32_e32 v210, 16, v250
	v_and_b32_e32 v211, 0xffff0000, v250
	v_lshlrev_b32_e32 v212, 16, v251
	v_and_b32_e32 v213, 0xffff0000, v251
	v_sub_f32_e32 v206, v206, v216
	v_sub_f32_e32 v207, v207, v216
	v_sub_f32_e32 v208, v208, v216
	v_sub_f32_e32 v209, v209, v216
	v_sub_f32_e32 v210, v210, v216
	v_sub_f32_e32 v211, v211, v216
	v_sub_f32_e32 v212, v212, v216
	v_sub_f32_e32 v213, v213, v216
	v_pk_mul_f32 v[206:207], v[216:217], v[206:207] op_sel:[1,0]
	v_pk_mul_f32 v[208:209], v[216:217], v[208:209] op_sel:[1,0]
	v_pk_mul_f32 v[210:211], v[216:217], v[210:211] op_sel:[1,0]
	v_pk_mul_f32 v[212:213], v[216:217], v[212:213] op_sel:[1,0]
	v_pk_fma_f32 v[206:207], v[98:99], v[206:207], v[102:103]
	v_pk_fma_f32 v[208:209], v[100:101], v[208:209], v[104:105]
	v_pk_fma_f32 v[210:211], v[90:91], v[210:211], v[94:95]
	v_pk_fma_f32 v[212:213], v[92:93], v[212:213], v[96:97]
	v_pk_fma_f32 v[206:207], v[206:207], s[66:67], v[70:71] op_sel_hi:[1,0,1]
	v_pk_fma_f32 v[208:209], v[208:209], s[66:67], v[72:73] op_sel_hi:[1,0,1]
	v_pk_fma_f32 v[210:211], v[210:211], s[66:67], v[66:67] op_sel_hi:[1,0,1]
	v_pk_fma_f32 v[212:213], v[212:213], s[66:67], v[68:69] op_sel_hi:[1,0,1]
	v_cvt_pk_bf16_f32 v248, v206, v207
	v_cvt_pk_bf16_f32 v249, v208, v209
	v_cvt_pk_bf16_f32 v250, v210, v211
	v_cvt_pk_bf16_f32 v251, v212, v213
	s_add_u32 s48, s82, 0xb0000
	s_addc_u32 s49, s83, 0
	global_store_dwordx4 v170, v[248:251], s[48:49]
	global_load_dwordx4 v[98:101], v174, s[12:13] offset:512
	global_load_dwordx4 v[90:93], v174, s[12:13] offset:528
	global_load_dwordx4 v[102:105], v174, s[14:15] offset:512
	global_load_dwordx4 v[94:97], v174, s[14:15] offset:528
	s_add_u32 s48, s82, 0x100
	s_addc_u32 s49, s83, 0
	global_load_dwordx4 v[220:223], v170, s[48:49]
	s_add_u32 s50, s10, 0x0
	s_addc_u32 s51, s11, 0
	global_load_dwordx2 v[176:177], v171, s[50:51]
	s_add_u32 s48, s82, 0x10100
	s_addc_u32 s49, s83, 0
	global_load_dwordx4 v[224:227], v170, s[48:49]
	s_add_u32 s50, s10, 0x80
	s_addc_u32 s51, s11, 0
	global_load_dwordx2 v[180:181], v171, s[50:51]
	s_add_u32 s48, s82, 0x20100
	s_addc_u32 s49, s83, 0
	global_load_dwordx4 v[228:231], v170, s[48:49]
	s_add_u32 s50, s10, 0x100
	s_addc_u32 s51, s11, 0
	global_load_dwordx2 v[182:183], v171, s[50:51]
	s_add_u32 s48, s82, 0x30100
	s_addc_u32 s49, s83, 0
	global_load_dwordx4 v[232:235], v170, s[48:49]
	s_add_u32 s50, s10, 0x180
	s_addc_u32 s51, s11, 0
	global_load_dwordx2 v[184:185], v171, s[50:51]
	s_add_u32 s48, s82, 0x80100
	s_addc_u32 s49, s83, 0
	global_load_dwordx4 v[236:239], v170, s[48:49]
	s_add_u32 s50, s10, 0x400
	s_addc_u32 s51, s11, 0
	global_load_dwordx2 v[168:169], v171, s[50:51]
	s_add_u32 s48, s82, 0x90100
	s_addc_u32 s49, s83, 0
	global_load_dwordx4 v[240:243], v170, s[48:49]
	s_add_u32 s50, s10, 0x480
	s_addc_u32 s51, s11, 0
	global_load_dwordx2 v[252:253], v171, s[50:51]
	s_add_u32 s48, s82, 0xa0100
	s_addc_u32 s49, s83, 0
	global_load_dwordx4 v[244:247], v170, s[48:49]
	s_add_u32 s50, s10, 0x500
	s_addc_u32 s51, s11, 0
	global_load_dwordx2 v[214:215], v171, s[50:51]
	s_add_u32 s48, s82, 0xb0100
	s_addc_u32 s49, s83, 0
	global_load_dwordx4 v[248:251], v170, s[48:49]
	s_add_u32 s50, s10, 0x580
	s_addc_u32 s51, s11, 0
	global_load_dwordx2 v[216:217], v171, s[50:51]
	s_waitcnt vmcnt(14)
	v_lshlrev_b32_e32 v206, 16, v220
	v_and_b32_e32 v207, 0xffff0000, v220
	v_lshlrev_b32_e32 v208, 16, v221
	v_and_b32_e32 v209, 0xffff0000, v221
	v_lshlrev_b32_e32 v210, 16, v222
	v_and_b32_e32 v211, 0xffff0000, v222
	v_lshlrev_b32_e32 v212, 16, v223
	v_and_b32_e32 v213, 0xffff0000, v223
	v_sub_f32_e32 v206, v206, v176
	v_sub_f32_e32 v207, v207, v176
	v_sub_f32_e32 v208, v208, v176
	v_sub_f32_e32 v209, v209, v176
	v_sub_f32_e32 v210, v210, v176
	v_sub_f32_e32 v211, v211, v176
	v_sub_f32_e32 v212, v212, v176
	v_sub_f32_e32 v213, v213, v176
	v_pk_mul_f32 v[206:207], v[176:177], v[206:207] op_sel:[1,0]
	v_pk_mul_f32 v[208:209], v[176:177], v[208:209] op_sel:[1,0]
	v_pk_mul_f32 v[210:211], v[176:177], v[210:211] op_sel:[1,0]
	v_pk_mul_f32 v[212:213], v[176:177], v[212:213] op_sel:[1,0]
	v_pk_fma_f32 v[206:207], v[98:99], v[206:207], v[102:103]
	v_pk_fma_f32 v[208:209], v[100:101], v[208:209], v[104:105]
	v_pk_fma_f32 v[210:211], v[90:91], v[210:211], v[94:95]
	v_pk_fma_f32 v[212:213], v[92:93], v[212:213], v[96:97]
	v_pk_fma_f32 v[206:207], v[206:207], s[66:67], v[62:63] op_sel_hi:[1,0,1]
	v_pk_fma_f32 v[208:209], v[208:209], s[66:67], v[64:65] op_sel_hi:[1,0,1]
	v_pk_fma_f32 v[210:211], v[210:211], s[66:67], v[58:59] op_sel_hi:[1,0,1]
	v_pk_fma_f32 v[212:213], v[212:213], s[66:67], v[60:61] op_sel_hi:[1,0,1]
	v_cvt_pk_bf16_f32 v220, v206, v207
	v_cvt_pk_bf16_f32 v221, v208, v209
	v_cvt_pk_bf16_f32 v222, v210, v211
	v_cvt_pk_bf16_f32 v223, v212, v213
	s_add_u32 s48, s82, 0x100
	s_addc_u32 s49, s83, 0
	global_store_dwordx4 v170, v[220:223], s[48:49]
	s_waitcnt vmcnt(13)
	v_lshlrev_b32_e32 v206, 16, v224
	v_and_b32_e32 v207, 0xffff0000, v224
	v_lshlrev_b32_e32 v208, 16, v225
	v_and_b32_e32 v209, 0xffff0000, v225
	v_lshlrev_b32_e32 v210, 16, v226
	v_and_b32_e32 v211, 0xffff0000, v226
	v_lshlrev_b32_e32 v212, 16, v227
	v_and_b32_e32 v213, 0xffff0000, v227
	v_sub_f32_e32 v206, v206, v180
	v_sub_f32_e32 v207, v207, v180
	v_sub_f32_e32 v208, v208, v180
	v_sub_f32_e32 v209, v209, v180
	v_sub_f32_e32 v210, v210, v180
	v_sub_f32_e32 v211, v211, v180
	v_sub_f32_e32 v212, v212, v180
	v_sub_f32_e32 v213, v213, v180
	v_pk_mul_f32 v[206:207], v[180:181], v[206:207] op_sel:[1,0]
	v_pk_mul_f32 v[208:209], v[180:181], v[208:209] op_sel:[1,0]
	v_pk_mul_f32 v[210:211], v[180:181], v[210:211] op_sel:[1,0]
	v_pk_mul_f32 v[212:213], v[180:181], v[212:213] op_sel:[1,0]
	v_pk_fma_f32 v[206:207], v[98:99], v[206:207], v[102:103]
	v_pk_fma_f32 v[208:209], v[100:101], v[208:209], v[104:105]
	v_pk_fma_f32 v[210:211], v[90:91], v[210:211], v[94:95]
	v_pk_fma_f32 v[212:213], v[92:93], v[212:213], v[96:97]
	v_pk_fma_f32 v[206:207], v[206:207], s[66:67], v[54:55] op_sel_hi:[1,0,1]
	v_pk_fma_f32 v[208:209], v[208:209], s[66:67], v[56:57] op_sel_hi:[1,0,1]
	v_pk_fma_f32 v[210:211], v[210:211], s[66:67], v[50:51] op_sel_hi:[1,0,1]
	v_pk_fma_f32 v[212:213], v[212:213], s[66:67], v[52:53] op_sel_hi:[1,0,1]
	v_cvt_pk_bf16_f32 v224, v206, v207
	v_cvt_pk_bf16_f32 v225, v208, v209
	v_cvt_pk_bf16_f32 v226, v210, v211
	v_cvt_pk_bf16_f32 v227, v212, v213
	s_add_u32 s48, s82, 0x10100
	s_addc_u32 s49, s83, 0
	global_store_dwordx4 v170, v[224:227], s[48:49]
	s_waitcnt vmcnt(12)
	v_lshlrev_b32_e32 v206, 16, v228
	v_and_b32_e32 v207, 0xffff0000, v228
	v_lshlrev_b32_e32 v208, 16, v229
	v_and_b32_e32 v209, 0xffff0000, v229
	v_lshlrev_b32_e32 v210, 16, v230
	v_and_b32_e32 v211, 0xffff0000, v230
	v_lshlrev_b32_e32 v212, 16, v231
	v_and_b32_e32 v213, 0xffff0000, v231
	v_sub_f32_e32 v206, v206, v182
	v_sub_f32_e32 v207, v207, v182
	v_sub_f32_e32 v208, v208, v182
	v_sub_f32_e32 v209, v209, v182
	v_sub_f32_e32 v210, v210, v182
	v_sub_f32_e32 v211, v211, v182
	v_sub_f32_e32 v212, v212, v182
	v_sub_f32_e32 v213, v213, v182
	v_pk_mul_f32 v[206:207], v[182:183], v[206:207] op_sel:[1,0]
	v_pk_mul_f32 v[208:209], v[182:183], v[208:209] op_sel:[1,0]
	v_pk_mul_f32 v[210:211], v[182:183], v[210:211] op_sel:[1,0]
	v_pk_mul_f32 v[212:213], v[182:183], v[212:213] op_sel:[1,0]
	v_pk_fma_f32 v[206:207], v[98:99], v[206:207], v[102:103]
	v_pk_fma_f32 v[208:209], v[100:101], v[208:209], v[104:105]
	v_pk_fma_f32 v[210:211], v[90:91], v[210:211], v[94:95]
	v_pk_fma_f32 v[212:213], v[92:93], v[212:213], v[96:97]
	v_pk_fma_f32 v[206:207], v[206:207], s[66:67], v[46:47] op_sel_hi:[1,0,1]
	v_pk_fma_f32 v[208:209], v[208:209], s[66:67], v[48:49] op_sel_hi:[1,0,1]
	v_pk_fma_f32 v[210:211], v[210:211], s[66:67], v[42:43] op_sel_hi:[1,0,1]
	v_pk_fma_f32 v[212:213], v[212:213], s[66:67], v[44:45] op_sel_hi:[1,0,1]
	v_cvt_pk_bf16_f32 v228, v206, v207
	v_cvt_pk_bf16_f32 v229, v208, v209
	v_cvt_pk_bf16_f32 v230, v210, v211
	v_cvt_pk_bf16_f32 v231, v212, v213
	s_add_u32 s48, s82, 0x20100
	s_addc_u32 s49, s83, 0
	global_store_dwordx4 v170, v[228:231], s[48:49]
	s_waitcnt vmcnt(11)
	v_lshlrev_b32_e32 v206, 16, v232
	v_and_b32_e32 v207, 0xffff0000, v232
	v_lshlrev_b32_e32 v208, 16, v233
	v_and_b32_e32 v209, 0xffff0000, v233
	v_lshlrev_b32_e32 v210, 16, v234
	v_and_b32_e32 v211, 0xffff0000, v234
	v_lshlrev_b32_e32 v212, 16, v235
	v_and_b32_e32 v213, 0xffff0000, v235
	v_sub_f32_e32 v206, v206, v184
	v_sub_f32_e32 v207, v207, v184
	v_sub_f32_e32 v208, v208, v184
	v_sub_f32_e32 v209, v209, v184
	v_sub_f32_e32 v210, v210, v184
	v_sub_f32_e32 v211, v211, v184
	v_sub_f32_e32 v212, v212, v184
	v_sub_f32_e32 v213, v213, v184
	v_pk_mul_f32 v[206:207], v[184:185], v[206:207] op_sel:[1,0]
	v_pk_mul_f32 v[208:209], v[184:185], v[208:209] op_sel:[1,0]
	v_pk_mul_f32 v[210:211], v[184:185], v[210:211] op_sel:[1,0]
	v_pk_mul_f32 v[212:213], v[184:185], v[212:213] op_sel:[1,0]
	v_pk_fma_f32 v[206:207], v[98:99], v[206:207], v[102:103]
	v_pk_fma_f32 v[208:209], v[100:101], v[208:209], v[104:105]
	v_pk_fma_f32 v[210:211], v[90:91], v[210:211], v[94:95]
	v_pk_fma_f32 v[212:213], v[92:93], v[212:213], v[96:97]
	v_pk_fma_f32 v[206:207], v[206:207], s[66:67], v[38:39] op_sel_hi:[1,0,1]
	v_pk_fma_f32 v[208:209], v[208:209], s[66:67], v[40:41] op_sel_hi:[1,0,1]
	v_pk_fma_f32 v[210:211], v[210:211], s[66:67], v[34:35] op_sel_hi:[1,0,1]
	v_pk_fma_f32 v[212:213], v[212:213], s[66:67], v[36:37] op_sel_hi:[1,0,1]
	v_cvt_pk_bf16_f32 v232, v206, v207
	v_cvt_pk_bf16_f32 v233, v208, v209
	v_cvt_pk_bf16_f32 v234, v210, v211
	v_cvt_pk_bf16_f32 v235, v212, v213
	s_add_u32 s48, s82, 0x30100
	s_addc_u32 s49, s83, 0
	global_store_dwordx4 v170, v[232:235], s[48:49]
	s_waitcnt vmcnt(10)
	v_lshlrev_b32_e32 v206, 16, v236
	v_and_b32_e32 v207, 0xffff0000, v236
	v_lshlrev_b32_e32 v208, 16, v237
	v_and_b32_e32 v209, 0xffff0000, v237
	v_lshlrev_b32_e32 v210, 16, v238
	v_and_b32_e32 v211, 0xffff0000, v238
	v_lshlrev_b32_e32 v212, 16, v239
	v_and_b32_e32 v213, 0xffff0000, v239
	v_sub_f32_e32 v206, v206, v168
	v_sub_f32_e32 v207, v207, v168
	v_sub_f32_e32 v208, v208, v168
	v_sub_f32_e32 v209, v209, v168
	v_sub_f32_e32 v210, v210, v168
	v_sub_f32_e32 v211, v211, v168
	v_sub_f32_e32 v212, v212, v168
	v_sub_f32_e32 v213, v213, v168
	v_pk_mul_f32 v[206:207], v[168:169], v[206:207] op_sel:[1,0]
	v_pk_mul_f32 v[208:209], v[168:169], v[208:209] op_sel:[1,0]
	v_pk_mul_f32 v[210:211], v[168:169], v[210:211] op_sel:[1,0]
	v_pk_mul_f32 v[212:213], v[168:169], v[212:213] op_sel:[1,0]
	v_pk_fma_f32 v[206:207], v[98:99], v[206:207], v[102:103]
	v_pk_fma_f32 v[208:209], v[100:101], v[208:209], v[104:105]
	v_pk_fma_f32 v[210:211], v[90:91], v[210:211], v[94:95]
	v_pk_fma_f32 v[212:213], v[92:93], v[212:213], v[96:97]
	v_pk_fma_f32 v[206:207], v[206:207], s[66:67], v[30:31] op_sel_hi:[1,0,1]
	v_pk_fma_f32 v[208:209], v[208:209], s[66:67], v[32:33] op_sel_hi:[1,0,1]
	v_pk_fma_f32 v[210:211], v[210:211], s[66:67], v[26:27] op_sel_hi:[1,0,1]
	v_pk_fma_f32 v[212:213], v[212:213], s[66:67], v[28:29] op_sel_hi:[1,0,1]
	v_cvt_pk_bf16_f32 v236, v206, v207
	v_cvt_pk_bf16_f32 v237, v208, v209
	v_cvt_pk_bf16_f32 v238, v210, v211
	v_cvt_pk_bf16_f32 v239, v212, v213
	s_add_u32 s48, s82, 0x80100
	s_addc_u32 s49, s83, 0
	global_store_dwordx4 v170, v[236:239], s[48:49]
	s_waitcnt vmcnt(9)
	v_lshlrev_b32_e32 v206, 16, v240
	v_and_b32_e32 v207, 0xffff0000, v240
	v_lshlrev_b32_e32 v208, 16, v241
	v_and_b32_e32 v209, 0xffff0000, v241
	v_lshlrev_b32_e32 v210, 16, v242
	v_and_b32_e32 v211, 0xffff0000, v242
	v_lshlrev_b32_e32 v212, 16, v243
	v_and_b32_e32 v213, 0xffff0000, v243
	v_sub_f32_e32 v206, v206, v252
	v_sub_f32_e32 v207, v207, v252
	v_sub_f32_e32 v208, v208, v252
	v_sub_f32_e32 v209, v209, v252
	v_sub_f32_e32 v210, v210, v252
	v_sub_f32_e32 v211, v211, v252
	v_sub_f32_e32 v212, v212, v252
	v_sub_f32_e32 v213, v213, v252
	v_pk_mul_f32 v[206:207], v[252:253], v[206:207] op_sel:[1,0]
	v_pk_mul_f32 v[208:209], v[252:253], v[208:209] op_sel:[1,0]
	v_pk_mul_f32 v[210:211], v[252:253], v[210:211] op_sel:[1,0]
	v_pk_mul_f32 v[212:213], v[252:253], v[212:213] op_sel:[1,0]
	v_pk_fma_f32 v[206:207], v[98:99], v[206:207], v[102:103]
	v_pk_fma_f32 v[208:209], v[100:101], v[208:209], v[104:105]
	v_pk_fma_f32 v[210:211], v[90:91], v[210:211], v[94:95]
	v_pk_fma_f32 v[212:213], v[92:93], v[212:213], v[96:97]
	v_pk_fma_f32 v[206:207], v[206:207], s[66:67], v[22:23] op_sel_hi:[1,0,1]
	v_pk_fma_f32 v[208:209], v[208:209], s[66:67], v[24:25] op_sel_hi:[1,0,1]
	v_pk_fma_f32 v[210:211], v[210:211], s[66:67], v[18:19] op_sel_hi:[1,0,1]
	v_pk_fma_f32 v[212:213], v[212:213], s[66:67], v[20:21] op_sel_hi:[1,0,1]
	v_cvt_pk_bf16_f32 v240, v206, v207
	v_cvt_pk_bf16_f32 v241, v208, v209
	v_cvt_pk_bf16_f32 v242, v210, v211
	v_cvt_pk_bf16_f32 v243, v212, v213
	s_add_u32 s48, s82, 0x90100
	s_addc_u32 s49, s83, 0
	global_store_dwordx4 v170, v[240:243], s[48:49]
	s_waitcnt vmcnt(8)
	v_lshlrev_b32_e32 v206, 16, v244
	v_and_b32_e32 v207, 0xffff0000, v244
	v_lshlrev_b32_e32 v208, 16, v245
	v_and_b32_e32 v209, 0xffff0000, v245
	v_lshlrev_b32_e32 v210, 16, v246
	v_and_b32_e32 v211, 0xffff0000, v246
	v_lshlrev_b32_e32 v212, 16, v247
	v_and_b32_e32 v213, 0xffff0000, v247
	v_sub_f32_e32 v206, v206, v214
	v_sub_f32_e32 v207, v207, v214
	v_sub_f32_e32 v208, v208, v214
	v_sub_f32_e32 v209, v209, v214
	v_sub_f32_e32 v210, v210, v214
	v_sub_f32_e32 v211, v211, v214
	v_sub_f32_e32 v212, v212, v214
	v_sub_f32_e32 v213, v213, v214
	v_pk_mul_f32 v[206:207], v[214:215], v[206:207] op_sel:[1,0]
	v_pk_mul_f32 v[208:209], v[214:215], v[208:209] op_sel:[1,0]
	v_pk_mul_f32 v[210:211], v[214:215], v[210:211] op_sel:[1,0]
	v_pk_mul_f32 v[212:213], v[214:215], v[212:213] op_sel:[1,0]
	v_pk_fma_f32 v[206:207], v[98:99], v[206:207], v[102:103]
	v_pk_fma_f32 v[208:209], v[100:101], v[208:209], v[104:105]
	v_pk_fma_f32 v[210:211], v[90:91], v[210:211], v[94:95]
	v_pk_fma_f32 v[212:213], v[92:93], v[212:213], v[96:97]
	v_pk_fma_f32 v[206:207], v[206:207], s[66:67], v[14:15] op_sel_hi:[1,0,1]
	v_pk_fma_f32 v[208:209], v[208:209], s[66:67], v[16:17] op_sel_hi:[1,0,1]
	v_pk_fma_f32 v[210:211], v[210:211], s[66:67], v[10:11] op_sel_hi:[1,0,1]
	v_pk_fma_f32 v[212:213], v[212:213], s[66:67], v[12:13] op_sel_hi:[1,0,1]
	v_cvt_pk_bf16_f32 v244, v206, v207
	v_cvt_pk_bf16_f32 v245, v208, v209
	v_cvt_pk_bf16_f32 v246, v210, v211
	v_cvt_pk_bf16_f32 v247, v212, v213
	s_add_u32 s48, s82, 0xa0100
	s_addc_u32 s49, s83, 0
	global_store_dwordx4 v170, v[244:247], s[48:49]
	s_waitcnt vmcnt(7)
	v_lshlrev_b32_e32 v206, 16, v248
	v_and_b32_e32 v207, 0xffff0000, v248
	v_lshlrev_b32_e32 v208, 16, v249
	v_and_b32_e32 v209, 0xffff0000, v249
	v_lshlrev_b32_e32 v210, 16, v250
	v_and_b32_e32 v211, 0xffff0000, v250
	v_lshlrev_b32_e32 v212, 16, v251
	v_and_b32_e32 v213, 0xffff0000, v251
	v_sub_f32_e32 v206, v206, v216
	v_sub_f32_e32 v207, v207, v216
	v_sub_f32_e32 v208, v208, v216
	v_sub_f32_e32 v209, v209, v216
	v_sub_f32_e32 v210, v210, v216
	v_sub_f32_e32 v211, v211, v216
	v_sub_f32_e32 v212, v212, v216
	v_sub_f32_e32 v213, v213, v216
	v_pk_mul_f32 v[206:207], v[216:217], v[206:207] op_sel:[1,0]
	v_pk_mul_f32 v[208:209], v[216:217], v[208:209] op_sel:[1,0]
	v_pk_mul_f32 v[210:211], v[216:217], v[210:211] op_sel:[1,0]
	v_pk_mul_f32 v[212:213], v[216:217], v[212:213] op_sel:[1,0]
	v_pk_fma_f32 v[206:207], v[98:99], v[206:207], v[102:103]
	v_pk_fma_f32 v[208:209], v[100:101], v[208:209], v[104:105]
	v_pk_fma_f32 v[210:211], v[90:91], v[210:211], v[94:95]
	v_pk_fma_f32 v[212:213], v[92:93], v[212:213], v[96:97]
	v_pk_fma_f32 v[206:207], v[206:207], s[66:67], v[6:7] op_sel_hi:[1,0,1]
	v_pk_fma_f32 v[208:209], v[208:209], s[66:67], v[8:9] op_sel_hi:[1,0,1]
	v_pk_fma_f32 v[210:211], v[210:211], s[66:67], v[2:3] op_sel_hi:[1,0,1]
	v_pk_fma_f32 v[212:213], v[212:213], s[66:67], v[4:5] op_sel_hi:[1,0,1]
	v_cvt_pk_bf16_f32 v248, v206, v207
	v_cvt_pk_bf16_f32 v249, v208, v209
	v_cvt_pk_bf16_f32 v250, v210, v211
	v_cvt_pk_bf16_f32 v251, v212, v213
	s_add_u32 s48, s82, 0xb0100
	s_addc_u32 s49, s83, 0
	global_store_dwordx4 v170, v[248:251], s[48:49]
	s_and_b64 vcc, exec, s[8:9]
	s_mov_b32 s43, s86
	s_mov_b32 s46, s84
	s_mov_b64 s[68:69], s[90:91]
	s_mov_b64 s[64:65], s[88:89]
	s_cbranch_vccz .LBB0_1249
	s_waitcnt vmcnt(0)
	v_readlane_b32 s86, v254, 39
	s_cmpk_gt_u32 s21, 0xff
	s_mov_b32 s84, 0xf800000
	s_mov_b32 s85, 0x100000
	v_readlane_b32 s87, v254, 40
	s_cbranch_scc1 .LBB0_1260
	s_barrier

.LBB0_1420:
	s_add_u32 s44, s92, 0xfff80080
	s_addc_u32 s45, s93, -1
	s_add_i32 s52, 0, 0x10000
	v_add_u32_e32 v126, s52, v205
	ds_read_b128 v[114:117], v126
	ds_read_b128 v[118:121], v126 offset:1024
	ds_read_b128 v[122:125], v126 offset:2048
	ds_read_b128 v[126:129], v126 offset:3072
	s_cmp_eq_u32 s51, 28
	s_cselect_b32 s95, s6, s45
	s_cselect_b32 s94, s7, s44
	s_cselect_b32 s45, s18, s50
	s_cselect_b32 s44, s19, s49
	v_lshl_add_u64 v[188:189], s[92:93], 0, v[168:169]
	s_add_i32 m0, s37, 0xc000
	ds_read_b128 v[172:175], v206
	ds_read_b128 v[176:179], v206 offset:1024
	ds_read_b128 v[180:183], v206 offset:2048
	ds_read_b128 v[184:187], v206 offset:3072
	ds_read_b128 v[208:211], v206 offset:4096
	ds_read_b128 v[212:215], v206 offset:5120
	ds_read_b128 v[216:219], v206 offset:6144
	ds_read_b128 v[220:223], v206 offset:7168
	global_load_lds_dwordx4 v[188:189], off
	v_lshl_add_u64 v[188:189], s[92:93], 0, v[170:171]
	s_add_i32 m0, s37, 0xe000
	s_nop 0
	global_load_lds_dwordx4 v[188:189], off
	s_waitcnt lgkmcnt(8)
	s_barrier
	s_waitcnt lgkmcnt(0)
	s_setprio 1
	s_waitcnt lgkmcnt(0)
	v_mfma_f32_16x16x32_bf16 v[138:141], v[114:117], v[172:175], v[138:141]
	v_mfma_f32_16x16x32_bf16 v[58:61], v[122:125], v[172:175], v[58:61]
	v_mfma_f32_16x16x32_bf16 v[134:137], v[114:117], v[180:183], v[134:137]
	v_mfma_f32_16x16x32_bf16 v[54:57], v[122:125], v[180:183], v[54:57]
	v_mfma_f32_16x16x32_bf16 v[110:113], v[114:117], v[208:211], v[110:113]
	v_mfma_f32_16x16x32_bf16 v[46:49], v[122:125], v[208:211], v[46:49]
	v_mfma_f32_16x16x32_bf16 v[102:105], v[114:117], v[216:219], v[102:105]
	v_mfma_f32_16x16x32_bf16 v[38:41], v[122:125], v[216:219], v[38:41]
	v_mfma_f32_16x16x32_bf16 v[138:141], v[118:121], v[176:179], v[138:141]
	v_mfma_f32_16x16x32_bf16 v[58:61], v[126:129], v[176:179], v[58:61]
	v_mfma_f32_16x16x32_bf16 v[134:137], v[118:121], v[184:187], v[134:137]
	v_mfma_f32_16x16x32_bf16 v[54:57], v[126:129], v[184:187], v[54:57]
	v_mfma_f32_16x16x32_bf16 v[110:113], v[118:121], v[212:215], v[110:113]
	v_mfma_f32_16x16x32_bf16 v[46:49], v[126:129], v[212:215], v[46:49]
	s_setprio 2
	s_barrier
	v_mfma_f32_16x16x32_bf16 v[102:105], v[118:121], v[220:223], v[102:105]
	v_mfma_f32_16x16x32_bf16 v[38:41], v[126:129], v[220:223], v[38:41]
	s_setprio 0
	s_add_i32 s54, 0, 0x14000
	v_add_u32_e32 v188, s54, v205
	s_add_i32 s52, s52, s23
	ds_read_b128 v[224:227], v188
	ds_read_b128 v[228:231], v188 offset:1024
	ds_read_b128 v[232:235], v188 offset:2048
	ds_read_b128 v[236:239], v188 offset:3072
	v_lshl_add_u64 v[188:189], s[44:45], 0, v[0:1]
	s_mov_b32 m0, s52
	v_lshl_add_u64 v[240:241], s[44:45], 0, v[158:159]
	global_load_lds_dwordx4 v[188:189], off
	s_add_i32 m0, s52, 0x2000
	s_nop 0
	global_load_lds_dwordx4 v[240:241], off
	s_barrier
	s_waitcnt lgkmcnt(0)
	s_setprio 1
	s_waitcnt lgkmcnt(0)
	v_mfma_f32_16x16x32_bf16 v[142:145], v[224:227], v[172:175], v[142:145]
	v_mfma_f32_16x16x32_bf16 v[62:65], v[232:235], v[172:175], v[62:65]
	v_mfma_f32_16x16x32_bf16 v[130:133], v[224:227], v[180:183], v[130:133]
	v_mfma_f32_16x16x32_bf16 v[50:53], v[232:235], v[180:183], v[50:53]
	v_mfma_f32_16x16x32_bf16 v[106:109], v[224:227], v[208:211], v[106:109]
	v_mfma_f32_16x16x32_bf16 v[42:45], v[232:235], v[208:211], v[42:45]
	v_mfma_f32_16x16x32_bf16 v[98:101], v[224:227], v[216:219], v[98:101]
	v_mfma_f32_16x16x32_bf16 v[34:37], v[232:235], v[216:219], v[34:37]
	v_mfma_f32_16x16x32_bf16 v[142:145], v[228:231], v[176:179], v[142:145]
	v_mfma_f32_16x16x32_bf16 v[62:65], v[236:239], v[176:179], v[62:65]
	v_mfma_f32_16x16x32_bf16 v[130:133], v[228:231], v[184:187], v[130:133]
	v_mfma_f32_16x16x32_bf16 v[50:53], v[236:239], v[184:187], v[50:53]
	v_mfma_f32_16x16x32_bf16 v[106:109], v[228:231], v[212:215], v[106:109]
	v_mfma_f32_16x16x32_bf16 v[42:45], v[236:239], v[212:215], v[42:45]
	s_setprio 2
	s_mov_b32 m0, s37
	v_lshl_add_u64 v[242:243], s[94:95], 0, v[162:163]
	s_barrier
	v_mfma_f32_16x16x32_bf16 v[98:101], v[228:231], v[220:223], v[98:101]
	v_mfma_f32_16x16x32_bf16 v[34:37], v[236:239], v[220:223], v[34:37]
	s_setprio 0
	ds_read_b128 v[172:175], v206 offset:16384
	ds_read_b128 v[176:179], v206 offset:17408
	ds_read_b128 v[180:183], v206 offset:18432
	ds_read_b128 v[184:187], v206 offset:19456
	ds_read_b128 v[208:211], v206 offset:20480
	ds_read_b128 v[212:215], v206 offset:21504
	ds_read_b128 v[216:219], v206 offset:22528
	ds_read_b128 v[220:223], v206 offset:23552
	global_load_lds_dwordx4 v[242:243], off
	v_lshl_add_u64 v[244:245], s[94:95], 0, v[160:161]
	s_mov_b32 m0, s40
	s_nop 0
	global_load_lds_dwordx4 v[244:245], off
	s_barrier
	s_waitcnt lgkmcnt(0)
	s_setprio 1
	s_waitcnt lgkmcnt(0)
	v_mfma_f32_16x16x32_bf16 v[94:97], v[114:117], v[172:175], v[94:97]
	v_mfma_f32_16x16x32_bf16 v[30:33], v[122:125], v[172:175], v[30:33]
	v_mfma_f32_16x16x32_bf16 v[86:89], v[114:117], v[180:183], v[86:89]
	v_mfma_f32_16x16x32_bf16 v[22:25], v[122:125], v[180:183], v[22:25]
	v_mfma_f32_16x16x32_bf16 v[78:81], v[114:117], v[208:211], v[78:81]
	v_mfma_f32_16x16x32_bf16 v[14:17], v[122:125], v[208:211], v[14:17]
	v_mfma_f32_16x16x32_bf16 v[70:73], v[114:117], v[216:219], v[70:73]
	v_mfma_f32_16x16x32_bf16 v[6:9], v[122:125], v[216:219], v[6:9]
	v_mfma_f32_16x16x32_bf16 v[94:97], v[118:121], v[176:179], v[94:97]
	v_mfma_f32_16x16x32_bf16 v[30:33], v[126:129], v[176:179], v[30:33]
	v_mfma_f32_16x16x32_bf16 v[86:89], v[118:121], v[184:187], v[86:89]
	v_mfma_f32_16x16x32_bf16 v[22:25], v[126:129], v[184:187], v[22:25]
	v_mfma_f32_16x16x32_bf16 v[78:81], v[118:121], v[212:215], v[78:81]
	v_mfma_f32_16x16x32_bf16 v[14:17], v[126:129], v[212:215], v[14:17]
	s_setprio 2
	s_barrier
	v_mfma_f32_16x16x32_bf16 v[70:73], v[118:121], v[220:223], v[70:73]
	v_mfma_f32_16x16x32_bf16 v[6:9], v[126:129], v[220:223], v[6:9]
	s_setprio 0
	s_add_u32 s52, s44, 0x80000
	s_addc_u32 s53, s45, 0
	s_add_i32 s54, s54, s23
	v_lshl_add_u64 v[114:115], s[52:53], 0, v[0:1]
	s_mov_b32 m0, s54
	s_nop 0
	global_load_lds_dwordx4 v[114:115], off
	v_lshl_add_u64 v[114:115], s[52:53], 0, v[158:159]
	s_add_i32 m0, s54, 0x2000
	s_nop 0
	global_load_lds_dwordx4 v[114:115], off
	s_waitcnt vmcnt(6)
	s_barrier
	s_setprio 1
	v_mfma_f32_16x16x32_bf16 v[90:93], v[224:227], v[172:175], v[90:93]
	v_mfma_f32_16x16x32_bf16 v[26:29], v[232:235], v[172:175], v[26:29]
	v_mfma_f32_16x16x32_bf16 v[82:85], v[224:227], v[180:183], v[82:85]
	v_mfma_f32_16x16x32_bf16 v[18:21], v[232:235], v[180:183], v[18:21]
	v_mfma_f32_16x16x32_bf16 v[74:77], v[224:227], v[208:211], v[74:77]
	v_mfma_f32_16x16x32_bf16 v[10:13], v[232:235], v[208:211], v[10:13]
	v_mfma_f32_16x16x32_bf16 v[66:69], v[224:227], v[216:219], v[66:69]
	v_mfma_f32_16x16x32_bf16 v[2:5], v[232:235], v[216:219], v[2:5]
	v_mfma_f32_16x16x32_bf16 v[90:93], v[228:231], v[176:179], v[90:93]
	v_mfma_f32_16x16x32_bf16 v[26:29], v[236:239], v[176:179], v[26:29]
	v_mfma_f32_16x16x32_bf16 v[82:85], v[228:231], v[184:187], v[82:85]
	v_mfma_f32_16x16x32_bf16 v[18:21], v[236:239], v[184:187], v[18:21]
	v_mfma_f32_16x16x32_bf16 v[74:77], v[228:231], v[212:215], v[74:77]
	v_mfma_f32_16x16x32_bf16 v[10:13], v[236:239], v[212:215], v[10:13]
	s_setprio 2
	s_add_i32 s54, 0, 0x18000
	v_add_u32_e32 v126, s54, v205
	s_barrier
	v_mfma_f32_16x16x32_bf16 v[66:69], v[228:231], v[220:223], v[66:69]
	v_mfma_f32_16x16x32_bf16 v[2:5], v[236:239], v[220:223], v[2:5]
	s_setprio 0
	ds_read_b128 v[114:117], v126
	ds_read_b128 v[118:121], v126 offset:1024
	ds_read_b128 v[122:125], v126 offset:2048
	ds_read_b128 v[126:129], v126 offset:3072
	s_add_u32 s52, s94, 0x80000
	s_addc_u32 s53, s95, 0
	s_mov_b32 m0, s41
	v_lshl_add_u64 v[224:225], s[52:53], 0, v[162:163]
	ds_read_b128 v[172:175], v206 offset:32768
	ds_read_b128 v[176:179], v206 offset:33792
	ds_read_b128 v[180:183], v206 offset:34816
	ds_read_b128 v[184:187], v206 offset:35840
	ds_read_b128 v[208:211], v206 offset:36864
	ds_read_b128 v[212:215], v206 offset:37888
	ds_read_b128 v[216:219], v206 offset:38912
	ds_read_b128 v[220:223], v206 offset:39936
	global_load_lds_dwordx4 v[224:225], off
	v_lshl_add_u64 v[224:225], s[52:53], 0, v[160:161]
	s_mov_b32 m0, s42
	s_nop 0
	global_load_lds_dwordx4 v[224:225], off
	s_waitcnt lgkmcnt(8)
	s_barrier
	s_waitcnt lgkmcnt(0)
	s_setprio 1
	s_waitcnt lgkmcnt(0)
	v_mfma_f32_16x16x32_bf16 v[138:141], v[114:117], v[172:175], v[138:141]
	v_mfma_f32_16x16x32_bf16 v[58:61], v[122:125], v[172:175], v[58:61]
	v_mfma_f32_16x16x32_bf16 v[134:137], v[114:117], v[180:183], v[134:137]
	v_mfma_f32_16x16x32_bf16 v[54:57], v[122:125], v[180:183], v[54:57]
	v_mfma_f32_16x16x32_bf16 v[110:113], v[114:117], v[208:211], v[110:113]
	v_mfma_f32_16x16x32_bf16 v[46:49], v[122:125], v[208:211], v[46:49]
	v_mfma_f32_16x16x32_bf16 v[102:105], v[114:117], v[216:219], v[102:105]
	v_mfma_f32_16x16x32_bf16 v[38:41], v[122:125], v[216:219], v[38:41]
	v_mfma_f32_16x16x32_bf16 v[138:141], v[118:121], v[176:179], v[138:141]
	v_mfma_f32_16x16x32_bf16 v[58:61], v[126:129], v[176:179], v[58:61]
	v_mfma_f32_16x16x32_bf16 v[134:137], v[118:121], v[184:187], v[134:137]
	v_mfma_f32_16x16x32_bf16 v[54:57], v[126:129], v[184:187], v[54:57]
	v_mfma_f32_16x16x32_bf16 v[110:113], v[118:121], v[212:215], v[110:113]
	v_mfma_f32_16x16x32_bf16 v[46:49], v[126:129], v[212:215], v[46:49]
	s_setprio 2
	s_barrier
	v_mfma_f32_16x16x32_bf16 v[102:105], v[118:121], v[220:223], v[102:105]
	v_mfma_f32_16x16x32_bf16 v[38:41], v[126:129], v[220:223], v[38:41]
	s_setprio 0
	s_add_i32 s52, 0, 0x1c000
	s_add_i32 s53, s54, s23
	v_add_u32_e32 v207, s52, v205
	v_lshl_add_u64 v[188:189], v[188:189], 0, s[62:63]
	s_mov_b32 m0, s53
	ds_read_b128 v[224:227], v207
	ds_read_b128 v[228:231], v207 offset:1024
	ds_read_b128 v[232:235], v207 offset:2048
	ds_read_b128 v[236:239], v207 offset:3072
	global_load_lds_dwordx4 v[188:189], off
	v_lshl_add_u64 v[188:189], v[240:241], 0, s[62:63]
	s_add_i32 m0, s53, 0x2000
	s_nop 0
	global_load_lds_dwordx4 v[188:189], off
	s_barrier
	s_waitcnt lgkmcnt(0)
	s_setprio 1
	s_waitcnt lgkmcnt(0)
	v_mfma_f32_16x16x32_bf16 v[142:145], v[224:227], v[172:175], v[142:145]
	v_mfma_f32_16x16x32_bf16 v[62:65], v[232:235], v[172:175], v[62:65]
	v_mfma_f32_16x16x32_bf16 v[130:133], v[224:227], v[180:183], v[130:133]
	v_mfma_f32_16x16x32_bf16 v[50:53], v[232:235], v[180:183], v[50:53]
	v_mfma_f32_16x16x32_bf16 v[106:109], v[224:227], v[208:211], v[106:109]
	v_mfma_f32_16x16x32_bf16 v[42:45], v[232:235], v[208:211], v[42:45]
	v_mfma_f32_16x16x32_bf16 v[98:101], v[224:227], v[216:219], v[98:101]
	v_mfma_f32_16x16x32_bf16 v[34:37], v[232:235], v[216:219], v[34:37]
	v_mfma_f32_16x16x32_bf16 v[142:145], v[228:231], v[176:179], v[142:145]
	v_mfma_f32_16x16x32_bf16 v[62:65], v[236:239], v[176:179], v[62:65]
	v_mfma_f32_16x16x32_bf16 v[130:133], v[228:231], v[184:187], v[130:133]
	v_mfma_f32_16x16x32_bf16 v[50:53], v[236:239], v[184:187], v[50:53]
	v_mfma_f32_16x16x32_bf16 v[106:109], v[228:231], v[212:215], v[106:109]
	v_mfma_f32_16x16x32_bf16 v[42:45], v[236:239], v[212:215], v[42:45]
	s_setprio 2
	s_mov_b32 m0, s46
	v_lshl_add_u64 v[188:189], v[242:243], 0, s[62:63]
	s_barrier
	v_mfma_f32_16x16x32_bf16 v[98:101], v[228:231], v[220:223], v[98:101]
	v_mfma_f32_16x16x32_bf16 v[34:37], v[236:239], v[220:223], v[34:37]
	s_setprio 0
	ds_read_b128 v[172:175], v206 offset:49152
	ds_read_b128 v[176:179], v206 offset:50176
	ds_read_b128 v[180:183], v206 offset:51200
	ds_read_b128 v[184:187], v206 offset:52224
	ds_read_b128 v[208:211], v206 offset:53248
	ds_read_b128 v[212:215], v206 offset:54272
	ds_read_b128 v[216:219], v206 offset:55296
	ds_read_b128 v[220:223], v206 offset:56320
	global_load_lds_dwordx4 v[188:189], off
	v_lshl_add_u64 v[188:189], v[244:245], 0, s[62:63]
	s_mov_b32 m0, s47
	s_nop 0
	global_load_lds_dwordx4 v[188:189], off
	s_barrier
	s_waitcnt lgkmcnt(0)
	s_setprio 1
	s_waitcnt lgkmcnt(0)
	v_mfma_f32_16x16x32_bf16 v[94:97], v[114:117], v[172:175], v[94:97]
	v_mfma_f32_16x16x32_bf16 v[30:33], v[122:125], v[172:175], v[30:33]
	v_mfma_f32_16x16x32_bf16 v[86:89], v[114:117], v[180:183], v[86:89]
	v_mfma_f32_16x16x32_bf16 v[22:25], v[122:125], v[180:183], v[22:25]
	v_mfma_f32_16x16x32_bf16 v[78:81], v[114:117], v[208:211], v[78:81]
	v_mfma_f32_16x16x32_bf16 v[14:17], v[122:125], v[208:211], v[14:17]
	v_mfma_f32_16x16x32_bf16 v[70:73], v[114:117], v[216:219], v[70:73]
	v_mfma_f32_16x16x32_bf16 v[6:9], v[122:125], v[216:219], v[6:9]
	v_mfma_f32_16x16x32_bf16 v[94:97], v[118:121], v[176:179], v[94:97]
	v_mfma_f32_16x16x32_bf16 v[30:33], v[126:129], v[176:179], v[30:33]
	v_mfma_f32_16x16x32_bf16 v[86:89], v[118:121], v[184:187], v[86:89]
	v_mfma_f32_16x16x32_bf16 v[22:25], v[126:129], v[184:187], v[22:25]
	v_mfma_f32_16x16x32_bf16 v[78:81], v[118:121], v[212:215], v[78:81]
	v_mfma_f32_16x16x32_bf16 v[14:17], v[126:129], v[212:215], v[14:17]
	s_setprio 2
	s_barrier
	v_mfma_f32_16x16x32_bf16 v[70:73], v[118:121], v[220:223], v[70:73]
	v_mfma_f32_16x16x32_bf16 v[6:9], v[126:129], v[220:223], v[6:9]
	s_setprio 0
	s_add_u32 s44, s44, 0x80080
	s_addc_u32 s45, s45, 0
	s_add_i32 s52, s52, s23
	v_lshl_add_u64 v[114:115], s[44:45], 0, v[0:1]
	s_mov_b32 m0, s52
	s_nop 0
	global_load_lds_dwordx4 v[114:115], off
	v_lshl_add_u64 v[114:115], s[44:45], 0, v[158:159]
	s_add_i32 m0, s52, 0x2000
	s_nop 0
	global_load_lds_dwordx4 v[114:115], off
	s_waitcnt vmcnt(6)
	s_barrier
	s_setprio 1
	v_mfma_f32_16x16x32_bf16 v[90:93], v[224:227], v[172:175], v[90:93]
	v_mfma_f32_16x16x32_bf16 v[26:29], v[232:235], v[172:175], v[26:29]
	v_mfma_f32_16x16x32_bf16 v[82:85], v[224:227], v[180:183], v[82:85]
	v_mfma_f32_16x16x32_bf16 v[18:21], v[232:235], v[180:183], v[18:21]
	v_mfma_f32_16x16x32_bf16 v[74:77], v[224:227], v[208:211], v[74:77]
	v_mfma_f32_16x16x32_bf16 v[10:13], v[232:235], v[208:211], v[10:13]
	v_mfma_f32_16x16x32_bf16 v[66:69], v[224:227], v[216:219], v[66:69]
	v_mfma_f32_16x16x32_bf16 v[2:5], v[232:235], v[216:219], v[2:5]
	v_mfma_f32_16x16x32_bf16 v[90:93], v[228:231], v[176:179], v[90:93]
	v_mfma_f32_16x16x32_bf16 v[26:29], v[236:239], v[176:179], v[26:29]
	v_mfma_f32_16x16x32_bf16 v[82:85], v[228:231], v[184:187], v[82:85]
	v_mfma_f32_16x16x32_bf16 v[18:21], v[236:239], v[184:187], v[18:21]
	v_mfma_f32_16x16x32_bf16 v[74:77], v[228:231], v[212:215], v[74:77]
	v_mfma_f32_16x16x32_bf16 v[10:13], v[236:239], v[212:215], v[10:13]
	s_setprio 2
	s_add_i32 s51, s51, 2
	s_add_u32 s92, s92, 0x100
	s_addc_u32 s93, s93, 0
	s_add_u32 s49, s49, 0x100
	s_addc_u32 s50, s50, 0
	s_cmp_gt_u32 s51, 29
	s_barrier
	v_mfma_f32_16x16x32_bf16 v[66:69], v[228:231], v[220:223], v[66:69]
	v_mfma_f32_16x16x32_bf16 v[2:5], v[236:239], v[220:223], v[2:5]
	s_setprio 0
	s_cbranch_scc0 .LBB0_1420
	v_lshl_or_b32 v174, s5, 7, v167
	v_ashrrev_i32_e32 v175, 31, v174
	v_lshlrev_b64 v[180:181], 2, v[174:175]
	v_lshl_add_u64 v[176:177], s[76:77], 0, v[180:181]
	v_lshl_add_u64 v[118:119], s[82:83], 0, v[180:181]
	v_lshl_add_u64 v[120:121], s[84:85], 0, v[180:181]
	v_lshl_add_u64 v[178:179], s[80:81], 0, v[180:181]
	global_load_dwordx4 v[114:117], v[176:177], off
	global_load_dwordx4 v[220:223], v[176:177], off offset:16
	global_load_dwordx4 v[122:125], v[118:119], off
	global_load_dwordx4 v[224:227], v[118:119], off offset:16
	global_load_dwordx4 v[228:231], v[120:121], off offset:16
	global_load_dwordx4 v[118:121], v[120:121], off
	s_lshl_b32 s4, s4, 8
	global_load_dwordx4 v[126:129], v[178:179], off
	global_load_dwordx4 v[232:235], v[178:179], off offset:16
	s_and_b32 s4, s4, 0x3f00
	s_add_i32 s4, s4, s43
	v_or_b32_e32 v207, s4, v164
	v_lshl_add_u64 v[172:173], v[174:175], 1, s[78:79]
	v_mov_b32_dpp v186, v138 row_shr:1 row_mask:0xf bank_mask:0xf bound_ctrl:1
	v_mov_b32_dpp v188, v138 row_shr:2 row_mask:0xf bank_mask:0xf bound_ctrl:1
	v_mov_b32_dpp v187, v139 row_shr:1 row_mask:0xf bank_mask:0xf bound_ctrl:1
	v_mov_b32_dpp v189, v139 row_shr:2 row_mask:0xf bank_mask:0xf bound_ctrl:1
	v_mov_b32_dpp v182, v140 row_shr:1 row_mask:0xf bank_mask:0xf bound_ctrl:1
	v_mov_b32_dpp v184, v140 row_shr:2 row_mask:0xf bank_mask:0xf bound_ctrl:1
	v_mov_b32_dpp v183, v141 row_shr:1 row_mask:0xf bank_mask:0xf bound_ctrl:1
	v_mov_b32_dpp v185, v141 row_shr:2 row_mask:0xf bank_mask:0xf bound_ctrl:1
	s_and_saveexec_b64 s[6:7], s[10:11]
	s_xor_b64 s[6:7], exec, s[6:7]
	s_cbranch_execz .LBB0_1423
	s_waitcnt vmcnt(0)
	v_pk_fma_f32 v[188:189], v[114:115], v[188:189], v[126:127]
	v_pk_fma_f32 v[184:185], v[116:117], v[184:185], v[128:129]
	v_pk_fma_f32 v[186:187], v[122:123], v[186:187], v[188:189]
	v_pk_fma_f32 v[182:183], v[124:125], v[182:183], v[184:185]
	v_pk_fma_f32 v[186:187], v[138:139], v[118:119], v[186:187]
	v_pk_fma_f32 v[182:183], v[140:141], v[120:121], v[182:183]
	v_mul_f32_e32 v175, 0xbfb8aa3b, v186
	v_exp_f32_e32 v175, v175
	v_mul_f32_e32 v188, 0xbfb8aa3b, v187
	v_exp_f32_e32 v188, v188
	v_mul_f32_e32 v184, 0xbfb8aa3b, v183
	v_add_f32_e32 v175, 1.0, v175
	v_exp_f32_e32 v185, v184
	v_add_f32_e32 v189, 1.0, v188
	v_rcp_f32_e32 v188, v175
	v_mul_f32_e32 v175, 0xbfb8aa3b, v182
	v_exp_f32_e32 v175, v175
	v_rcp_f32_e32 v189, v189
	v_add_f32_e32 v175, 1.0, v175
	v_rcp_f32_e32 v184, v175
	v_add_f32_e32 v175, 1.0, v185
	v_rcp_f32_e32 v185, v175
	v_pk_mul_f32 v[186:187], v[186:187], v[188:189]
	v_pk_mul_f32 v[182:183], v[182:183], v[184:185]
	v_pk_mul_f32 v[186:187], v[142:143], v[186:187]
	v_pk_mul_f32 v[182:183], v[144:145], v[182:183]
	v_cvt_pk_bf16_f32 v184, v186, v187
	v_cvt_pk_bf16_f32 v185, v182, v183
	v_mad_i64_i32 v[182:183], s[18:19], v207, s39, v[172:173]
	global_store_dwordx2 v[182:183], v[184:185], off

.LBB0_1617:
	s_add_u32 s68, s64, 0x100
	s_addc_u32 s69, s65, 0
	s_add_i32 s48, 0, 0x10000
	v_add_u32_e32 v102, s48, v187
	ds_read_b128 v[90:93], v102
	ds_read_b128 v[94:97], v102 offset:1024
	ds_read_b128 v[98:101], v102 offset:2048
	ds_read_b128 v[102:105], v102 offset:3072
	s_cmpk_eq_i32 s47, 0x54
	s_cselect_b32 s81, s11, s69
	s_cselect_b32 s80, s10, s68
	s_cselect_b32 s45, s13, s5
	s_cselect_b32 s44, s12, s4
	v_lshl_add_u64 v[184:185], s[64:65], 0, v[164:165]
	s_add_i32 m0, s27, 0xc000
	ds_read_b128 v[168:171], v189
	ds_read_b128 v[172:175], v189 offset:1024
	ds_read_b128 v[176:179], v189 offset:2048
	ds_read_b128 v[180:183], v189 offset:3072
	ds_read_b128 v[206:209], v189 offset:4096
	ds_read_b128 v[210:213], v189 offset:5120
	ds_read_b128 v[214:217], v189 offset:6144
	ds_read_b128 v[218:221], v189 offset:7168
	global_load_lds_dwordx4 v[184:185], off
	v_lshl_add_u64 v[184:185], s[64:65], 0, v[166:167]
	s_add_i32 m0, s27, 0xe000
	s_nop 0
	global_load_lds_dwordx4 v[184:185], off
	s_waitcnt lgkmcnt(8)
	s_barrier
	s_waitcnt lgkmcnt(0)
	s_setprio 1
	s_waitcnt lgkmcnt(0)
	v_mfma_f32_16x16x32_bf16 v[142:145], v[90:93], v[168:171], v[142:145]
	v_mfma_f32_16x16x32_bf16 v[138:141], v[98:101], v[168:171], v[138:141]
	v_mfma_f32_16x16x32_bf16 v[134:137], v[90:93], v[176:179], v[134:137]
	v_mfma_f32_16x16x32_bf16 v[130:133], v[98:101], v[176:179], v[130:133]
	v_mfma_f32_16x16x32_bf16 v[126:129], v[90:93], v[206:209], v[126:129]
	v_mfma_f32_16x16x32_bf16 v[122:125], v[98:101], v[206:209], v[122:125]
	v_mfma_f32_16x16x32_bf16 v[118:121], v[90:93], v[214:217], v[118:121]
	v_mfma_f32_16x16x32_bf16 v[114:117], v[98:101], v[214:217], v[114:117]
	v_mfma_f32_16x16x32_bf16 v[142:145], v[94:97], v[172:175], v[142:145]
	v_mfma_f32_16x16x32_bf16 v[138:141], v[102:105], v[172:175], v[138:141]
	v_mfma_f32_16x16x32_bf16 v[134:137], v[94:97], v[180:183], v[134:137]
	v_mfma_f32_16x16x32_bf16 v[130:133], v[102:105], v[180:183], v[130:133]
	v_mfma_f32_16x16x32_bf16 v[126:129], v[94:97], v[210:213], v[126:129]
	v_mfma_f32_16x16x32_bf16 v[122:125], v[102:105], v[210:213], v[122:125]
	s_setprio 2
	s_barrier
	v_mfma_f32_16x16x32_bf16 v[118:121], v[94:97], v[218:221], v[118:121]
	v_mfma_f32_16x16x32_bf16 v[114:117], v[102:105], v[218:221], v[114:117]
	s_setprio 0
	s_add_i32 s50, 0, 0x14000
	v_add_u32_e32 v184, s50, v187
	s_add_i32 s48, s48, s22
	ds_read_b128 v[222:225], v184
	ds_read_b128 v[226:229], v184 offset:1024
	ds_read_b128 v[230:233], v184 offset:2048
	ds_read_b128 v[234:237], v184 offset:3072
	v_lshl_add_u64 v[184:185], s[44:45], 0, v[0:1]
	s_mov_b32 m0, s48
	v_lshl_add_u64 v[238:239], s[44:45], 0, v[158:159]
	global_load_lds_dwordx4 v[184:185], off
	s_add_i32 m0, s48, 0x2000
	s_nop 0
	global_load_lds_dwordx4 v[238:239], off
	s_barrier
	s_waitcnt lgkmcnt(0)
	s_setprio 1
	s_waitcnt lgkmcnt(0)
	v_mfma_f32_16x16x32_bf16 v[62:65], v[222:225], v[168:171], v[62:65]
	v_mfma_f32_16x16x32_bf16 v[58:61], v[230:233], v[168:171], v[58:61]
	v_mfma_f32_16x16x32_bf16 v[54:57], v[222:225], v[176:179], v[54:57]
	v_mfma_f32_16x16x32_bf16 v[50:53], v[230:233], v[176:179], v[50:53]
	v_mfma_f32_16x16x32_bf16 v[46:49], v[222:225], v[206:209], v[46:49]
	v_mfma_f32_16x16x32_bf16 v[42:45], v[230:233], v[206:209], v[42:45]
	v_mfma_f32_16x16x32_bf16 v[38:41], v[222:225], v[214:217], v[38:41]
	v_mfma_f32_16x16x32_bf16 v[34:37], v[230:233], v[214:217], v[34:37]
	v_mfma_f32_16x16x32_bf16 v[62:65], v[226:229], v[172:175], v[62:65]
	v_mfma_f32_16x16x32_bf16 v[58:61], v[234:237], v[172:175], v[58:61]
	v_mfma_f32_16x16x32_bf16 v[54:57], v[226:229], v[180:183], v[54:57]
	v_mfma_f32_16x16x32_bf16 v[50:53], v[234:237], v[180:183], v[50:53]
	v_mfma_f32_16x16x32_bf16 v[46:49], v[226:229], v[210:213], v[46:49]
	v_mfma_f32_16x16x32_bf16 v[42:45], v[234:237], v[210:213], v[42:45]
	s_setprio 2
	s_mov_b32 m0, s27
	v_lshl_add_u64 v[240:241], s[80:81], 0, v[162:163]
	s_barrier
	v_mfma_f32_16x16x32_bf16 v[38:41], v[226:229], v[218:221], v[38:41]
	v_mfma_f32_16x16x32_bf16 v[34:37], v[234:237], v[218:221], v[34:37]
	s_setprio 0
	ds_read_b128 v[168:171], v189 offset:16384
	ds_read_b128 v[172:175], v189 offset:17408
	ds_read_b128 v[176:179], v189 offset:18432
	ds_read_b128 v[180:183], v189 offset:19456
	ds_read_b128 v[206:209], v189 offset:20480
	ds_read_b128 v[210:213], v189 offset:21504
	ds_read_b128 v[214:217], v189 offset:22528
	ds_read_b128 v[218:221], v189 offset:23552
	global_load_lds_dwordx4 v[240:241], off
	v_lshl_add_u64 v[242:243], s[80:81], 0, v[160:161]
	s_mov_b32 m0, s36
	s_nop 0
	global_load_lds_dwordx4 v[242:243], off
	s_barrier
	s_waitcnt lgkmcnt(0)
	s_setprio 1
	s_waitcnt lgkmcnt(0)
	v_mfma_f32_16x16x32_bf16 v[110:113], v[90:93], v[168:171], v[110:113]
	v_mfma_f32_16x16x32_bf16 v[106:109], v[98:101], v[168:171], v[106:109]
	v_mfma_f32_16x16x32_bf16 v[86:89], v[90:93], v[176:179], v[86:89]
	v_mfma_f32_16x16x32_bf16 v[82:85], v[98:101], v[176:179], v[82:85]
	v_mfma_f32_16x16x32_bf16 v[78:81], v[90:93], v[206:209], v[78:81]
	v_mfma_f32_16x16x32_bf16 v[74:77], v[98:101], v[206:209], v[74:77]
	v_mfma_f32_16x16x32_bf16 v[70:73], v[90:93], v[214:217], v[70:73]
	v_mfma_f32_16x16x32_bf16 v[66:69], v[98:101], v[214:217], v[66:69]
	v_mfma_f32_16x16x32_bf16 v[110:113], v[94:97], v[172:175], v[110:113]
	v_mfma_f32_16x16x32_bf16 v[106:109], v[102:105], v[172:175], v[106:109]
	v_mfma_f32_16x16x32_bf16 v[86:89], v[94:97], v[180:183], v[86:89]
	v_mfma_f32_16x16x32_bf16 v[82:85], v[102:105], v[180:183], v[82:85]
	v_mfma_f32_16x16x32_bf16 v[78:81], v[94:97], v[210:213], v[78:81]
	v_mfma_f32_16x16x32_bf16 v[74:77], v[102:105], v[210:213], v[74:77]
	s_setprio 2
	s_barrier
	v_mfma_f32_16x16x32_bf16 v[70:73], v[94:97], v[218:221], v[70:73]
	v_mfma_f32_16x16x32_bf16 v[66:69], v[102:105], v[218:221], v[66:69]
	s_setprio 0
	s_add_u32 s48, s44, 0x160000
	s_addc_u32 s49, s45, 0
	s_add_i32 s50, s50, s22
	v_lshl_add_u64 v[90:91], s[48:49], 0, v[0:1]
	s_mov_b32 m0, s50
	s_nop 0
	global_load_lds_dwordx4 v[90:91], off
	v_lshl_add_u64 v[90:91], s[48:49], 0, v[158:159]
	s_add_i32 m0, s50, 0x2000
	s_nop 0
	global_load_lds_dwordx4 v[90:91], off
	s_waitcnt vmcnt(6)
	s_barrier
	s_setprio 1
	v_mfma_f32_16x16x32_bf16 v[30:33], v[222:225], v[168:171], v[30:33]
	v_mfma_f32_16x16x32_bf16 v[26:29], v[230:233], v[168:171], v[26:29]
	v_mfma_f32_16x16x32_bf16 v[22:25], v[222:225], v[176:179], v[22:25]
	v_mfma_f32_16x16x32_bf16 v[18:21], v[230:233], v[176:179], v[18:21]
	v_mfma_f32_16x16x32_bf16 v[14:17], v[222:225], v[206:209], v[14:17]
	v_mfma_f32_16x16x32_bf16 v[10:13], v[230:233], v[206:209], v[10:13]
	v_mfma_f32_16x16x32_bf16 v[6:9], v[222:225], v[214:217], v[6:9]
	v_mfma_f32_16x16x32_bf16 v[2:5], v[230:233], v[214:217], v[2:5]
	v_mfma_f32_16x16x32_bf16 v[30:33], v[226:229], v[172:175], v[30:33]
	v_mfma_f32_16x16x32_bf16 v[26:29], v[234:237], v[172:175], v[26:29]
	v_mfma_f32_16x16x32_bf16 v[22:25], v[226:229], v[180:183], v[22:25]
	v_mfma_f32_16x16x32_bf16 v[18:21], v[234:237], v[180:183], v[18:21]
	v_mfma_f32_16x16x32_bf16 v[14:17], v[226:229], v[210:213], v[14:17]
	v_mfma_f32_16x16x32_bf16 v[10:13], v[234:237], v[210:213], v[10:13]
	s_setprio 2
	s_add_i32 s50, 0, 0x18000
	v_add_u32_e32 v102, s50, v187
	s_barrier
	v_mfma_f32_16x16x32_bf16 v[6:9], v[226:229], v[218:221], v[6:9]
	v_mfma_f32_16x16x32_bf16 v[2:5], v[234:237], v[218:221], v[2:5]
	s_setprio 0
	ds_read_b128 v[90:93], v102
	ds_read_b128 v[94:97], v102 offset:1024
	ds_read_b128 v[98:101], v102 offset:2048
	ds_read_b128 v[102:105], v102 offset:3072
	s_add_u32 s48, s80, 0x160000
	s_addc_u32 s49, s81, 0
	s_mov_b32 m0, s37
	v_lshl_add_u64 v[222:223], s[48:49], 0, v[162:163]
	ds_read_b128 v[168:171], v189 offset:32768
	ds_read_b128 v[172:175], v189 offset:33792
	ds_read_b128 v[176:179], v189 offset:34816
	ds_read_b128 v[180:183], v189 offset:35840
	ds_read_b128 v[206:209], v189 offset:36864
	ds_read_b128 v[210:213], v189 offset:37888
	ds_read_b128 v[214:217], v189 offset:38912
	ds_read_b128 v[218:221], v189 offset:39936
	global_load_lds_dwordx4 v[222:223], off
	v_lshl_add_u64 v[222:223], s[48:49], 0, v[160:161]
	s_mov_b32 m0, s40
	s_nop 0
	global_load_lds_dwordx4 v[222:223], off
	s_waitcnt lgkmcnt(8)
	s_barrier
	s_waitcnt lgkmcnt(0)
	s_setprio 1
	s_waitcnt lgkmcnt(0)
	v_mfma_f32_16x16x32_bf16 v[142:145], v[90:93], v[168:171], v[142:145]
	v_mfma_f32_16x16x32_bf16 v[138:141], v[98:101], v[168:171], v[138:141]
	v_mfma_f32_16x16x32_bf16 v[134:137], v[90:93], v[176:179], v[134:137]
	v_mfma_f32_16x16x32_bf16 v[130:133], v[98:101], v[176:179], v[130:133]
	v_mfma_f32_16x16x32_bf16 v[126:129], v[90:93], v[206:209], v[126:129]
	v_mfma_f32_16x16x32_bf16 v[122:125], v[98:101], v[206:209], v[122:125]
	v_mfma_f32_16x16x32_bf16 v[118:121], v[90:93], v[214:217], v[118:121]
	v_mfma_f32_16x16x32_bf16 v[114:117], v[98:101], v[214:217], v[114:117]
	v_mfma_f32_16x16x32_bf16 v[142:145], v[94:97], v[172:175], v[142:145]
	v_mfma_f32_16x16x32_bf16 v[138:141], v[102:105], v[172:175], v[138:141]
	v_mfma_f32_16x16x32_bf16 v[134:137], v[94:97], v[180:183], v[134:137]
	v_mfma_f32_16x16x32_bf16 v[130:133], v[102:105], v[180:183], v[130:133]
	v_mfma_f32_16x16x32_bf16 v[126:129], v[94:97], v[210:213], v[126:129]
	v_mfma_f32_16x16x32_bf16 v[122:125], v[102:105], v[210:213], v[122:125]
	s_setprio 2
	s_barrier
	v_mfma_f32_16x16x32_bf16 v[118:121], v[94:97], v[218:221], v[118:121]
	v_mfma_f32_16x16x32_bf16 v[114:117], v[102:105], v[218:221], v[114:117]
	s_setprio 0
	s_add_i32 s48, 0, 0x1c000
	s_add_i32 s49, s50, s22
	v_add_u32_e32 v205, s48, v187
	v_lshl_add_u64 v[184:185], v[184:185], 0, s[62:63]
	s_mov_b32 m0, s49
	ds_read_b128 v[222:225], v205
	ds_read_b128 v[226:229], v205 offset:1024
	ds_read_b128 v[230:233], v205 offset:2048
	ds_read_b128 v[234:237], v205 offset:3072
	global_load_lds_dwordx4 v[184:185], off
	v_lshl_add_u64 v[184:185], v[238:239], 0, s[62:63]
	s_add_i32 m0, s49, 0x2000
	s_nop 0
	global_load_lds_dwordx4 v[184:185], off
	s_barrier
	s_waitcnt lgkmcnt(0)
	s_setprio 1
	s_waitcnt lgkmcnt(0)
	v_mfma_f32_16x16x32_bf16 v[62:65], v[222:225], v[168:171], v[62:65]
	v_mfma_f32_16x16x32_bf16 v[58:61], v[230:233], v[168:171], v[58:61]
	v_mfma_f32_16x16x32_bf16 v[54:57], v[222:225], v[176:179], v[54:57]
	v_mfma_f32_16x16x32_bf16 v[50:53], v[230:233], v[176:179], v[50:53]
	v_mfma_f32_16x16x32_bf16 v[46:49], v[222:225], v[206:209], v[46:49]
	v_mfma_f32_16x16x32_bf16 v[42:45], v[230:233], v[206:209], v[42:45]
	v_mfma_f32_16x16x32_bf16 v[38:41], v[222:225], v[214:217], v[38:41]
	v_mfma_f32_16x16x32_bf16 v[34:37], v[230:233], v[214:217], v[34:37]
	v_mfma_f32_16x16x32_bf16 v[62:65], v[226:229], v[172:175], v[62:65]
	v_mfma_f32_16x16x32_bf16 v[58:61], v[234:237], v[172:175], v[58:61]
	v_mfma_f32_16x16x32_bf16 v[54:57], v[226:229], v[180:183], v[54:57]
	v_mfma_f32_16x16x32_bf16 v[50:53], v[234:237], v[180:183], v[50:53]
	v_mfma_f32_16x16x32_bf16 v[46:49], v[226:229], v[210:213], v[46:49]
	v_mfma_f32_16x16x32_bf16 v[42:45], v[234:237], v[210:213], v[42:45]
	s_setprio 2
	s_mov_b32 m0, s28
	v_lshl_add_u64 v[184:185], v[240:241], 0, s[62:63]
	s_barrier
	v_mfma_f32_16x16x32_bf16 v[38:41], v[226:229], v[218:221], v[38:41]
	v_mfma_f32_16x16x32_bf16 v[34:37], v[234:237], v[218:221], v[34:37]
	s_setprio 0
	ds_read_b128 v[168:171], v189 offset:49152
	ds_read_b128 v[172:175], v189 offset:50176
	ds_read_b128 v[176:179], v189 offset:51200
	ds_read_b128 v[180:183], v189 offset:52224
	ds_read_b128 v[206:209], v189 offset:53248
	ds_read_b128 v[210:213], v189 offset:54272
	ds_read_b128 v[214:217], v189 offset:55296
	ds_read_b128 v[218:221], v189 offset:56320
	global_load_lds_dwordx4 v[184:185], off
	v_lshl_add_u64 v[184:185], v[242:243], 0, s[62:63]
	s_mov_b32 m0, s41
	s_nop 0
	global_load_lds_dwordx4 v[184:185], off
	s_barrier
	s_waitcnt lgkmcnt(0)
	s_setprio 1
	s_waitcnt lgkmcnt(0)
	v_mfma_f32_16x16x32_bf16 v[110:113], v[90:93], v[168:171], v[110:113]
	v_mfma_f32_16x16x32_bf16 v[106:109], v[98:101], v[168:171], v[106:109]
	v_mfma_f32_16x16x32_bf16 v[86:89], v[90:93], v[176:179], v[86:89]
	v_mfma_f32_16x16x32_bf16 v[82:85], v[98:101], v[176:179], v[82:85]
	v_mfma_f32_16x16x32_bf16 v[78:81], v[90:93], v[206:209], v[78:81]
	v_mfma_f32_16x16x32_bf16 v[74:77], v[98:101], v[206:209], v[74:77]
	v_mfma_f32_16x16x32_bf16 v[70:73], v[90:93], v[214:217], v[70:73]
	v_mfma_f32_16x16x32_bf16 v[66:69], v[98:101], v[214:217], v[66:69]
	v_mfma_f32_16x16x32_bf16 v[110:113], v[94:97], v[172:175], v[110:113]
	v_mfma_f32_16x16x32_bf16 v[106:109], v[102:105], v[172:175], v[106:109]
	v_mfma_f32_16x16x32_bf16 v[86:89], v[94:97], v[180:183], v[86:89]
	v_mfma_f32_16x16x32_bf16 v[82:85], v[102:105], v[180:183], v[82:85]
	v_mfma_f32_16x16x32_bf16 v[78:81], v[94:97], v[210:213], v[78:81]
	v_mfma_f32_16x16x32_bf16 v[74:77], v[102:105], v[210:213], v[74:77]
	s_setprio 2
	s_barrier
	v_mfma_f32_16x16x32_bf16 v[70:73], v[94:97], v[218:221], v[70:73]
	v_mfma_f32_16x16x32_bf16 v[66:69], v[102:105], v[218:221], v[66:69]
	s_setprio 0
	s_add_u32 s44, s44, 0x160080
	s_addc_u32 s45, s45, 0
	s_add_i32 s48, s48, s22
	v_lshl_add_u64 v[90:91], s[44:45], 0, v[0:1]
	s_mov_b32 m0, s48
	s_nop 0
	global_load_lds_dwordx4 v[90:91], off
	v_lshl_add_u64 v[90:91], s[44:45], 0, v[158:159]
	s_add_i32 m0, s48, 0x2000
	s_nop 0
	global_load_lds_dwordx4 v[90:91], off
	s_waitcnt vmcnt(6)
	s_barrier
	s_setprio 1
	v_mfma_f32_16x16x32_bf16 v[30:33], v[222:225], v[168:171], v[30:33]
	v_mfma_f32_16x16x32_bf16 v[26:29], v[230:233], v[168:171], v[26:29]
	v_mfma_f32_16x16x32_bf16 v[22:25], v[222:225], v[176:179], v[22:25]
	v_mfma_f32_16x16x32_bf16 v[18:21], v[230:233], v[176:179], v[18:21]
	v_mfma_f32_16x16x32_bf16 v[14:17], v[222:225], v[206:209], v[14:17]
	v_mfma_f32_16x16x32_bf16 v[10:13], v[230:233], v[206:209], v[10:13]
	v_mfma_f32_16x16x32_bf16 v[6:9], v[222:225], v[214:217], v[6:9]
	v_mfma_f32_16x16x32_bf16 v[2:5], v[230:233], v[214:217], v[2:5]
	v_mfma_f32_16x16x32_bf16 v[30:33], v[226:229], v[172:175], v[30:33]
	v_mfma_f32_16x16x32_bf16 v[26:29], v[234:237], v[172:175], v[26:29]
	v_mfma_f32_16x16x32_bf16 v[22:25], v[226:229], v[180:183], v[22:25]
	v_mfma_f32_16x16x32_bf16 v[18:21], v[234:237], v[180:183], v[18:21]
	v_mfma_f32_16x16x32_bf16 v[14:17], v[226:229], v[210:213], v[14:17]
	v_mfma_f32_16x16x32_bf16 v[10:13], v[234:237], v[210:213], v[10:13]
	s_setprio 2
	s_add_i32 s47, s47, 2
	s_add_u32 s4, s4, 0x100
	s_addc_u32 s5, s5, 0
	s_cmpk_gt_u32 s47, 0x55
	s_mov_b64 s[64:65], s[68:69]
	s_barrier
	v_mfma_f32_16x16x32_bf16 v[6:9], v[226:229], v[218:221], v[6:9]
	v_mfma_f32_16x16x32_bf16 v[2:5], v[234:237], v[218:221], v[2:5]
	s_setprio 0
	s_cbranch_scc0 .LBB0_1617
	s_lshl_b32 s4, s46, 8
	s_and_b32 s4, s4, 0x3f00
	v_add_u32_e32 v178, s4, v186
	s_ashr_i32 s4, s43, 31
	s_lshr_b32 s4, s4, 29
	s_add_i32 s4, s43, s4
	s_and_b32 s4, s4, 0xfffff8
	s_sub_i32 s4, s43, s4
	v_lshl_or_b32 v172, s4, 8, v188
	v_ashrrev_i32_e32 v173, 31, v172
	v_ashrrev_i32_e32 v179, 31, v178
	v_lshlrev_b32_e32 v170, 12, v178
	v_lshl_add_u32 v170, v172, 1, v170
	v_lshlrev_b32_e32 v171, 3, v178
	v_lshlrev_b32_e32 v174, 2, v172
	global_load_dwordx4 v[98:101], v174, s[74:75]
	global_load_dwordx4 v[90:93], v174, s[74:75] offset:16
	global_load_dwordx4 v[102:105], v174, s[76:77]
	global_load_dwordx4 v[94:97], v174, s[76:77] offset:16
	s_add_u32 s48, s72, 0x0
	s_addc_u32 s49, s73, 0
	global_load_dwordx4 v[220:223], v170, s[48:49]
	s_add_u32 s50, s14, 0x0
	s_addc_u32 s51, s15, 0
	global_load_dwordx2 v[176:177], v171, s[50:51]
	s_add_u32 s48, s72, 0x10000
	s_addc_u32 s49, s73, 0
	global_load_dwordx4 v[224:227], v170, s[48:49]
	s_add_u32 s50, s14, 0x80
	s_addc_u32 s51, s15, 0
	global_load_dwordx2 v[180:181], v171, s[50:51]
	s_add_u32 s48, s72, 0x20000
	s_addc_u32 s49, s73, 0
	global_load_dwordx4 v[228:231], v170, s[48:49]
	s_add_u32 s50, s14, 0x100
	s_addc_u32 s51, s15, 0
	global_load_dwordx2 v[182:183], v171, s[50:51]
	s_add_u32 s48, s72, 0x30000
	s_addc_u32 s49, s73, 0
	global_load_dwordx4 v[232:235], v170, s[48:49]
	s_add_u32 s50, s14, 0x180
	s_addc_u32 s51, s15, 0
	global_load_dwordx2 v[184:185], v171, s[50:51]
	s_add_u32 s48, s72, 0x80000
	s_addc_u32 s49, s73, 0
	global_load_dwordx4 v[236:239], v170, s[48:49]
	s_add_u32 s50, s14, 0x400
	s_addc_u32 s51, s15, 0
	global_load_dwordx2 v[168:169], v171, s[50:51]
	s_add_u32 s48, s72, 0x90000
	s_addc_u32 s49, s73, 0
	global_load_dwordx4 v[240:243], v170, s[48:49]
	s_add_u32 s50, s14, 0x480
	s_addc_u32 s51, s15, 0
	global_load_dwordx2 v[252:253], v171, s[50:51]
	s_add_u32 s48, s72, 0xa0000
	s_addc_u32 s49, s73, 0
	global_load_dwordx4 v[244:247], v170, s[48:49]
	s_add_u32 s50, s14, 0x500
	s_addc_u32 s51, s15, 0
	global_load_dwordx2 v[214:215], v171, s[50:51]
	s_add_u32 s48, s72, 0xb0000
	s_addc_u32 s49, s73, 0
	global_load_dwordx4 v[248:251], v170, s[48:49]
	s_add_u32 s50, s14, 0x580
	s_addc_u32 s51, s15, 0
	global_load_dwordx2 v[216:217], v171, s[50:51]
	s_waitcnt vmcnt(14)
	v_lshlrev_b32_e32 v206, 16, v220
	v_and_b32_e32 v207, 0xffff0000, v220
	v_lshlrev_b32_e32 v208, 16, v221
	v_and_b32_e32 v209, 0xffff0000, v221
	v_lshlrev_b32_e32 v210, 16, v222
	v_and_b32_e32 v211, 0xffff0000, v222
	v_lshlrev_b32_e32 v212, 16, v223
	v_and_b32_e32 v213, 0xffff0000, v223
	v_sub_f32_e32 v206, v206, v176
	v_sub_f32_e32 v207, v207, v176
	v_sub_f32_e32 v208, v208, v176
	v_sub_f32_e32 v209, v209, v176
	v_sub_f32_e32 v210, v210, v176
	v_sub_f32_e32 v211, v211, v176
	v_sub_f32_e32 v212, v212, v176
	v_sub_f32_e32 v213, v213, v176
	v_pk_mul_f32 v[206:207], v[176:177], v[206:207] op_sel:[1,0]
	v_pk_mul_f32 v[208:209], v[176:177], v[208:209] op_sel:[1,0]
	v_pk_mul_f32 v[210:211], v[176:177], v[210:211] op_sel:[1,0]
	v_pk_mul_f32 v[212:213], v[176:177], v[212:213] op_sel:[1,0]
	v_pk_fma_f32 v[206:207], v[98:99], v[206:207], v[102:103]
	v_pk_fma_f32 v[208:209], v[100:101], v[208:209], v[104:105]
	v_pk_fma_f32 v[210:211], v[90:91], v[210:211], v[94:95]
	v_pk_fma_f32 v[212:213], v[92:93], v[212:213], v[96:97]
	v_pk_fma_f32 v[206:207], v[206:207], s[66:67], v[142:143] op_sel_hi:[1,0,1]
	v_pk_fma_f32 v[208:209], v[208:209], s[66:67], v[144:145] op_sel_hi:[1,0,1]
	v_pk_fma_f32 v[210:211], v[210:211], s[66:67], v[138:139] op_sel_hi:[1,0,1]
	v_pk_fma_f32 v[212:213], v[212:213], s[66:67], v[140:141] op_sel_hi:[1,0,1]
	v_cvt_pk_bf16_f32 v220, v206, v207
	v_cvt_pk_bf16_f32 v221, v208, v209
	v_cvt_pk_bf16_f32 v222, v210, v211
	v_cvt_pk_bf16_f32 v223, v212, v213
	s_add_u32 s48, s72, 0x0
	s_addc_u32 s49, s73, 0
	global_store_dwordx4 v170, v[220:223], s[48:49]
	s_waitcnt vmcnt(13)
	v_lshlrev_b32_e32 v206, 16, v224
	v_and_b32_e32 v207, 0xffff0000, v224
	v_lshlrev_b32_e32 v208, 16, v225
	v_and_b32_e32 v209, 0xffff0000, v225
	v_lshlrev_b32_e32 v210, 16, v226
	v_and_b32_e32 v211, 0xffff0000, v226
	v_lshlrev_b32_e32 v212, 16, v227
	v_and_b32_e32 v213, 0xffff0000, v227
	v_sub_f32_e32 v206, v206, v180
	v_sub_f32_e32 v207, v207, v180
	v_sub_f32_e32 v208, v208, v180
	v_sub_f32_e32 v209, v209, v180
	v_sub_f32_e32 v210, v210, v180
	v_sub_f32_e32 v211, v211, v180
	v_sub_f32_e32 v212, v212, v180
	v_sub_f32_e32 v213, v213, v180
	v_pk_mul_f32 v[206:207], v[180:181], v[206:207] op_sel:[1,0]
	v_pk_mul_f32 v[208:209], v[180:181], v[208:209] op_sel:[1,0]
	v_pk_mul_f32 v[210:211], v[180:181], v[210:211] op_sel:[1,0]
	v_pk_mul_f32 v[212:213], v[180:181], v[212:213] op_sel:[1,0]
	v_pk_fma_f32 v[206:207], v[98:99], v[206:207], v[102:103]
	v_pk_fma_f32 v[208:209], v[100:101], v[208:209], v[104:105]
	v_pk_fma_f32 v[210:211], v[90:91], v[210:211], v[94:95]
	v_pk_fma_f32 v[212:213], v[92:93], v[212:213], v[96:97]
	v_pk_fma_f32 v[206:207], v[206:207], s[66:67], v[134:135] op_sel_hi:[1,0,1]
	v_pk_fma_f32 v[208:209], v[208:209], s[66:67], v[136:137] op_sel_hi:[1,0,1]
	v_pk_fma_f32 v[210:211], v[210:211], s[66:67], v[130:131] op_sel_hi:[1,0,1]
	v_pk_fma_f32 v[212:213], v[212:213], s[66:67], v[132:133] op_sel_hi:[1,0,1]
	v_cvt_pk_bf16_f32 v224, v206, v207
	v_cvt_pk_bf16_f32 v225, v208, v209
	v_cvt_pk_bf16_f32 v226, v210, v211
	v_cvt_pk_bf16_f32 v227, v212, v213
	s_add_u32 s48, s72, 0x10000
	s_addc_u32 s49, s73, 0
	global_store_dwordx4 v170, v[224:227], s[48:49]
	s_waitcnt vmcnt(12)
	v_lshlrev_b32_e32 v206, 16, v228
	v_and_b32_e32 v207, 0xffff0000, v228
	v_lshlrev_b32_e32 v208, 16, v229
	v_and_b32_e32 v209, 0xffff0000, v229
	v_lshlrev_b32_e32 v210, 16, v230
	v_and_b32_e32 v211, 0xffff0000, v230
	v_lshlrev_b32_e32 v212, 16, v231
	v_and_b32_e32 v213, 0xffff0000, v231
	v_sub_f32_e32 v206, v206, v182
	v_sub_f32_e32 v207, v207, v182
	v_sub_f32_e32 v208, v208, v182
	v_sub_f32_e32 v209, v209, v182
	v_sub_f32_e32 v210, v210, v182
	v_sub_f32_e32 v211, v211, v182
	v_sub_f32_e32 v212, v212, v182
	v_sub_f32_e32 v213, v213, v182
	v_pk_mul_f32 v[206:207], v[182:183], v[206:207] op_sel:[1,0]
	v_pk_mul_f32 v[208:209], v[182:183], v[208:209] op_sel:[1,0]
	v_pk_mul_f32 v[210:211], v[182:183], v[210:211] op_sel:[1,0]
	v_pk_mul_f32 v[212:213], v[182:183], v[212:213] op_sel:[1,0]
	v_pk_fma_f32 v[206:207], v[98:99], v[206:207], v[102:103]
	v_pk_fma_f32 v[208:209], v[100:101], v[208:209], v[104:105]
	v_pk_fma_f32 v[210:211], v[90:91], v[210:211], v[94:95]
	v_pk_fma_f32 v[212:213], v[92:93], v[212:213], v[96:97]
	v_pk_fma_f32 v[206:207], v[206:207], s[66:67], v[126:127] op_sel_hi:[1,0,1]
	v_pk_fma_f32 v[208:209], v[208:209], s[66:67], v[128:129] op_sel_hi:[1,0,1]
	v_pk_fma_f32 v[210:211], v[210:211], s[66:67], v[122:123] op_sel_hi:[1,0,1]
	v_pk_fma_f32 v[212:213], v[212:213], s[66:67], v[124:125] op_sel_hi:[1,0,1]
	v_cvt_pk_bf16_f32 v228, v206, v207
	v_cvt_pk_bf16_f32 v229, v208, v209
	v_cvt_pk_bf16_f32 v230, v210, v211
	v_cvt_pk_bf16_f32 v231, v212, v213
	s_add_u32 s48, s72, 0x20000
	s_addc_u32 s49, s73, 0
	global_store_dwordx4 v170, v[228:231], s[48:49]
	s_waitcnt vmcnt(11)
	v_lshlrev_b32_e32 v206, 16, v232
	v_and_b32_e32 v207, 0xffff0000, v232
	v_lshlrev_b32_e32 v208, 16, v233
	v_and_b32_e32 v209, 0xffff0000, v233
	v_lshlrev_b32_e32 v210, 16, v234
	v_and_b32_e32 v211, 0xffff0000, v234
	v_lshlrev_b32_e32 v212, 16, v235
	v_and_b32_e32 v213, 0xffff0000, v235
	v_sub_f32_e32 v206, v206, v184
	v_sub_f32_e32 v207, v207, v184
	v_sub_f32_e32 v208, v208, v184
	v_sub_f32_e32 v209, v209, v184
	v_sub_f32_e32 v210, v210, v184
	v_sub_f32_e32 v211, v211, v184
	v_sub_f32_e32 v212, v212, v184
	v_sub_f32_e32 v213, v213, v184
	v_pk_mul_f32 v[206:207], v[184:185], v[206:207] op_sel:[1,0]
	v_pk_mul_f32 v[208:209], v[184:185], v[208:209] op_sel:[1,0]
	v_pk_mul_f32 v[210:211], v[184:185], v[210:211] op_sel:[1,0]
	v_pk_mul_f32 v[212:213], v[184:185], v[212:213] op_sel:[1,0]
	v_pk_fma_f32 v[206:207], v[98:99], v[206:207], v[102:103]
	v_pk_fma_f32 v[208:209], v[100:101], v[208:209], v[104:105]
	v_pk_fma_f32 v[210:211], v[90:91], v[210:211], v[94:95]
	v_pk_fma_f32 v[212:213], v[92:93], v[212:213], v[96:97]
	v_pk_fma_f32 v[206:207], v[206:207], s[66:67], v[118:119] op_sel_hi:[1,0,1]
	v_pk_fma_f32 v[208:209], v[208:209], s[66:67], v[120:121] op_sel_hi:[1,0,1]
	v_pk_fma_f32 v[210:211], v[210:211], s[66:67], v[114:115] op_sel_hi:[1,0,1]
	v_pk_fma_f32 v[212:213], v[212:213], s[66:67], v[116:117] op_sel_hi:[1,0,1]
	v_cvt_pk_bf16_f32 v232, v206, v207
	v_cvt_pk_bf16_f32 v233, v208, v209
	v_cvt_pk_bf16_f32 v234, v210, v211
	v_cvt_pk_bf16_f32 v235, v212, v213
	s_add_u32 s48, s72, 0x30000
	s_addc_u32 s49, s73, 0
	global_store_dwordx4 v170, v[232:235], s[48:49]
	s_waitcnt vmcnt(10)
	v_lshlrev_b32_e32 v206, 16, v236
	v_and_b32_e32 v207, 0xffff0000, v236
	v_lshlrev_b32_e32 v208, 16, v237
	v_and_b32_e32 v209, 0xffff0000, v237
	v_lshlrev_b32_e32 v210, 16, v238
	v_and_b32_e32 v211, 0xffff0000, v238
	v_lshlrev_b32_e32 v212, 16, v239
	v_and_b32_e32 v213, 0xffff0000, v239
	v_sub_f32_e32 v206, v206, v168
	v_sub_f32_e32 v207, v207, v168
	v_sub_f32_e32 v208, v208, v168
	v_sub_f32_e32 v209, v209, v168
	v_sub_f32_e32 v210, v210, v168
	v_sub_f32_e32 v211, v211, v168
	v_sub_f32_e32 v212, v212, v168
	v_sub_f32_e32 v213, v213, v168
	v_pk_mul_f32 v[206:207], v[168:169], v[206:207] op_sel:[1,0]
	v_pk_mul_f32 v[208:209], v[168:169], v[208:209] op_sel:[1,0]
	v_pk_mul_f32 v[210:211], v[168:169], v[210:211] op_sel:[1,0]
	v_pk_mul_f32 v[212:213], v[168:169], v[212:213] op_sel:[1,0]
	v_pk_fma_f32 v[206:207], v[98:99], v[206:207], v[102:103]
	v_pk_fma_f32 v[208:209], v[100:101], v[208:209], v[104:105]
	v_pk_fma_f32 v[210:211], v[90:91], v[210:211], v[94:95]
	v_pk_fma_f32 v[212:213], v[92:93], v[212:213], v[96:97]
	v_pk_fma_f32 v[206:207], v[206:207], s[66:67], v[110:111] op_sel_hi:[1,0,1]
	v_pk_fma_f32 v[208:209], v[208:209], s[66:67], v[112:113] op_sel_hi:[1,0,1]
	v_pk_fma_f32 v[210:211], v[210:211], s[66:67], v[106:107] op_sel_hi:[1,0,1]
	v_pk_fma_f32 v[212:213], v[212:213], s[66:67], v[108:109] op_sel_hi:[1,0,1]
	v_cvt_pk_bf16_f32 v236, v206, v207
	v_cvt_pk_bf16_f32 v237, v208, v209
	v_cvt_pk_bf16_f32 v238, v210, v211
	v_cvt_pk_bf16_f32 v239, v212, v213
	s_add_u32 s48, s72, 0x80000
	s_addc_u32 s49, s73, 0
	global_store_dwordx4 v170, v[236:239], s[48:49]
	s_waitcnt vmcnt(9)
	v_lshlrev_b32_e32 v206, 16, v240
	v_and_b32_e32 v207, 0xffff0000, v240
	v_lshlrev_b32_e32 v208, 16, v241
	v_and_b32_e32 v209, 0xffff0000, v241
	v_lshlrev_b32_e32 v210, 16, v242
	v_and_b32_e32 v211, 0xffff0000, v242
	v_lshlrev_b32_e32 v212, 16, v243
	v_and_b32_e32 v213, 0xffff0000, v243
	v_sub_f32_e32 v206, v206, v252
	v_sub_f32_e32 v207, v207, v252
	v_sub_f32_e32 v208, v208, v252
	v_sub_f32_e32 v209, v209, v252
	v_sub_f32_e32 v210, v210, v252
	v_sub_f32_e32 v211, v211, v252
	v_sub_f32_e32 v212, v212, v252
	v_sub_f32_e32 v213, v213, v252
	v_pk_mul_f32 v[206:207], v[252:253], v[206:207] op_sel:[1,0]
	v_pk_mul_f32 v[208:209], v[252:253], v[208:209] op_sel:[1,0]
	v_pk_mul_f32 v[210:211], v[252:253], v[210:211] op_sel:[1,0]
	v_pk_mul_f32 v[212:213], v[252:253], v[212:213] op_sel:[1,0]
	v_pk_fma_f32 v[206:207], v[98:99], v[206:207], v[102:103]
	v_pk_fma_f32 v[208:209], v[100:101], v[208:209], v[104:105]
	v_pk_fma_f32 v[210:211], v[90:91], v[210:211], v[94:95]
	v_pk_fma_f32 v[212:213], v[92:93], v[212:213], v[96:97]
	v_pk_fma_f32 v[206:207], v[206:207], s[66:67], v[86:87] op_sel_hi:[1,0,1]
	v_pk_fma_f32 v[208:209], v[208:209], s[66:67], v[88:89] op_sel_hi:[1,0,1]
	v_pk_fma_f32 v[210:211], v[210:211], s[66:67], v[82:83] op_sel_hi:[1,0,1]
	v_pk_fma_f32 v[212:213], v[212:213], s[66:67], v[84:85] op_sel_hi:[1,0,1]
	v_cvt_pk_bf16_f32 v240, v206, v207
	v_cvt_pk_bf16_f32 v241, v208, v209
	v_cvt_pk_bf16_f32 v242, v210, v211
	v_cvt_pk_bf16_f32 v243, v212, v213
	s_add_u32 s48, s72, 0x90000
	s_addc_u32 s49, s73, 0
	global_store_dwordx4 v170, v[240:243], s[48:49]
	s_waitcnt vmcnt(8)
	v_lshlrev_b32_e32 v206, 16, v244
	v_and_b32_e32 v207, 0xffff0000, v244
	v_lshlrev_b32_e32 v208, 16, v245
	v_and_b32_e32 v209, 0xffff0000, v245
	v_lshlrev_b32_e32 v210, 16, v246
	v_and_b32_e32 v211, 0xffff0000, v246
	v_lshlrev_b32_e32 v212, 16, v247
	v_and_b32_e32 v213, 0xffff0000, v247
	v_sub_f32_e32 v206, v206, v214
	v_sub_f32_e32 v207, v207, v214
	v_sub_f32_e32 v208, v208, v214
	v_sub_f32_e32 v209, v209, v214
	v_sub_f32_e32 v210, v210, v214
	v_sub_f32_e32 v211, v211, v214
	v_sub_f32_e32 v212, v212, v214
	v_sub_f32_e32 v213, v213, v214
	v_pk_mul_f32 v[206:207], v[214:215], v[206:207] op_sel:[1,0]
	v_pk_mul_f32 v[208:209], v[214:215], v[208:209] op_sel:[1,0]
	v_pk_mul_f32 v[210:211], v[214:215], v[210:211] op_sel:[1,0]
	v_pk_mul_f32 v[212:213], v[214:215], v[212:213] op_sel:[1,0]
	v_pk_fma_f32 v[206:207], v[98:99], v[206:207], v[102:103]
	v_pk_fma_f32 v[208:209], v[100:101], v[208:209], v[104:105]
	v_pk_fma_f32 v[210:211], v[90:91], v[210:211], v[94:95]
	v_pk_fma_f32 v[212:213], v[92:93], v[212:213], v[96:97]
	v_pk_fma_f32 v[206:207], v[206:207], s[66:67], v[78:79] op_sel_hi:[1,0,1]
	v_pk_fma_f32 v[208:209], v[208:209], s[66:67], v[80:81] op_sel_hi:[1,0,1]
	v_pk_fma_f32 v[210:211], v[210:211], s[66:67], v[74:75] op_sel_hi:[1,0,1]
	v_pk_fma_f32 v[212:213], v[212:213], s[66:67], v[76:77] op_sel_hi:[1,0,1]
	v_cvt_pk_bf16_f32 v244, v206, v207
	v_cvt_pk_bf16_f32 v245, v208, v209
	v_cvt_pk_bf16_f32 v246, v210, v211
	v_cvt_pk_bf16_f32 v247, v212, v213
	s_add_u32 s48, s72, 0xa0000
	s_addc_u32 s49, s73, 0
	global_store_dwordx4 v170, v[244:247], s[48:49]
	s_waitcnt vmcnt(7)
	v_lshlrev_b32_e32 v206, 16, v248
	v_and_b32_e32 v207, 0xffff0000, v248
	v_lshlrev_b32_e32 v208, 16, v249
	v_and_b32_e32 v209, 0xffff0000, v249
	v_lshlrev_b32_e32 v210, 16, v250
	v_and_b32_e32 v211, 0xffff0000, v250
	v_lshlrev_b32_e32 v212, 16, v251
	v_and_b32_e32 v213, 0xffff0000, v251
	v_sub_f32_e32 v206, v206, v216
	v_sub_f32_e32 v207, v207, v216
	v_sub_f32_e32 v208, v208, v216
	v_sub_f32_e32 v209, v209, v216
	v_sub_f32_e32 v210, v210, v216
	v_sub_f32_e32 v211, v211, v216
	v_sub_f32_e32 v212, v212, v216
	v_sub_f32_e32 v213, v213, v216
	v_pk_mul_f32 v[206:207], v[216:217], v[206:207] op_sel:[1,0]
	v_pk_mul_f32 v[208:209], v[216:217], v[208:209] op_sel:[1,0]
	v_pk_mul_f32 v[210:211], v[216:217], v[210:211] op_sel:[1,0]
	v_pk_mul_f32 v[212:213], v[216:217], v[212:213] op_sel:[1,0]
	v_pk_fma_f32 v[206:207], v[98:99], v[206:207], v[102:103]
	v_pk_fma_f32 v[208:209], v[100:101], v[208:209], v[104:105]
	v_pk_fma_f32 v[210:211], v[90:91], v[210:211], v[94:95]
	v_pk_fma_f32 v[212:213], v[92:93], v[212:213], v[96:97]
	v_pk_fma_f32 v[206:207], v[206:207], s[66:67], v[70:71] op_sel_hi:[1,0,1]
	v_pk_fma_f32 v[208:209], v[208:209], s[66:67], v[72:73] op_sel_hi:[1,0,1]
	v_pk_fma_f32 v[210:211], v[210:211], s[66:67], v[66:67] op_sel_hi:[1,0,1]
	v_pk_fma_f32 v[212:213], v[212:213], s[66:67], v[68:69] op_sel_hi:[1,0,1]
	v_cvt_pk_bf16_f32 v248, v206, v207
	v_cvt_pk_bf16_f32 v249, v208, v209
	v_cvt_pk_bf16_f32 v250, v210, v211
	v_cvt_pk_bf16_f32 v251, v212, v213
	s_add_u32 s48, s72, 0xb0000
	s_addc_u32 s49, s73, 0
	global_store_dwordx4 v170, v[248:251], s[48:49]
	global_load_dwordx4 v[98:101], v174, s[74:75] offset:512
	global_load_dwordx4 v[90:93], v174, s[74:75] offset:528
	global_load_dwordx4 v[102:105], v174, s[76:77] offset:512
	global_load_dwordx4 v[94:97], v174, s[76:77] offset:528
	s_add_u32 s48, s72, 0x100
	s_addc_u32 s49, s73, 0
	global_load_dwordx4 v[220:223], v170, s[48:49]
	s_add_u32 s50, s14, 0x0
	s_addc_u32 s51, s15, 0
	global_load_dwordx2 v[176:177], v171, s[50:51]
	s_add_u32 s48, s72, 0x10100
	s_addc_u32 s49, s73, 0
	global_load_dwordx4 v[224:227], v170, s[48:49]
	s_add_u32 s50, s14, 0x80
	s_addc_u32 s51, s15, 0
	global_load_dwordx2 v[180:181], v171, s[50:51]
	s_add_u32 s48, s72, 0x20100
	s_addc_u32 s49, s73, 0
	global_load_dwordx4 v[228:231], v170, s[48:49]
	s_add_u32 s50, s14, 0x100
	s_addc_u32 s51, s15, 0
	global_load_dwordx2 v[182:183], v171, s[50:51]
	s_add_u32 s48, s72, 0x30100
	s_addc_u32 s49, s73, 0
	global_load_dwordx4 v[232:235], v170, s[48:49]
	s_add_u32 s50, s14, 0x180
	s_addc_u32 s51, s15, 0
	global_load_dwordx2 v[184:185], v171, s[50:51]
	s_add_u32 s48, s72, 0x80100
	s_addc_u32 s49, s73, 0
	global_load_dwordx4 v[236:239], v170, s[48:49]
	s_add_u32 s50, s14, 0x400
	s_addc_u32 s51, s15, 0
	global_load_dwordx2 v[168:169], v171, s[50:51]
	s_add_u32 s48, s72, 0x90100
	s_addc_u32 s49, s73, 0
	global_load_dwordx4 v[240:243], v170, s[48:49]
	s_add_u32 s50, s14, 0x480
	s_addc_u32 s51, s15, 0
	global_load_dwordx2 v[252:253], v171, s[50:51]
	s_add_u32 s48, s72, 0xa0100
	s_addc_u32 s49, s73, 0
	global_load_dwordx4 v[244:247], v170, s[48:49]
	s_add_u32 s50, s14, 0x500
	s_addc_u32 s51, s15, 0
	global_load_dwordx2 v[214:215], v171, s[50:51]
	s_add_u32 s48, s72, 0xb0100
	s_addc_u32 s49, s73, 0
	global_load_dwordx4 v[248:251], v170, s[48:49]
	s_add_u32 s50, s14, 0x580
	s_addc_u32 s51, s15, 0
	global_load_dwordx2 v[216:217], v171, s[50:51]
	s_waitcnt vmcnt(14)
	v_lshlrev_b32_e32 v206, 16, v220
	v_and_b32_e32 v207, 0xffff0000, v220
	v_lshlrev_b32_e32 v208, 16, v221
	v_and_b32_e32 v209, 0xffff0000, v221
	v_lshlrev_b32_e32 v210, 16, v222
	v_and_b32_e32 v211, 0xffff0000, v222
	v_lshlrev_b32_e32 v212, 16, v223
	v_and_b32_e32 v213, 0xffff0000, v223
	v_sub_f32_e32 v206, v206, v176
	v_sub_f32_e32 v207, v207, v176
	v_sub_f32_e32 v208, v208, v176
	v_sub_f32_e32 v209, v209, v176
	v_sub_f32_e32 v210, v210, v176
	v_sub_f32_e32 v211, v211, v176
	v_sub_f32_e32 v212, v212, v176
	v_sub_f32_e32 v213, v213, v176
	v_pk_mul_f32 v[206:207], v[176:177], v[206:207] op_sel:[1,0]
	v_pk_mul_f32 v[208:209], v[176:177], v[208:209] op_sel:[1,0]
	v_pk_mul_f32 v[210:211], v[176:177], v[210:211] op_sel:[1,0]
	v_pk_mul_f32 v[212:213], v[176:177], v[212:213] op_sel:[1,0]
	v_pk_fma_f32 v[206:207], v[98:99], v[206:207], v[102:103]
	v_pk_fma_f32 v[208:209], v[100:101], v[208:209], v[104:105]
	v_pk_fma_f32 v[210:211], v[90:91], v[210:211], v[94:95]
	v_pk_fma_f32 v[212:213], v[92:93], v[212:213], v[96:97]
	v_pk_fma_f32 v[206:207], v[206:207], s[66:67], v[62:63] op_sel_hi:[1,0,1]
	v_pk_fma_f32 v[208:209], v[208:209], s[66:67], v[64:65] op_sel_hi:[1,0,1]
	v_pk_fma_f32 v[210:211], v[210:211], s[66:67], v[58:59] op_sel_hi:[1,0,1]
	v_pk_fma_f32 v[212:213], v[212:213], s[66:67], v[60:61] op_sel_hi:[1,0,1]
	v_cvt_pk_bf16_f32 v220, v206, v207
	v_cvt_pk_bf16_f32 v221, v208, v209
	v_cvt_pk_bf16_f32 v222, v210, v211
	v_cvt_pk_bf16_f32 v223, v212, v213
	s_add_u32 s48, s72, 0x100
	s_addc_u32 s49, s73, 0
	global_store_dwordx4 v170, v[220:223], s[48:49]
	s_waitcnt vmcnt(13)
	v_lshlrev_b32_e32 v206, 16, v224
	v_and_b32_e32 v207, 0xffff0000, v224
	v_lshlrev_b32_e32 v208, 16, v225
	v_and_b32_e32 v209, 0xffff0000, v225
	v_lshlrev_b32_e32 v210, 16, v226
	v_and_b32_e32 v211, 0xffff0000, v226
	v_lshlrev_b32_e32 v212, 16, v227
	v_and_b32_e32 v213, 0xffff0000, v227
	v_sub_f32_e32 v206, v206, v180
	v_sub_f32_e32 v207, v207, v180
	v_sub_f32_e32 v208, v208, v180
	v_sub_f32_e32 v209, v209, v180
	v_sub_f32_e32 v210, v210, v180
	v_sub_f32_e32 v211, v211, v180
	v_sub_f32_e32 v212, v212, v180
	v_sub_f32_e32 v213, v213, v180
	v_pk_mul_f32 v[206:207], v[180:181], v[206:207] op_sel:[1,0]
	v_pk_mul_f32 v[208:209], v[180:181], v[208:209] op_sel:[1,0]
	v_pk_mul_f32 v[210:211], v[180:181], v[210:211] op_sel:[1,0]
	v_pk_mul_f32 v[212:213], v[180:181], v[212:213] op_sel:[1,0]
	v_pk_fma_f32 v[206:207], v[98:99], v[206:207], v[102:103]
	v_pk_fma_f32 v[208:209], v[100:101], v[208:209], v[104:105]
	v_pk_fma_f32 v[210:211], v[90:91], v[210:211], v[94:95]
	v_pk_fma_f32 v[212:213], v[92:93], v[212:213], v[96:97]
	v_pk_fma_f32 v[206:207], v[206:207], s[66:67], v[54:55] op_sel_hi:[1,0,1]
	v_pk_fma_f32 v[208:209], v[208:209], s[66:67], v[56:57] op_sel_hi:[1,0,1]
	v_pk_fma_f32 v[210:211], v[210:211], s[66:67], v[50:51] op_sel_hi:[1,0,1]
	v_pk_fma_f32 v[212:213], v[212:213], s[66:67], v[52:53] op_sel_hi:[1,0,1]
	v_cvt_pk_bf16_f32 v224, v206, v207
	v_cvt_pk_bf16_f32 v225, v208, v209
	v_cvt_pk_bf16_f32 v226, v210, v211
	v_cvt_pk_bf16_f32 v227, v212, v213
	s_add_u32 s48, s72, 0x10100
	s_addc_u32 s49, s73, 0
	global_store_dwordx4 v170, v[224:227], s[48:49]
	s_waitcnt vmcnt(12)
	v_lshlrev_b32_e32 v206, 16, v228
	v_and_b32_e32 v207, 0xffff0000, v228
	v_lshlrev_b32_e32 v208, 16, v229
	v_and_b32_e32 v209, 0xffff0000, v229
	v_lshlrev_b32_e32 v210, 16, v230
	v_and_b32_e32 v211, 0xffff0000, v230
	v_lshlrev_b32_e32 v212, 16, v231
	v_and_b32_e32 v213, 0xffff0000, v231
	v_sub_f32_e32 v206, v206, v182
	v_sub_f32_e32 v207, v207, v182
	v_sub_f32_e32 v208, v208, v182
	v_sub_f32_e32 v209, v209, v182
	v_sub_f32_e32 v210, v210, v182
	v_sub_f32_e32 v211, v211, v182
	v_sub_f32_e32 v212, v212, v182
	v_sub_f32_e32 v213, v213, v182
	v_pk_mul_f32 v[206:207], v[182:183], v[206:207] op_sel:[1,0]
	v_pk_mul_f32 v[208:209], v[182:183], v[208:209] op_sel:[1,0]
	v_pk_mul_f32 v[210:211], v[182:183], v[210:211] op_sel:[1,0]
	v_pk_mul_f32 v[212:213], v[182:183], v[212:213] op_sel:[1,0]
	v_pk_fma_f32 v[206:207], v[98:99], v[206:207], v[102:103]
	v_pk_fma_f32 v[208:209], v[100:101], v[208:209], v[104:105]
	v_pk_fma_f32 v[210:211], v[90:91], v[210:211], v[94:95]
	v_pk_fma_f32 v[212:213], v[92:93], v[212:213], v[96:97]
	v_pk_fma_f32 v[206:207], v[206:207], s[66:67], v[46:47] op_sel_hi:[1,0,1]
	v_pk_fma_f32 v[208:209], v[208:209], s[66:67], v[48:49] op_sel_hi:[1,0,1]
	v_pk_fma_f32 v[210:211], v[210:211], s[66:67], v[42:43] op_sel_hi:[1,0,1]
	v_pk_fma_f32 v[212:213], v[212:213], s[66:67], v[44:45] op_sel_hi:[1,0,1]
	v_cvt_pk_bf16_f32 v228, v206, v207
	v_cvt_pk_bf16_f32 v229, v208, v209
	v_cvt_pk_bf16_f32 v230, v210, v211
	v_cvt_pk_bf16_f32 v231, v212, v213
	s_add_u32 s48, s72, 0x20100
	s_addc_u32 s49, s73, 0
	global_store_dwordx4 v170, v[228:231], s[48:49]
	s_waitcnt vmcnt(11)
	v_lshlrev_b32_e32 v206, 16, v232
	v_and_b32_e32 v207, 0xffff0000, v232
	v_lshlrev_b32_e32 v208, 16, v233
	v_and_b32_e32 v209, 0xffff0000, v233
	v_lshlrev_b32_e32 v210, 16, v234
	v_and_b32_e32 v211, 0xffff0000, v234
	v_lshlrev_b32_e32 v212, 16, v235
	v_and_b32_e32 v213, 0xffff0000, v235
	v_sub_f32_e32 v206, v206, v184
	v_sub_f32_e32 v207, v207, v184
	v_sub_f32_e32 v208, v208, v184
	v_sub_f32_e32 v209, v209, v184
	v_sub_f32_e32 v210, v210, v184
	v_sub_f32_e32 v211, v211, v184
	v_sub_f32_e32 v212, v212, v184
	v_sub_f32_e32 v213, v213, v184
	v_pk_mul_f32 v[206:207], v[184:185], v[206:207] op_sel:[1,0]
	v_pk_mul_f32 v[208:209], v[184:185], v[208:209] op_sel:[1,0]
	v_pk_mul_f32 v[210:211], v[184:185], v[210:211] op_sel:[1,0]
	v_pk_mul_f32 v[212:213], v[184:185], v[212:213] op_sel:[1,0]
	v_pk_fma_f32 v[206:207], v[98:99], v[206:207], v[102:103]
	v_pk_fma_f32 v[208:209], v[100:101], v[208:209], v[104:105]
	v_pk_fma_f32 v[210:211], v[90:91], v[210:211], v[94:95]
	v_pk_fma_f32 v[212:213], v[92:93], v[212:213], v[96:97]
	v_pk_fma_f32 v[206:207], v[206:207], s[66:67], v[38:39] op_sel_hi:[1,0,1]
	v_pk_fma_f32 v[208:209], v[208:209], s[66:67], v[40:41] op_sel_hi:[1,0,1]
	v_pk_fma_f32 v[210:211], v[210:211], s[66:67], v[34:35] op_sel_hi:[1,0,1]
	v_pk_fma_f32 v[212:213], v[212:213], s[66:67], v[36:37] op_sel_hi:[1,0,1]
	v_cvt_pk_bf16_f32 v232, v206, v207
	v_cvt_pk_bf16_f32 v233, v208, v209
	v_cvt_pk_bf16_f32 v234, v210, v211
	v_cvt_pk_bf16_f32 v235, v212, v213
	s_add_u32 s48, s72, 0x30100
	s_addc_u32 s49, s73, 0
	global_store_dwordx4 v170, v[232:235], s[48:49]
	s_waitcnt vmcnt(10)
	v_lshlrev_b32_e32 v206, 16, v236
	v_and_b32_e32 v207, 0xffff0000, v236
	v_lshlrev_b32_e32 v208, 16, v237
	v_and_b32_e32 v209, 0xffff0000, v237
	v_lshlrev_b32_e32 v210, 16, v238
	v_and_b32_e32 v211, 0xffff0000, v238
	v_lshlrev_b32_e32 v212, 16, v239
	v_and_b32_e32 v213, 0xffff0000, v239
	v_sub_f32_e32 v206, v206, v168
	v_sub_f32_e32 v207, v207, v168
	v_sub_f32_e32 v208, v208, v168
	v_sub_f32_e32 v209, v209, v168
	v_sub_f32_e32 v210, v210, v168
	v_sub_f32_e32 v211, v211, v168
	v_sub_f32_e32 v212, v212, v168
	v_sub_f32_e32 v213, v213, v168
	v_pk_mul_f32 v[206:207], v[168:169], v[206:207] op_sel:[1,0]
	v_pk_mul_f32 v[208:209], v[168:169], v[208:209] op_sel:[1,0]
	v_pk_mul_f32 v[210:211], v[168:169], v[210:211] op_sel:[1,0]
	v_pk_mul_f32 v[212:213], v[168:169], v[212:213] op_sel:[1,0]
	v_pk_fma_f32 v[206:207], v[98:99], v[206:207], v[102:103]
	v_pk_fma_f32 v[208:209], v[100:101], v[208:209], v[104:105]
	v_pk_fma_f32 v[210:211], v[90:91], v[210:211], v[94:95]
	v_pk_fma_f32 v[212:213], v[92:93], v[212:213], v[96:97]
	v_pk_fma_f32 v[206:207], v[206:207], s[66:67], v[30:31] op_sel_hi:[1,0,1]
	v_pk_fma_f32 v[208:209], v[208:209], s[66:67], v[32:33] op_sel_hi:[1,0,1]
	v_pk_fma_f32 v[210:211], v[210:211], s[66:67], v[26:27] op_sel_hi:[1,0,1]
	v_pk_fma_f32 v[212:213], v[212:213], s[66:67], v[28:29] op_sel_hi:[1,0,1]
	v_cvt_pk_bf16_f32 v236, v206, v207
	v_cvt_pk_bf16_f32 v237, v208, v209
	v_cvt_pk_bf16_f32 v238, v210, v211
	v_cvt_pk_bf16_f32 v239, v212, v213
	s_add_u32 s48, s72, 0x80100
	s_addc_u32 s49, s73, 0
	global_store_dwordx4 v170, v[236:239], s[48:49]
	s_waitcnt vmcnt(9)
	v_lshlrev_b32_e32 v206, 16, v240
	v_and_b32_e32 v207, 0xffff0000, v240
	v_lshlrev_b32_e32 v208, 16, v241
	v_and_b32_e32 v209, 0xffff0000, v241
	v_lshlrev_b32_e32 v210, 16, v242
	v_and_b32_e32 v211, 0xffff0000, v242
	v_lshlrev_b32_e32 v212, 16, v243
	v_and_b32_e32 v213, 0xffff0000, v243
	v_sub_f32_e32 v206, v206, v252
	v_sub_f32_e32 v207, v207, v252
	v_sub_f32_e32 v208, v208, v252
	v_sub_f32_e32 v209, v209, v252
	v_sub_f32_e32 v210, v210, v252
	v_sub_f32_e32 v211, v211, v252
	v_sub_f32_e32 v212, v212, v252
	v_sub_f32_e32 v213, v213, v252
	v_pk_mul_f32 v[206:207], v[252:253], v[206:207] op_sel:[1,0]
	v_pk_mul_f32 v[208:209], v[252:253], v[208:209] op_sel:[1,0]
	v_pk_mul_f32 v[210:211], v[252:253], v[210:211] op_sel:[1,0]
	v_pk_mul_f32 v[212:213], v[252:253], v[212:213] op_sel:[1,0]
	v_pk_fma_f32 v[206:207], v[98:99], v[206:207], v[102:103]
	v_pk_fma_f32 v[208:209], v[100:101], v[208:209], v[104:105]
	v_pk_fma_f32 v[210:211], v[90:91], v[210:211], v[94:95]
	v_pk_fma_f32 v[212:213], v[92:93], v[212:213], v[96:97]
	v_pk_fma_f32 v[206:207], v[206:207], s[66:67], v[22:23] op_sel_hi:[1,0,1]
	v_pk_fma_f32 v[208:209], v[208:209], s[66:67], v[24:25] op_sel_hi:[1,0,1]
	v_pk_fma_f32 v[210:211], v[210:211], s[66:67], v[18:19] op_sel_hi:[1,0,1]
	v_pk_fma_f32 v[212:213], v[212:213], s[66:67], v[20:21] op_sel_hi:[1,0,1]
	v_cvt_pk_bf16_f32 v240, v206, v207
	v_cvt_pk_bf16_f32 v241, v208, v209
	v_cvt_pk_bf16_f32 v242, v210, v211
	v_cvt_pk_bf16_f32 v243, v212, v213
	s_add_u32 s48, s72, 0x90100
	s_addc_u32 s49, s73, 0
	global_store_dwordx4 v170, v[240:243], s[48:49]
	s_waitcnt vmcnt(8)
	v_lshlrev_b32_e32 v206, 16, v244
	v_and_b32_e32 v207, 0xffff0000, v244
	v_lshlrev_b32_e32 v208, 16, v245
	v_and_b32_e32 v209, 0xffff0000, v245
	v_lshlrev_b32_e32 v210, 16, v246
	v_and_b32_e32 v211, 0xffff0000, v246
	v_lshlrev_b32_e32 v212, 16, v247
	v_and_b32_e32 v213, 0xffff0000, v247
	v_sub_f32_e32 v206, v206, v214
	v_sub_f32_e32 v207, v207, v214
	v_sub_f32_e32 v208, v208, v214
	v_sub_f32_e32 v209, v209, v214
	v_sub_f32_e32 v210, v210, v214
	v_sub_f32_e32 v211, v211, v214
	v_sub_f32_e32 v212, v212, v214
	v_sub_f32_e32 v213, v213, v214
	v_pk_mul_f32 v[206:207], v[214:215], v[206:207] op_sel:[1,0]
	v_pk_mul_f32 v[208:209], v[214:215], v[208:209] op_sel:[1,0]
	v_pk_mul_f32 v[210:211], v[214:215], v[210:211] op_sel:[1,0]
	v_pk_mul_f32 v[212:213], v[214:215], v[212:213] op_sel:[1,0]
	v_pk_fma_f32 v[206:207], v[98:99], v[206:207], v[102:103]
	v_pk_fma_f32 v[208:209], v[100:101], v[208:209], v[104:105]
	v_pk_fma_f32 v[210:211], v[90:91], v[210:211], v[94:95]
	v_pk_fma_f32 v[212:213], v[92:93], v[212:213], v[96:97]
	v_pk_fma_f32 v[206:207], v[206:207], s[66:67], v[14:15] op_sel_hi:[1,0,1]
	v_pk_fma_f32 v[208:209], v[208:209], s[66:67], v[16:17] op_sel_hi:[1,0,1]
	v_pk_fma_f32 v[210:211], v[210:211], s[66:67], v[10:11] op_sel_hi:[1,0,1]
	v_pk_fma_f32 v[212:213], v[212:213], s[66:67], v[12:13] op_sel_hi:[1,0,1]
	v_cvt_pk_bf16_f32 v244, v206, v207
	v_cvt_pk_bf16_f32 v245, v208, v209
	v_cvt_pk_bf16_f32 v246, v210, v211
	v_cvt_pk_bf16_f32 v247, v212, v213
	s_add_u32 s48, s72, 0xa0100
	s_addc_u32 s49, s73, 0
	global_store_dwordx4 v170, v[244:247], s[48:49]
	s_waitcnt vmcnt(7)
	v_lshlrev_b32_e32 v206, 16, v248
	v_and_b32_e32 v207, 0xffff0000, v248
	v_lshlrev_b32_e32 v208, 16, v249
	v_and_b32_e32 v209, 0xffff0000, v249
	v_lshlrev_b32_e32 v210, 16, v250
	v_and_b32_e32 v211, 0xffff0000, v250
	v_lshlrev_b32_e32 v212, 16, v251
	v_and_b32_e32 v213, 0xffff0000, v251
	v_sub_f32_e32 v206, v206, v216
	v_sub_f32_e32 v207, v207, v216
	v_sub_f32_e32 v208, v208, v216
	v_sub_f32_e32 v209, v209, v216
	v_sub_f32_e32 v210, v210, v216
	v_sub_f32_e32 v211, v211, v216
	v_sub_f32_e32 v212, v212, v216
	v_sub_f32_e32 v213, v213, v216
	v_pk_mul_f32 v[206:207], v[216:217], v[206:207] op_sel:[1,0]
	v_pk_mul_f32 v[208:209], v[216:217], v[208:209] op_sel:[1,0]
	v_pk_mul_f32 v[210:211], v[216:217], v[210:211] op_sel:[1,0]
	v_pk_mul_f32 v[212:213], v[216:217], v[212:213] op_sel:[1,0]
	v_pk_fma_f32 v[206:207], v[98:99], v[206:207], v[102:103]
	v_pk_fma_f32 v[208:209], v[100:101], v[208:209], v[104:105]
	v_pk_fma_f32 v[210:211], v[90:91], v[210:211], v[94:95]
	v_pk_fma_f32 v[212:213], v[92:93], v[212:213], v[96:97]
	v_pk_fma_f32 v[206:207], v[206:207], s[66:67], v[6:7] op_sel_hi:[1,0,1]
	v_pk_fma_f32 v[208:209], v[208:209], s[66:67], v[8:9] op_sel_hi:[1,0,1]
	v_pk_fma_f32 v[210:211], v[210:211], s[66:67], v[2:3] op_sel_hi:[1,0,1]
	v_pk_fma_f32 v[212:213], v[212:213], s[66:67], v[4:5] op_sel_hi:[1,0,1]
	v_cvt_pk_bf16_f32 v248, v206, v207
	v_cvt_pk_bf16_f32 v249, v208, v209
	v_cvt_pk_bf16_f32 v250, v210, v211
	v_cvt_pk_bf16_f32 v251, v212, v213
	s_add_u32 s48, s72, 0xb0100
	s_addc_u32 s49, s73, 0
	global_store_dwordx4 v170, v[248:251], s[48:49]
	s_and_b64 vcc, exec, s[8:9]
	s_mov_b32 s43, s6
	s_mov_b32 s46, s7
	s_mov_b64 s[68:69], s[12:13]
	s_mov_b64 s[64:65], s[10:11]
	s_cbranch_vccz .LBB0_1606
	s_waitcnt vmcnt(0)
	s_cmpk_gt_u32 s19, 0xff
	s_cbranch_scc1 .LBB0_1621
	s_barrier
